# GEMM loops: MFMA issue order changed to share one operand between consecutive MFMAs (snake order), on top of the saddr DMA version
# speedup vs baseline: 1.0034x; 1.0012x over previous
; #define PG8_STAGE(bufoff, gbase, voff) do { _Pragma("unroll") for (int _i = 0; _i < 2; ++_i) \
;         __builtin_amdgcn_global_load_lds((const unsigned*)((const char*)(gbase) + (voff)[_i]), (LAS unsigned*)(lds + (bufoff) + ldsw + _i * 8192), 16, 0, 0); } while (0)
; #define PG8_LDA(dst, b, h) do { _Pragma("unroll") for (int m = 0; m < 4; ++m) _Pragma("unroll") for (int k = 0; k < 2; ++k) dst[m][k] = *(const LAS bf16x8*)(lds + PG8_SA(b, h) + aoff + m * 2048 + k * 1024); } while (0)
; #define PG8_LDB(dst, b, h) do { _Pragma("unroll") for (int n = 0; n < 2; ++n) _Pragma("unroll") for (int k = 0; k < 2; ++k) dst[n][k] = *(const LAS bf16x8*)(lds + PG8_SB(b, h) + boff + n * 2048 + k * 1024); } while (0)
; #define PG8_WAIT_V(n) asm volatile("s_waitcnt vmcnt(" #n ")" ::: "memory")
; #define PG8_WAIT_L(n) asm volatile("s_waitcnt lgkmcnt(" #n ")" ::: "memory")
; #define PG8_BAR __builtin_amdgcn_s_barrier()
; #define PG8_SCHED __builtin_amdgcn_sched_barrier(0)
;     ...
;         for (int t = 0; t < nt; t += 2) {
;             const bool last = (t == nt - 2);
;             const char* a1 = PG8_ATILE(cA, cA2, t + 1);
;             const char* a2 = last ? nA : PG8_ATILE(cA, cA2, t + 2); const char* b2 = last ? nB : cB + (size_t)(t + 2) * 128;
;             const char* a3 = last ? nA + kA1 : PG8_ATILE(cA, cA2, t + 3); const char* b3 = b2 + kB1;
;             if constexpr (SP2) {
;             PG8_LDB(B0, 0, 0); PG8_LDB(B1, 0, 1); PG8_SCHED; PG8_LDA(At, 0, 0); PG8_STAGE(PG8_SA(1, 1), a1 + hA, voffA);
;             PG8_WAIT_V(8); PG8_WAIT_L(0); PG8_BAR; PG8_MMA(0, 0, At, B0); PG8_MMA(0, 1, At, B1); PG8_BAR; PG8_SCHED;
;             PG8_LDA(At, 0, 1); PG8_STAGE(PG8_SB(0, 0), b2, voffB); PG8_STAGE(PG8_SB(0, 1), b2 + hB, voffB); PG8_STAGE(PG8_SA(0, 0), a2, voffA);
;             PG8_WAIT_V(8); PG8_WAIT_L(0); PG8_BAR; PG8_MMA(1, 0, At, B0); PG8_MMA(1, 1, At, B1); PG8_BAR; PG8_SCHED;
;             PG8_LDB(B0, 1, 0); PG8_LDB(B1, 1, 1); PG8_SCHED; PG8_LDA(At, 1, 0); PG8_STAGE(PG8_SA(0, 1), a2 + hA, voffA);
;             PG8_WAIT_V(8); PG8_WAIT_L(0); PG8_BAR; PG8_MMA(0, 0, At, B0); PG8_MMA(0, 1, At, B1); PG8_BAR; PG8_SCHED;
;             PG8_LDA(At, 1, 1); PG8_STAGE(PG8_SB(1, 0), b3, voffB); PG8_STAGE(PG8_SB(1, 1), b3 + hB, voffB); PG8_STAGE(PG8_SA(1, 0), a3, voffA);
;             PG8_WAIT_V(8); PG8_WAIT_L(0); PG8_BAR; PG8_MMA(1, 0, At, B0); PG8_MMA(1, 1, At, B1); PG8_BAR; PG8_SCHED;
.LBB0_96:
	s_and_b64 s[2:3], exec, s[80:81]
	s_cselect_b32 s73, s27, s13
	s_cselect_b32 s72, s26, s9
	s_add_i32 s17, 0, 0x10000
	s_add_i32 s36, 0, 0x14000
	v_add_u32_e32 v132, s17, v182
	v_add_u32_e32 v180, s36, v182
	ds_read_b128 v[16:19], v132
	ds_read_b128 v[24:27], v132 offset:1024
	ds_read_b128 v[120:123], v132 offset:2048
	ds_read_b128 v[132:135], v132 offset:3072
	ds_read_b128 v[140:143], v180
	ds_read_b128 v[148:151], v180 offset:1024
	ds_read_b128 v[176:179], v180 offset:2048
	ds_read_b128 v[184:187], v180 offset:3072
	s_add_u32 s2, s78, 0x10000
	s_addc_u32 s3, s79, 0
	v_lshl_add_u64 v[180:181], s[2:3], 0, v[152:153]
	s_add_i32 m0, s94, 0xc000
	ds_read_b128 v[188:191], v183
	ds_read_b128 v[192:195], v183 offset:1024
	ds_read_b128 v[196:199], v183 offset:2048
	ds_read_b128 v[200:203], v183 offset:3072
	ds_read_b128 v[208:211], v183 offset:4096
	ds_read_b128 v[214:217], v183 offset:5120
	ds_read_b128 v[230:233], v183 offset:6144
	ds_read_b128 v[234:237], v183 offset:7168
	global_load_lds_dwordx4 v[180:181], off
	v_lshl_add_u64 v[180:181], s[2:3], 0, v[154:155]
	s_add_i32 m0, s94, 0xe000
	s_nop 0
	global_load_lds_dwordx4 v[180:181], off
	s_waitcnt vmcnt(8)
	s_waitcnt lgkmcnt(0)
	s_barrier
	s_setprio 1
	s_waitcnt lgkmcnt(0)
	v_mfma_f32_16x16x32_bf16 v[144:147], v[16:19], v[188:191], v[144:147]
	v_mfma_f32_16x16x32_bf16 v[136:139], v[120:123], v[188:191], v[136:139]
	v_mfma_f32_16x16x32_bf16 v[112:115], v[120:123], v[196:199], v[112:115]
	v_mfma_f32_16x16x32_bf16 v[116:119], v[16:19], v[196:199], v[116:119]
	v_mfma_f32_16x16x32_bf16 v[100:103], v[16:19], v[208:211], v[100:103]
	v_mfma_f32_16x16x32_bf16 v[96:99], v[120:123], v[208:211], v[96:99]
	v_mfma_f32_16x16x32_bf16 v[80:83], v[120:123], v[230:233], v[80:83]
	v_mfma_f32_16x16x32_bf16 v[84:87], v[16:19], v[230:233], v[84:87]
	v_mfma_f32_16x16x32_bf16 v[144:147], v[24:27], v[192:195], v[144:147]
	v_mfma_f32_16x16x32_bf16 v[136:139], v[132:135], v[192:195], v[136:139]
	v_mfma_f32_16x16x32_bf16 v[112:115], v[132:135], v[200:203], v[112:115]
	v_mfma_f32_16x16x32_bf16 v[116:119], v[24:27], v[200:203], v[116:119]
	v_mfma_f32_16x16x32_bf16 v[100:103], v[24:27], v[214:217], v[100:103]
	v_mfma_f32_16x16x32_bf16 v[96:99], v[132:135], v[214:217], v[96:99]
	v_mfma_f32_16x16x32_bf16 v[80:83], v[132:135], v[234:237], v[80:83]
	v_mfma_f32_16x16x32_bf16 v[84:87], v[24:27], v[234:237], v[84:87]
	s_setprio 0
	s_setprio 1
	v_mfma_f32_16x16x32_bf16 v[128:131], v[140:143], v[188:191], v[128:131]
	v_mfma_f32_16x16x32_bf16 v[124:127], v[176:179], v[188:191], v[124:127]
	v_mfma_f32_16x16x32_bf16 v[104:107], v[176:179], v[196:199], v[104:107]
	v_mfma_f32_16x16x32_bf16 v[108:111], v[140:143], v[196:199], v[108:111]
	v_mfma_f32_16x16x32_bf16 v[92:95], v[140:143], v[208:211], v[92:95]
	v_mfma_f32_16x16x32_bf16 v[88:91], v[176:179], v[208:211], v[88:91]
	v_mfma_f32_16x16x32_bf16 v[72:75], v[176:179], v[230:233], v[72:75]
	v_mfma_f32_16x16x32_bf16 v[76:79], v[140:143], v[230:233], v[76:79]
	v_mfma_f32_16x16x32_bf16 v[128:131], v[148:151], v[192:195], v[128:131]
	v_mfma_f32_16x16x32_bf16 v[124:127], v[184:187], v[192:195], v[124:127]
	v_mfma_f32_16x16x32_bf16 v[104:107], v[184:187], v[200:203], v[104:107]
	v_mfma_f32_16x16x32_bf16 v[108:111], v[148:151], v[200:203], v[108:111]
	v_mfma_f32_16x16x32_bf16 v[92:95], v[148:151], v[214:217], v[92:95]
	v_mfma_f32_16x16x32_bf16 v[88:91], v[184:187], v[214:217], v[88:91]
	v_mfma_f32_16x16x32_bf16 v[72:75], v[184:187], v[234:237], v[72:75]
	v_mfma_f32_16x16x32_bf16 v[76:79], v[148:151], v[234:237], v[76:79]
	s_setprio 0
	s_barrier
	s_add_i32 s2, s17, s93
	v_lshl_add_u64 v[180:181], s[72:73], 0, v[156:157]
	s_mov_b32 m0, s2
	ds_read_b128 v[188:191], v183 offset:16384
	ds_read_b128 v[192:195], v183 offset:17408
	ds_read_b128 v[196:199], v183 offset:18432
	ds_read_b128 v[200:203], v183 offset:19456
	ds_read_b128 v[208:211], v183 offset:20480
	ds_read_b128 v[214:217], v183 offset:21504
	ds_read_b128 v[230:233], v183 offset:22528
	ds_read_b128 v[234:237], v183 offset:23552
	global_load_lds_dwordx4 v[180:181], off
	s_add_i32 m0, s2, 0x2000
	s_add_u32 s2, s72, 0x18000
	v_lshl_add_u64 v[204:205], s[72:73], 0, v[168:169]
	s_addc_u32 s3, s73, 0
	s_add_i32 s17, s36, s93
	global_load_lds_dwordx4 v[204:205], off
	v_lshl_add_u64 v[206:207], s[2:3], 0, v[156:157]
	s_mov_b32 m0, s17
	s_nop 0
	global_load_lds_dwordx4 v[206:207], off
	v_lshl_add_u64 v[206:207], s[2:3], 0, v[168:169]
	s_add_i32 m0, s17, 0x2000
	s_nop 0
	global_load_lds_dwordx4 v[206:207], off
	v_lshl_add_u64 v[206:207], s[76:77], 0, v[152:153]
	s_mov_b32 m0, s94
	s_nop 0
	global_load_lds_dwordx4 v[206:207], off
	v_lshl_add_u64 v[206:207], s[76:77], 0, v[154:155]
	s_mov_b32 m0, s95
	s_nop 0
	global_load_lds_dwordx4 v[206:207], off
	s_waitcnt vmcnt(8)
	s_waitcnt lgkmcnt(0)
	s_barrier
; #define PG8_STAGE(bufoff, gbase, voff) do { _Pragma("unroll") for (int _i = 0; _i < 2; ++_i) \
;         __builtin_amdgcn_global_load_lds((const unsigned*)((const char*)(gbase) + (voff)[_i]), (LAS unsigned*)(lds + (bufoff) + ldsw + _i * 8192), 16, 0, 0); } while (0)
; #define PG8_LDA(dst, b, h) do { _Pragma("unroll") for (int m = 0; m < 4; ++m) _Pragma("unroll") for (int k = 0; k < 2; ++k) dst[m][k] = *(const LAS bf16x8*)(lds + PG8_SA(b, h) + aoff + m * 2048 + k * 1024); } while (0)
; #define PG8_LDB(dst, b, h) do { _Pragma("unroll") for (int n = 0; n < 2; ++n) _Pragma("unroll") for (int k = 0; k < 2; ++k) dst[n][k] = *(const LAS bf16x8*)(lds + PG8_SB(b, h) + boff + n * 2048 + k * 1024); } while (0)
; #define PG8_MMA(ai, bj, At, Bt) do { __builtin_amdgcn_s_setprio(1); _Pragma("unroll") for (int m = 0; m < 4; ++m) _Pragma("unroll") for (int n = 0; n < 2; ++n) _Pragma("unroll") for (int k = 0; k < 2; ++k) \
;         acc[ai][bj][m][n] = __builtin_amdgcn_mfma_f32_16x16x32_bf16(Bt[n][k], At[m][k], acc[ai][bj][m][n], 0, 0, 0); __builtin_amdgcn_s_setprio(0); } while (0)
; #define PG8_WAIT_V(n) asm volatile("s_waitcnt vmcnt(" #n ")" ::: "memory")
; #define PG8_WAIT_L(n) asm volatile("s_waitcnt lgkmcnt(" #n ")" ::: "memory")
; #define PG8_BAR __builtin_amdgcn_s_barrier()
; #define PG8_SCHED __builtin_amdgcn_sched_barrier(0)
;     ...
;             PG8_WAIT_V(8); PG8_WAIT_L(0); PG8_BAR; PG8_MMA(1, 0, At, B0); PG8_MMA(1, 1, At, B1); PG8_BAR; PG8_SCHED;
;             PG8_LDB(B0, 1, 0); PG8_LDB(B1, 1, 1); PG8_SCHED; PG8_LDA(At, 1, 0); PG8_STAGE(PG8_SA(0, 1), a2 + hA, voffA);
;             PG8_WAIT_V(8); PG8_WAIT_L(0); PG8_BAR; PG8_MMA(0, 0, At, B0); PG8_MMA(0, 1, At, B1); PG8_BAR; PG8_SCHED;
;             PG8_LDA(At, 1, 1); PG8_STAGE(PG8_SB(1, 0), b3, voffB); PG8_STAGE(PG8_SB(1, 1), b3 + hB, voffB); PG8_STAGE(PG8_SA(1, 0), a3, voffA);
;             PG8_WAIT_V(8); PG8_WAIT_L(0); PG8_BAR; PG8_MMA(1, 0, At, B0); PG8_MMA(1, 1, At, B1); PG8_BAR; PG8_SCHED;
	s_setprio 1
	s_waitcnt lgkmcnt(0)
	v_mfma_f32_16x16x32_bf16 v[68:71], v[16:19], v[188:191], v[68:71]
	v_mfma_f32_16x16x32_bf16 v[64:67], v[120:123], v[188:191], v[64:67]
	v_mfma_f32_16x16x32_bf16 v[48:51], v[120:123], v[196:199], v[48:51]
	v_mfma_f32_16x16x32_bf16 v[52:55], v[16:19], v[196:199], v[52:55]
	v_mfma_f32_16x16x32_bf16 v[36:39], v[16:19], v[208:211], v[36:39]
	v_mfma_f32_16x16x32_bf16 v[32:35], v[120:123], v[208:211], v[32:35]
	v_mfma_f32_16x16x32_bf16 v[8:11], v[120:123], v[230:233], v[8:11]
	v_mfma_f32_16x16x32_bf16 v[12:15], v[16:19], v[230:233], v[12:15]
	v_mfma_f32_16x16x32_bf16 v[68:71], v[24:27], v[192:195], v[68:71]
	v_mfma_f32_16x16x32_bf16 v[64:67], v[132:135], v[192:195], v[64:67]
	v_mfma_f32_16x16x32_bf16 v[48:51], v[132:135], v[200:203], v[48:51]
	v_mfma_f32_16x16x32_bf16 v[52:55], v[24:27], v[200:203], v[52:55]
	v_mfma_f32_16x16x32_bf16 v[36:39], v[24:27], v[214:217], v[36:39]
	v_mfma_f32_16x16x32_bf16 v[32:35], v[132:135], v[214:217], v[32:35]
	v_mfma_f32_16x16x32_bf16 v[8:11], v[132:135], v[234:237], v[8:11]
	v_mfma_f32_16x16x32_bf16 v[12:15], v[24:27], v[234:237], v[12:15]
	s_setprio 0
	s_setprio 1
	v_mfma_f32_16x16x32_bf16 v[44:47], v[140:143], v[196:199], v[44:47]
	v_mfma_f32_16x16x32_bf16 v[40:43], v[176:179], v[196:199], v[40:43]
	v_mfma_f32_16x16x32_bf16 v[28:31], v[140:143], v[208:211], v[28:31]
	v_mfma_f32_16x16x32_bf16 v[20:23], v[176:179], v[208:211], v[20:23]
	v_mfma_f32_16x16x32_bf16 v[4:7], v[140:143], v[230:233], v[4:7]
	v_mfma_f32_16x16x32_bf16 v[0:3], v[176:179], v[230:233], v[0:3]
	v_mfma_f32_16x16x32_bf16 v[16:19], v[140:143], v[188:191], v[60:63]
	v_mfma_f32_16x16x32_bf16 v[24:27], v[176:179], v[188:191], v[56:59]
	v_mfma_f32_16x16x32_bf16 v[44:47], v[148:151], v[200:203], v[44:47]
	v_mfma_f32_16x16x32_bf16 v[40:43], v[184:187], v[200:203], v[40:43]
	v_mfma_f32_16x16x32_bf16 v[28:31], v[148:151], v[214:217], v[28:31]
	v_mfma_f32_16x16x32_bf16 v[20:23], v[184:187], v[214:217], v[20:23]
	v_mfma_f32_16x16x32_bf16 v[4:7], v[148:151], v[234:237], v[4:7]
	v_mfma_f32_16x16x32_bf16 v[0:3], v[184:187], v[234:237], v[0:3]
	v_mfma_f32_16x16x32_bf16 v[16:19], v[148:151], v[192:195], v[16:19]
	v_mfma_f32_16x16x32_bf16 v[24:27], v[184:187], v[192:195], v[24:27]
	s_setprio 0
	s_barrier
	s_add_i32 s17, 0, 0x18000
	s_add_i32 s36, 0, 0x1c000
	v_add_u32_e32 v132, s17, v182
	v_add_u32_e32 v184, s36, v182
	ds_read_b128 v[56:59], v132
	ds_read_b128 v[60:63], v132 offset:1024
	ds_read_b128 v[120:123], v132 offset:2048
	ds_read_b128 v[132:135], v132 offset:3072
	ds_read_b128 v[140:143], v184
	ds_read_b128 v[148:151], v184 offset:1024
	ds_read_b128 v[176:179], v184 offset:2048
	ds_read_b128 v[184:187], v184 offset:3072
	s_add_u32 s2, s76, 0x10000
	s_addc_u32 s3, s77, 0
	s_mov_b32 m0, s44
	v_lshl_add_u64 v[206:207], s[2:3], 0, v[152:153]
	ds_read_b128 v[188:191], v183 offset:32768
	ds_read_b128 v[192:195], v183 offset:33792
	ds_read_b128 v[196:199], v183 offset:34816
	ds_read_b128 v[200:203], v183 offset:35840
	ds_read_b128 v[208:211], v183 offset:36864
	ds_read_b128 v[214:217], v183 offset:37888
	ds_read_b128 v[230:233], v183 offset:38912
	ds_read_b128 v[234:237], v183 offset:39936
	global_load_lds_dwordx4 v[206:207], off
	v_lshl_add_u64 v[206:207], s[2:3], 0, v[154:155]
	s_mov_b32 m0, s45
	s_nop 0
	global_load_lds_dwordx4 v[206:207], off
	s_waitcnt vmcnt(8)
	s_waitcnt lgkmcnt(0)
	s_barrier
	s_setprio 1
	s_waitcnt lgkmcnt(0)
	v_mfma_f32_16x16x32_bf16 v[144:147], v[56:59], v[188:191], v[144:147]
	v_mfma_f32_16x16x32_bf16 v[136:139], v[120:123], v[188:191], v[136:139]
	v_mfma_f32_16x16x32_bf16 v[112:115], v[120:123], v[196:199], v[112:115]
	v_mfma_f32_16x16x32_bf16 v[116:119], v[56:59], v[196:199], v[116:119]
	v_mfma_f32_16x16x32_bf16 v[100:103], v[56:59], v[208:211], v[100:103]
	v_mfma_f32_16x16x32_bf16 v[96:99], v[120:123], v[208:211], v[96:99]
	v_mfma_f32_16x16x32_bf16 v[80:83], v[120:123], v[230:233], v[80:83]
	v_mfma_f32_16x16x32_bf16 v[84:87], v[56:59], v[230:233], v[84:87]
	v_mfma_f32_16x16x32_bf16 v[144:147], v[60:63], v[192:195], v[144:147]
	v_mfma_f32_16x16x32_bf16 v[136:139], v[132:135], v[192:195], v[136:139]
	v_mfma_f32_16x16x32_bf16 v[112:115], v[132:135], v[200:203], v[112:115]
	v_mfma_f32_16x16x32_bf16 v[116:119], v[60:63], v[200:203], v[116:119]
	v_mfma_f32_16x16x32_bf16 v[100:103], v[60:63], v[214:217], v[100:103]
	v_mfma_f32_16x16x32_bf16 v[96:99], v[132:135], v[214:217], v[96:99]
	v_mfma_f32_16x16x32_bf16 v[80:83], v[132:135], v[234:237], v[80:83]
	v_mfma_f32_16x16x32_bf16 v[84:87], v[60:63], v[234:237], v[84:87]
	s_setprio 0
	s_setprio 1
	v_mfma_f32_16x16x32_bf16 v[128:131], v[140:143], v[188:191], v[128:131]
	v_mfma_f32_16x16x32_bf16 v[124:127], v[176:179], v[188:191], v[124:127]
	v_mfma_f32_16x16x32_bf16 v[104:107], v[176:179], v[196:199], v[104:107]
	v_mfma_f32_16x16x32_bf16 v[108:111], v[140:143], v[196:199], v[108:111]
	v_mfma_f32_16x16x32_bf16 v[92:95], v[140:143], v[208:211], v[92:95]
	v_mfma_f32_16x16x32_bf16 v[88:91], v[176:179], v[208:211], v[88:91]
	v_mfma_f32_16x16x32_bf16 v[72:75], v[176:179], v[230:233], v[72:75]
	v_mfma_f32_16x16x32_bf16 v[76:79], v[140:143], v[230:233], v[76:79]
	v_mfma_f32_16x16x32_bf16 v[128:131], v[148:151], v[192:195], v[128:131]
	v_mfma_f32_16x16x32_bf16 v[124:127], v[184:187], v[192:195], v[124:127]
	v_mfma_f32_16x16x32_bf16 v[104:107], v[184:187], v[200:203], v[104:107]
	v_mfma_f32_16x16x32_bf16 v[108:111], v[148:151], v[200:203], v[108:111]
	v_mfma_f32_16x16x32_bf16 v[92:95], v[148:151], v[214:217], v[92:95]
	v_mfma_f32_16x16x32_bf16 v[88:91], v[184:187], v[214:217], v[88:91]
	v_mfma_f32_16x16x32_bf16 v[72:75], v[184:187], v[234:237], v[72:75]
	v_mfma_f32_16x16x32_bf16 v[76:79], v[148:151], v[234:237], v[76:79]
	s_setprio 0
	s_barrier
; #define PG8_STAGE(bufoff, gbase, voff) do { _Pragma("unroll") for (int _i = 0; _i < 2; ++_i) \
;         __builtin_amdgcn_global_load_lds((const unsigned*)((const char*)(gbase) + (voff)[_i]), (LAS unsigned*)(lds + (bufoff) + ldsw + _i * 8192), 16, 0, 0); } while (0)
; #define PG8_LDA(dst, b, h) do { _Pragma("unroll") for (int m = 0; m < 4; ++m) _Pragma("unroll") for (int k = 0; k < 2; ++k) dst[m][k] = *(const LAS bf16x8*)(lds + PG8_SA(b, h) + aoff + m * 2048 + k * 1024); } while (0)
; #define PG8_MMA(ai, bj, At, Bt) do { __builtin_amdgcn_s_setprio(1); _Pragma("unroll") for (int m = 0; m < 4; ++m) _Pragma("unroll") for (int n = 0; n < 2; ++n) _Pragma("unroll") for (int k = 0; k < 2; ++k) \
;         acc[ai][bj][m][n] = __builtin_amdgcn_mfma_f32_16x16x32_bf16(Bt[n][k], At[m][k], acc[ai][bj][m][n], 0, 0, 0); __builtin_amdgcn_s_setprio(0); } while (0)
; #define PG8_WAIT_V(n) asm volatile("s_waitcnt vmcnt(" #n ")" ::: "memory")
; #define PG8_WAIT_L(n) asm volatile("s_waitcnt lgkmcnt(" #n ")" ::: "memory")
; #define PG8_BAR __builtin_amdgcn_s_barrier()
; #define PG8_SCHED __builtin_amdgcn_sched_barrier(0)
;     ...
;             PG8_LDA(At, 1, 1); PG8_STAGE(PG8_SB(1, 0), b3, voffB); PG8_STAGE(PG8_SB(1, 1), b3 + hB, voffB); PG8_STAGE(PG8_SA(1, 0), a3, voffA);
;             PG8_WAIT_V(8); PG8_WAIT_L(0); PG8_BAR; PG8_MMA(1, 0, At, B0); PG8_MMA(1, 1, At, B1); PG8_BAR; PG8_SCHED;
	s_add_i32 s2, s17, s93
	v_lshl_add_u64 v[180:181], v[180:181], 0, s[38:39]
	s_mov_b32 m0, s2
	ds_read_b128 v[188:191], v183 offset:49152
	ds_read_b128 v[192:195], v183 offset:50176
	ds_read_b128 v[196:199], v183 offset:51200
	ds_read_b128 v[200:203], v183 offset:52224
	ds_read_b128 v[208:211], v183 offset:53248
	ds_read_b128 v[214:217], v183 offset:54272
	ds_read_b128 v[230:233], v183 offset:55296
	ds_read_b128 v[234:237], v183 offset:56320
	global_load_lds_dwordx4 v[180:181], off
	s_add_i32 m0, s2, 0x2000
	s_add_u32 s2, s72, 0x18080
	v_lshl_add_u64 v[180:181], v[204:205], 0, s[38:39]
	s_addc_u32 s3, s73, 0
	s_add_i32 s17, s36, s93
	global_load_lds_dwordx4 v[180:181], off
	v_lshl_add_u64 v[180:181], s[2:3], 0, v[156:157]
	s_mov_b32 m0, s17
	s_nop 0
	global_load_lds_dwordx4 v[180:181], off
	v_lshl_add_u64 v[180:181], s[2:3], 0, v[168:169]
	s_add_i32 m0, s17, 0x2000
	s_nop 0
	global_load_lds_dwordx4 v[180:181], off
	v_lshl_add_u64 v[180:181], s[74:75], 0, v[152:153]
	s_mov_b32 m0, s51
	s_nop 0
	global_load_lds_dwordx4 v[180:181], off
	v_lshl_add_u64 v[180:181], s[74:75], 0, v[154:155]
	s_mov_b32 m0, s50
	s_nop 0
	global_load_lds_dwordx4 v[180:181], off
	s_waitcnt vmcnt(8)
	s_waitcnt lgkmcnt(0)
	s_barrier
	s_setprio 1
	s_waitcnt lgkmcnt(0)
	v_mfma_f32_16x16x32_bf16 v[68:71], v[56:59], v[188:191], v[68:71]
	v_mfma_f32_16x16x32_bf16 v[64:67], v[120:123], v[188:191], v[64:67]
	v_mfma_f32_16x16x32_bf16 v[48:51], v[120:123], v[196:199], v[48:51]
	v_mfma_f32_16x16x32_bf16 v[52:55], v[56:59], v[196:199], v[52:55]
	v_mfma_f32_16x16x32_bf16 v[36:39], v[56:59], v[208:211], v[36:39]
	v_mfma_f32_16x16x32_bf16 v[32:35], v[120:123], v[208:211], v[32:35]
	v_mfma_f32_16x16x32_bf16 v[8:11], v[120:123], v[230:233], v[8:11]
	v_mfma_f32_16x16x32_bf16 v[12:15], v[56:59], v[230:233], v[12:15]
	v_mfma_f32_16x16x32_bf16 v[68:71], v[60:63], v[192:195], v[68:71]
	v_mfma_f32_16x16x32_bf16 v[64:67], v[132:135], v[192:195], v[64:67]
	v_mfma_f32_16x16x32_bf16 v[48:51], v[132:135], v[200:203], v[48:51]
	v_mfma_f32_16x16x32_bf16 v[52:55], v[60:63], v[200:203], v[52:55]
	v_mfma_f32_16x16x32_bf16 v[36:39], v[60:63], v[214:217], v[36:39]
	v_mfma_f32_16x16x32_bf16 v[32:35], v[132:135], v[214:217], v[32:35]
	v_mfma_f32_16x16x32_bf16 v[8:11], v[132:135], v[234:237], v[8:11]
	v_mfma_f32_16x16x32_bf16 v[12:15], v[60:63], v[234:237], v[12:15]
	s_setprio 0
	s_setprio 1
	v_mfma_f32_16x16x32_bf16 v[16:19], v[140:143], v[188:191], v[16:19]
	v_mfma_f32_16x16x32_bf16 v[60:63], v[148:151], v[192:195], v[16:19]
	v_mfma_f32_16x16x32_bf16 v[16:19], v[176:179], v[188:191], v[24:27]
	v_mfma_f32_16x16x32_bf16 v[56:59], v[184:187], v[192:195], v[16:19]
	v_mfma_f32_16x16x32_bf16 v[16:19], v[140:143], v[196:199], v[44:47]
	v_mfma_f32_16x16x32_bf16 v[44:47], v[148:151], v[200:203], v[16:19]
	v_mfma_f32_16x16x32_bf16 v[16:19], v[176:179], v[196:199], v[40:43]
	v_mfma_f32_16x16x32_bf16 v[40:43], v[184:187], v[200:203], v[16:19]
	v_mfma_f32_16x16x32_bf16 v[16:19], v[140:143], v[208:211], v[28:31]
	v_mfma_f32_16x16x32_bf16 v[28:31], v[148:151], v[214:217], v[16:19]
	v_mfma_f32_16x16x32_bf16 v[16:19], v[176:179], v[208:211], v[20:23]
	v_mfma_f32_16x16x32_bf16 v[4:7], v[140:143], v[230:233], v[4:7]
	v_mfma_f32_16x16x32_bf16 v[0:3], v[176:179], v[230:233], v[0:3]
	v_mfma_f32_16x16x32_bf16 v[20:23], v[184:187], v[214:217], v[16:19]
	v_mfma_f32_16x16x32_bf16 v[4:7], v[148:151], v[234:237], v[4:7]
	v_mfma_f32_16x16x32_bf16 v[0:3], v[184:187], v[234:237], v[0:3]
	s_setprio 0
	s_barrier
	s_add_u32 s90, s90, 0x100
	s_addc_u32 s91, s91, 0
	s_add_u32 s9, s9, 0x100
	s_addc_u32 s13, s13, 0
	s_cmp_gt_u32 s15, 3
	s_mov_b32 s72, s15
	s_cbranch_scc1 .LBB0_103

; #define PG8_STAGE(bufoff, gbase, voff) do { _Pragma("unroll") for (int _i = 0; _i < 2; ++_i) \
;         __builtin_amdgcn_global_load_lds((const unsigned*)((const char*)(gbase) + (voff)[_i]), (LAS unsigned*)(lds + (bufoff) + ldsw + _i * 8192), 16, 0, 0); } while (0)
; #define PG8_LDA(dst, b, h) do { _Pragma("unroll") for (int m = 0; m < 4; ++m) _Pragma("unroll") for (int k = 0; k < 2; ++k) dst[m][k] = *(const LAS bf16x8*)(lds + PG8_SA(b, h) + aoff + m * 2048 + k * 1024); } while (0)
; #define PG8_LDB(dst, b, h) do { _Pragma("unroll") for (int n = 0; n < 2; ++n) _Pragma("unroll") for (int k = 0; k < 2; ++k) dst[n][k] = *(const LAS bf16x8*)(lds + PG8_SB(b, h) + boff + n * 2048 + k * 1024); } while (0)
; #define PG8_MMA(ai, bj, At, Bt) do { __builtin_amdgcn_s_setprio(1); _Pragma("unroll") for (int m = 0; m < 4; ++m) _Pragma("unroll") for (int n = 0; n < 2; ++n) _Pragma("unroll") for (int k = 0; k < 2; ++k) \
;         acc[ai][bj][m][n] = __builtin_amdgcn_mfma_f32_16x16x32_bf16(Bt[n][k], At[m][k], acc[ai][bj][m][n], 0, 0, 0); __builtin_amdgcn_s_setprio(0); } while (0)
; #define PG8_WAIT_V(n) asm volatile("s_waitcnt vmcnt(" #n ")" ::: "memory")
; #define PG8_WAIT_L(n) asm volatile("s_waitcnt lgkmcnt(" #n ")" ::: "memory")
; #define PG8_BAR __builtin_amdgcn_s_barrier()
; #define PG8_SCHED __builtin_amdgcn_sched_barrier(0)
;     ...
;             PG8_LDB(B0, 0, 0); PG8_LDB(B1, 0, 1); PG8_SCHED; PG8_LDA(At, 0, 0); PG8_STAGE(PG8_SA(1, 1), a1 + hA, voffA);
;             PG8_WAIT_V(8); PG8_WAIT_L(0); PG8_BAR; PG8_MMA(0, 0, At, B0); PG8_MMA(0, 1, At, B1); PG8_BAR; PG8_SCHED;
;             PG8_LDA(At, 0, 1); PG8_STAGE(PG8_SB(0, 0), b2, voffB); PG8_STAGE(PG8_SB(0, 1), b2 + hB, voffB); PG8_STAGE(PG8_SA(0, 0), a2, voffA);
;             PG8_WAIT_V(8); PG8_WAIT_L(0); PG8_BAR; PG8_MMA(1, 0, At, B0); PG8_MMA(1, 1, At, B1); PG8_BAR; PG8_SCHED;
.LBB0_119:
	s_add_u32 s2, s52, s94
	s_addc_u32 s3, s53, s95
	s_add_u32 s76, s2, 0x100
	s_addc_u32 s77, s3, 0
	s_add_u32 s74, s80, s94
	s_addc_u32 s75, s81, s95
	s_add_u32 s2, s2, 0x180
	s_addc_u32 s3, s3, 0
	s_add_i32 vcc_hi, 0, 0x10000
	s_add_i32 s12, 0, 0x14000
	v_add_u32_e32 v155, vcc_hi, v153
	ds_read_b128 v[168:171], v155
	ds_read_b128 v[172:175], v155 offset:1024
	ds_read_b128 v[176:179], v155 offset:2048
	ds_read_b128 v[180:183], v155 offset:3072
	v_add_u32_e32 v155, s12, v153
	ds_read_b128 v[184:187], v155
	ds_read_b128 v[188:191], v155 offset:1024
	ds_read_b128 v[192:195], v155 offset:2048
	ds_read_b128 v[196:199], v155 offset:3072
	s_cmpk_eq_i32 s94, 0x300
	s_cselect_b32 s73, s97, s3
	s_cselect_b32 s72, s96, s2
	s_cselect_b32 s75, s82, s75
	s_cselect_b32 s74, s91, s74
	s_cselect_b32 s77, s83, s77
	s_cselect_b32 s76, s89, s76
	v_lshl_add_u64 v[204:205], v[142:143], 0, s[94:95]
	s_add_i32 m0, s1, 0xc000
	ds_read_b128 v[208:211], v154
	ds_read_b128 v[214:217], v154 offset:1024
	ds_read_b128 v[230:233], v154 offset:2048
	ds_read_b128 v[234:237], v154 offset:3072
	ds_read_b128 v[238:241], v154 offset:4096
	ds_read_b128 v[242:245], v154 offset:5120
	ds_read_b128 v[246:249], v154 offset:6144
	ds_read_b128 v[200:203], v154 offset:7168
	global_load_lds_dwordx4 v[204:205], off
	v_lshl_add_u64 v[204:205], v[144:145], 0, s[94:95]
	s_add_i32 m0, s1, 0xe000
	s_nop 0
	global_load_lds_dwordx4 v[204:205], off
	s_waitcnt vmcnt(8)
	s_waitcnt lgkmcnt(0)
	s_barrier
	s_setprio 1
	s_waitcnt lgkmcnt(0)
	v_mfma_f32_16x16x32_bf16 v[124:127], v[168:171], v[208:211], v[124:127]
	v_mfma_f32_16x16x32_bf16 v[120:123], v[176:179], v[208:211], v[120:123]
	v_mfma_f32_16x16x32_bf16 v[112:115], v[176:179], v[230:233], v[112:115]
	v_mfma_f32_16x16x32_bf16 v[116:119], v[168:171], v[230:233], v[116:119]
	v_mfma_f32_16x16x32_bf16 v[108:111], v[168:171], v[238:241], v[108:111]
	v_mfma_f32_16x16x32_bf16 v[100:103], v[176:179], v[238:241], v[100:103]
	v_mfma_f32_16x16x32_bf16 v[84:87], v[176:179], v[246:249], v[84:87]
	v_mfma_f32_16x16x32_bf16 v[92:95], v[168:171], v[246:249], v[92:95]
	v_mfma_f32_16x16x32_bf16 v[124:127], v[172:175], v[214:217], v[124:127]
	v_mfma_f32_16x16x32_bf16 v[120:123], v[180:183], v[214:217], v[120:123]
	v_mfma_f32_16x16x32_bf16 v[112:115], v[180:183], v[234:237], v[112:115]
	v_mfma_f32_16x16x32_bf16 v[116:119], v[172:175], v[234:237], v[116:119]
	v_mfma_f32_16x16x32_bf16 v[108:111], v[172:175], v[242:245], v[108:111]
	v_mfma_f32_16x16x32_bf16 v[100:103], v[180:183], v[242:245], v[100:103]
	v_mfma_f32_16x16x32_bf16 v[84:87], v[180:183], v[200:203], v[84:87]
	v_mfma_f32_16x16x32_bf16 v[92:95], v[172:175], v[200:203], v[92:95]
	s_setprio 0
	s_setprio 1
	v_mfma_f32_16x16x32_bf16 v[104:107], v[184:187], v[208:211], v[104:107]
	v_mfma_f32_16x16x32_bf16 v[96:99], v[192:195], v[208:211], v[96:99]
	v_mfma_f32_16x16x32_bf16 v[80:83], v[192:195], v[230:233], v[80:83]
	v_mfma_f32_16x16x32_bf16 v[88:91], v[184:187], v[230:233], v[88:91]
	v_mfma_f32_16x16x32_bf16 v[76:79], v[184:187], v[238:241], v[76:79]
	v_mfma_f32_16x16x32_bf16 v[72:75], v[192:195], v[238:241], v[72:75]
	v_mfma_f32_16x16x32_bf16 v[64:67], v[192:195], v[246:249], v[64:67]
	v_mfma_f32_16x16x32_bf16 v[68:71], v[184:187], v[246:249], v[68:71]
	v_mfma_f32_16x16x32_bf16 v[104:107], v[188:191], v[214:217], v[104:107]
	v_mfma_f32_16x16x32_bf16 v[96:99], v[196:199], v[214:217], v[96:99]
	v_mfma_f32_16x16x32_bf16 v[80:83], v[196:199], v[234:237], v[80:83]
	v_mfma_f32_16x16x32_bf16 v[88:91], v[188:191], v[234:237], v[88:91]
	v_mfma_f32_16x16x32_bf16 v[76:79], v[188:191], v[242:245], v[76:79]
	v_mfma_f32_16x16x32_bf16 v[72:75], v[196:199], v[242:245], v[72:75]
	v_mfma_f32_16x16x32_bf16 v[64:67], v[196:199], v[200:203], v[64:67]
	v_mfma_f32_16x16x32_bf16 v[68:71], v[188:191], v[200:203], v[68:71]
	s_setprio 0
	s_barrier
	s_add_i32 s2, vcc_hi, s0
	v_lshl_add_u64 v[204:205], s[74:75], 0, v[130:131]
	s_mov_b32 m0, s2
	ds_read_b128 v[200:203], v154 offset:16384
	ds_read_b128 v[208:211], v154 offset:17408
	ds_read_b128 v[214:217], v154 offset:18432
	ds_read_b128 v[230:233], v154 offset:19456
	ds_read_b128 v[234:237], v154 offset:20480
	ds_read_b128 v[238:241], v154 offset:21504
	ds_read_b128 v[242:245], v154 offset:22528
	ds_read_b128 v[246:249], v154 offset:23552
	global_load_lds_dwordx4 v[204:205], off
	s_add_i32 m0, s2, 0x2000
	s_add_u32 s2, s74, 0x20000
	v_lshl_add_u64 v[206:207], s[74:75], 0, v[134:135]
	s_addc_u32 s3, s75, 0
	s_add_i32 s12, s12, s0
	global_load_lds_dwordx4 v[206:207], off
	v_lshl_add_u64 v[250:251], s[2:3], 0, v[130:131]
	s_mov_b32 m0, s12
	s_nop 0
	global_load_lds_dwordx4 v[250:251], off
	v_lshl_add_u64 v[250:251], s[2:3], 0, v[134:135]
	s_add_i32 m0, s12, 0x2000
	s_nop 0
	global_load_lds_dwordx4 v[250:251], off
	v_lshl_add_u64 v[250:251], s[76:77], 0, v[128:129]
	s_mov_b32 m0, s1
	s_nop 0
	global_load_lds_dwordx4 v[250:251], off
	v_lshl_add_u64 v[250:251], s[76:77], 0, v[132:133]
	s_mov_b32 m0, s4
	s_nop 0
	global_load_lds_dwordx4 v[250:251], off
	s_waitcnt vmcnt(8)
	s_waitcnt lgkmcnt(0)
	s_barrier
; #define PG8_STAGE(bufoff, gbase, voff) do { _Pragma("unroll") for (int _i = 0; _i < 2; ++_i) \
;         __builtin_amdgcn_global_load_lds((const unsigned*)((const char*)(gbase) + (voff)[_i]), (LAS unsigned*)(lds + (bufoff) + ldsw + _i * 8192), 16, 0, 0); } while (0)
; #define PG8_LDA(dst, b, h) do { _Pragma("unroll") for (int m = 0; m < 4; ++m) _Pragma("unroll") for (int k = 0; k < 2; ++k) dst[m][k] = *(const LAS bf16x8*)(lds + PG8_SA(b, h) + aoff + m * 2048 + k * 1024); } while (0)
; #define PG8_LDB(dst, b, h) do { _Pragma("unroll") for (int n = 0; n < 2; ++n) _Pragma("unroll") for (int k = 0; k < 2; ++k) dst[n][k] = *(const LAS bf16x8*)(lds + PG8_SB(b, h) + boff + n * 2048 + k * 1024); } while (0)
; #define PG8_MMA(ai, bj, At, Bt) do { __builtin_amdgcn_s_setprio(1); _Pragma("unroll") for (int m = 0; m < 4; ++m) _Pragma("unroll") for (int n = 0; n < 2; ++n) _Pragma("unroll") for (int k = 0; k < 2; ++k) \
;         acc[ai][bj][m][n] = __builtin_amdgcn_mfma_f32_16x16x32_bf16(Bt[n][k], At[m][k], acc[ai][bj][m][n], 0, 0, 0); __builtin_amdgcn_s_setprio(0); } while (0)
; #define PG8_WAIT_V(n) asm volatile("s_waitcnt vmcnt(" #n ")" ::: "memory")
; #define PG8_WAIT_L(n) asm volatile("s_waitcnt lgkmcnt(" #n ")" ::: "memory")
; #define PG8_BAR __builtin_amdgcn_s_barrier()
; #define PG8_SCHED __builtin_amdgcn_sched_barrier(0)
;     ...
;             PG8_WAIT_V(8); PG8_WAIT_L(0); PG8_BAR; PG8_MMA(1, 0, At, B0); PG8_MMA(1, 1, At, B1); PG8_BAR; PG8_SCHED;
;             PG8_LDB(B0, 1, 0); PG8_LDB(B1, 1, 1); PG8_SCHED; PG8_LDA(At, 1, 0); PG8_STAGE(PG8_SA(0, 1), a2 + hA, voffA);
;             PG8_WAIT_V(8); PG8_WAIT_L(0); PG8_BAR; PG8_MMA(0, 0, At, B0); PG8_MMA(0, 1, At, B1); PG8_BAR; PG8_SCHED;
	s_setprio 1
	s_waitcnt lgkmcnt(0)
	v_mfma_f32_16x16x32_bf16 v[60:63], v[168:171], v[200:203], v[60:63]
	v_mfma_f32_16x16x32_bf16 v[56:59], v[176:179], v[200:203], v[56:59]
	v_mfma_f32_16x16x32_bf16 v[48:51], v[176:179], v[214:217], v[48:51]
	v_mfma_f32_16x16x32_bf16 v[52:55], v[168:171], v[214:217], v[52:55]
	v_mfma_f32_16x16x32_bf16 v[44:47], v[168:171], v[234:237], v[44:47]
	v_mfma_f32_16x16x32_bf16 v[36:39], v[176:179], v[234:237], v[36:39]
	v_mfma_f32_16x16x32_bf16 v[20:23], v[176:179], v[242:245], v[20:23]
	v_mfma_f32_16x16x32_bf16 v[28:31], v[168:171], v[242:245], v[28:31]
	v_mfma_f32_16x16x32_bf16 v[60:63], v[172:175], v[208:211], v[60:63]
	v_mfma_f32_16x16x32_bf16 v[56:59], v[180:183], v[208:211], v[56:59]
	v_mfma_f32_16x16x32_bf16 v[48:51], v[180:183], v[230:233], v[48:51]
	v_mfma_f32_16x16x32_bf16 v[52:55], v[172:175], v[230:233], v[52:55]
	v_mfma_f32_16x16x32_bf16 v[44:47], v[172:175], v[238:241], v[44:47]
	v_mfma_f32_16x16x32_bf16 v[36:39], v[180:183], v[238:241], v[36:39]
	v_mfma_f32_16x16x32_bf16 v[20:23], v[180:183], v[246:249], v[20:23]
	v_mfma_f32_16x16x32_bf16 v[28:31], v[172:175], v[246:249], v[28:31]
	s_setprio 0
	s_setprio 1
	v_mfma_f32_16x16x32_bf16 v[40:43], v[184:187], v[200:203], v[40:43]
	v_mfma_f32_16x16x32_bf16 v[32:35], v[192:195], v[200:203], v[32:35]
	v_mfma_f32_16x16x32_bf16 v[16:19], v[192:195], v[214:217], v[16:19]
	v_mfma_f32_16x16x32_bf16 v[24:27], v[184:187], v[214:217], v[24:27]
	v_mfma_f32_16x16x32_bf16 v[12:15], v[184:187], v[234:237], v[12:15]
	v_mfma_f32_16x16x32_bf16 v[8:11], v[192:195], v[234:237], v[8:11]
	v_mfma_f32_16x16x32_bf16 v[0:3], v[192:195], v[242:245], v[0:3]
	v_mfma_f32_16x16x32_bf16 v[4:7], v[184:187], v[242:245], v[4:7]
	v_mfma_f32_16x16x32_bf16 v[40:43], v[188:191], v[208:211], v[40:43]
	v_mfma_f32_16x16x32_bf16 v[32:35], v[196:199], v[208:211], v[32:35]
	v_mfma_f32_16x16x32_bf16 v[16:19], v[196:199], v[230:233], v[16:19]
	v_mfma_f32_16x16x32_bf16 v[24:27], v[188:191], v[230:233], v[24:27]
	v_mfma_f32_16x16x32_bf16 v[12:15], v[188:191], v[238:241], v[12:15]
	v_mfma_f32_16x16x32_bf16 v[8:11], v[196:199], v[238:241], v[8:11]
	v_mfma_f32_16x16x32_bf16 v[0:3], v[196:199], v[246:249], v[0:3]
	v_mfma_f32_16x16x32_bf16 v[4:7], v[188:191], v[246:249], v[4:7]
	s_setprio 0
	s_barrier
	s_add_i32 s12, 0, 0x18000
	v_add_u32_e32 v155, s12, v153
	s_add_i32 s13, 0, 0x1c000
	ds_read_b128 v[168:171], v155
	ds_read_b128 v[172:175], v155 offset:1024
	ds_read_b128 v[176:179], v155 offset:2048
	ds_read_b128 v[180:183], v155 offset:3072
	v_add_u32_e32 v155, s13, v153
	ds_read_b128 v[184:187], v155
	ds_read_b128 v[188:191], v155 offset:1024
	ds_read_b128 v[192:195], v155 offset:2048
	ds_read_b128 v[196:199], v155 offset:3072
	s_add_u32 s2, s76, 0x20000
	s_addc_u32 s3, s77, 0
	s_mov_b32 m0, s5
	v_lshl_add_u64 v[250:251], s[2:3], 0, v[128:129]
	ds_read_b128 v[200:203], v154 offset:32768
	ds_read_b128 v[208:211], v154 offset:33792
	ds_read_b128 v[214:217], v154 offset:34816
	ds_read_b128 v[230:233], v154 offset:35840
	ds_read_b128 v[234:237], v154 offset:36864
	ds_read_b128 v[238:241], v154 offset:37888
	ds_read_b128 v[242:245], v154 offset:38912
	ds_read_b128 v[246:249], v154 offset:39936
	global_load_lds_dwordx4 v[250:251], off
	v_lshl_add_u64 v[250:251], s[2:3], 0, v[132:133]
	s_mov_b32 m0, s6
	s_nop 0
	global_load_lds_dwordx4 v[250:251], off
	s_waitcnt vmcnt(8)
	s_waitcnt lgkmcnt(0)
	s_barrier
	s_setprio 1
	s_waitcnt lgkmcnt(0)
	v_mfma_f32_16x16x32_bf16 v[124:127], v[168:171], v[200:203], v[124:127]
	v_mfma_f32_16x16x32_bf16 v[120:123], v[176:179], v[200:203], v[120:123]
	v_mfma_f32_16x16x32_bf16 v[112:115], v[176:179], v[214:217], v[112:115]
	v_mfma_f32_16x16x32_bf16 v[116:119], v[168:171], v[214:217], v[116:119]
	v_mfma_f32_16x16x32_bf16 v[108:111], v[168:171], v[234:237], v[108:111]
	v_mfma_f32_16x16x32_bf16 v[100:103], v[176:179], v[234:237], v[100:103]
	v_mfma_f32_16x16x32_bf16 v[84:87], v[176:179], v[242:245], v[84:87]
	v_mfma_f32_16x16x32_bf16 v[92:95], v[168:171], v[242:245], v[92:95]
	v_mfma_f32_16x16x32_bf16 v[124:127], v[172:175], v[208:211], v[124:127]
	v_mfma_f32_16x16x32_bf16 v[120:123], v[180:183], v[208:211], v[120:123]
	v_mfma_f32_16x16x32_bf16 v[112:115], v[180:183], v[230:233], v[112:115]
	v_mfma_f32_16x16x32_bf16 v[116:119], v[172:175], v[230:233], v[116:119]
	v_mfma_f32_16x16x32_bf16 v[108:111], v[172:175], v[238:241], v[108:111]
	v_mfma_f32_16x16x32_bf16 v[100:103], v[180:183], v[238:241], v[100:103]
	v_mfma_f32_16x16x32_bf16 v[84:87], v[180:183], v[246:249], v[84:87]
	v_mfma_f32_16x16x32_bf16 v[92:95], v[172:175], v[246:249], v[92:95]
	s_setprio 0
	s_setprio 1
	v_mfma_f32_16x16x32_bf16 v[104:107], v[184:187], v[200:203], v[104:107]
	v_mfma_f32_16x16x32_bf16 v[96:99], v[192:195], v[200:203], v[96:99]
	v_mfma_f32_16x16x32_bf16 v[80:83], v[192:195], v[214:217], v[80:83]
	v_mfma_f32_16x16x32_bf16 v[88:91], v[184:187], v[214:217], v[88:91]
	v_mfma_f32_16x16x32_bf16 v[76:79], v[184:187], v[234:237], v[76:79]
	v_mfma_f32_16x16x32_bf16 v[72:75], v[192:195], v[234:237], v[72:75]
	v_mfma_f32_16x16x32_bf16 v[64:67], v[192:195], v[242:245], v[64:67]
	v_mfma_f32_16x16x32_bf16 v[68:71], v[184:187], v[242:245], v[68:71]
	v_mfma_f32_16x16x32_bf16 v[104:107], v[188:191], v[208:211], v[104:107]
	v_mfma_f32_16x16x32_bf16 v[96:99], v[196:199], v[208:211], v[96:99]
	v_mfma_f32_16x16x32_bf16 v[80:83], v[196:199], v[230:233], v[80:83]
	v_mfma_f32_16x16x32_bf16 v[88:91], v[188:191], v[230:233], v[88:91]
	v_mfma_f32_16x16x32_bf16 v[76:79], v[188:191], v[238:241], v[76:79]
	v_mfma_f32_16x16x32_bf16 v[72:75], v[196:199], v[238:241], v[72:75]
	v_mfma_f32_16x16x32_bf16 v[64:67], v[196:199], v[246:249], v[64:67]
	v_mfma_f32_16x16x32_bf16 v[68:71], v[188:191], v[246:249], v[68:71]
	s_setprio 0
	s_barrier
; #define PG8_STAGE(bufoff, gbase, voff) do { _Pragma("unroll") for (int _i = 0; _i < 2; ++_i) \
;         __builtin_amdgcn_global_load_lds((const unsigned*)((const char*)(gbase) + (voff)[_i]), (LAS unsigned*)(lds + (bufoff) + ldsw + _i * 8192), 16, 0, 0); } while (0)
; #define PG8_LDA(dst, b, h) do { _Pragma("unroll") for (int m = 0; m < 4; ++m) _Pragma("unroll") for (int k = 0; k < 2; ++k) dst[m][k] = *(const LAS bf16x8*)(lds + PG8_SA(b, h) + aoff + m * 2048 + k * 1024); } while (0)
; #define PG8_MMA(ai, bj, At, Bt) do { __builtin_amdgcn_s_setprio(1); _Pragma("unroll") for (int m = 0; m < 4; ++m) _Pragma("unroll") for (int n = 0; n < 2; ++n) _Pragma("unroll") for (int k = 0; k < 2; ++k) \
;         acc[ai][bj][m][n] = __builtin_amdgcn_mfma_f32_16x16x32_bf16(Bt[n][k], At[m][k], acc[ai][bj][m][n], 0, 0, 0); __builtin_amdgcn_s_setprio(0); } while (0)
; #define PG8_WAIT_V(n) asm volatile("s_waitcnt vmcnt(" #n ")" ::: "memory")
; #define PG8_WAIT_L(n) asm volatile("s_waitcnt lgkmcnt(" #n ")" ::: "memory")
; #define PG8_BAR __builtin_amdgcn_s_barrier()
; #define PG8_SCHED __builtin_amdgcn_sched_barrier(0)
;     ...
;         for (int t = 0; t < nt; t += 2) {
;     ...
;             PG8_LDA(At, 1, 1); PG8_STAGE(PG8_SB(1, 0), b3, voffB); PG8_STAGE(PG8_SB(1, 1), b3 + hB, voffB); PG8_STAGE(PG8_SA(1, 0), a3, voffA);
;             PG8_WAIT_V(8); PG8_WAIT_L(0); PG8_BAR; PG8_MMA(1, 0, At, B0); PG8_MMA(1, 1, At, B1); PG8_BAR; PG8_SCHED;
	s_add_i32 s2, s12, s0
	v_lshl_add_u64 v[204:205], v[204:205], 0, s[38:39]
	s_mov_b32 m0, s2
	ds_read_b128 v[200:203], v154 offset:49152
	ds_read_b128 v[208:211], v154 offset:50176
	ds_read_b128 v[214:217], v154 offset:51200
	ds_read_b128 v[230:233], v154 offset:52224
	ds_read_b128 v[234:237], v154 offset:53248
	ds_read_b128 v[238:241], v154 offset:54272
	ds_read_b128 v[242:245], v154 offset:55296
	ds_read_b128 v[246:249], v154 offset:56320
	global_load_lds_dwordx4 v[204:205], off
	s_add_i32 m0, s2, 0x2000
	s_add_u32 s2, s74, 0x20080
	v_lshl_add_u64 v[204:205], v[206:207], 0, s[38:39]
	s_addc_u32 s3, s75, 0
	s_add_i32 s12, s13, s0
	global_load_lds_dwordx4 v[204:205], off
	v_lshl_add_u64 v[204:205], s[2:3], 0, v[130:131]
	s_mov_b32 m0, s12
	s_nop 0
	global_load_lds_dwordx4 v[204:205], off
	v_lshl_add_u64 v[204:205], s[2:3], 0, v[134:135]
	s_add_i32 m0, s12, 0x2000
	s_nop 0
	global_load_lds_dwordx4 v[204:205], off
	v_lshl_add_u64 v[204:205], s[72:73], 0, v[128:129]
	s_mov_b32 m0, s8
	s_nop 0
	global_load_lds_dwordx4 v[204:205], off
	v_lshl_add_u64 v[204:205], s[72:73], 0, v[132:133]
	s_mov_b32 m0, s9
	s_nop 0
	global_load_lds_dwordx4 v[204:205], off
	s_waitcnt vmcnt(8)
	s_waitcnt lgkmcnt(0)
	s_barrier
	s_setprio 1
	s_waitcnt lgkmcnt(0)
	v_mfma_f32_16x16x32_bf16 v[60:63], v[168:171], v[200:203], v[60:63]
	v_mfma_f32_16x16x32_bf16 v[56:59], v[176:179], v[200:203], v[56:59]
	v_mfma_f32_16x16x32_bf16 v[48:51], v[176:179], v[214:217], v[48:51]
	v_mfma_f32_16x16x32_bf16 v[52:55], v[168:171], v[214:217], v[52:55]
	v_mfma_f32_16x16x32_bf16 v[44:47], v[168:171], v[234:237], v[44:47]
	v_mfma_f32_16x16x32_bf16 v[36:39], v[176:179], v[234:237], v[36:39]
	v_mfma_f32_16x16x32_bf16 v[20:23], v[176:179], v[242:245], v[20:23]
	v_mfma_f32_16x16x32_bf16 v[28:31], v[168:171], v[242:245], v[28:31]
	v_mfma_f32_16x16x32_bf16 v[60:63], v[172:175], v[208:211], v[60:63]
	v_mfma_f32_16x16x32_bf16 v[56:59], v[180:183], v[208:211], v[56:59]
	v_mfma_f32_16x16x32_bf16 v[48:51], v[180:183], v[230:233], v[48:51]
	v_mfma_f32_16x16x32_bf16 v[52:55], v[172:175], v[230:233], v[52:55]
	v_mfma_f32_16x16x32_bf16 v[44:47], v[172:175], v[238:241], v[44:47]
	v_mfma_f32_16x16x32_bf16 v[36:39], v[180:183], v[238:241], v[36:39]
	v_mfma_f32_16x16x32_bf16 v[20:23], v[180:183], v[246:249], v[20:23]
	v_mfma_f32_16x16x32_bf16 v[28:31], v[172:175], v[246:249], v[28:31]
	s_setprio 0
	s_setprio 1
	v_mfma_f32_16x16x32_bf16 v[40:43], v[184:187], v[200:203], v[40:43]
	v_mfma_f32_16x16x32_bf16 v[32:35], v[192:195], v[200:203], v[32:35]
	v_mfma_f32_16x16x32_bf16 v[16:19], v[192:195], v[214:217], v[16:19]
	v_mfma_f32_16x16x32_bf16 v[24:27], v[184:187], v[214:217], v[24:27]
	v_mfma_f32_16x16x32_bf16 v[12:15], v[184:187], v[234:237], v[12:15]
	v_mfma_f32_16x16x32_bf16 v[8:11], v[192:195], v[234:237], v[8:11]
	v_mfma_f32_16x16x32_bf16 v[0:3], v[192:195], v[242:245], v[0:3]
	v_mfma_f32_16x16x32_bf16 v[4:7], v[184:187], v[242:245], v[4:7]
	v_mfma_f32_16x16x32_bf16 v[40:43], v[188:191], v[208:211], v[40:43]
	v_mfma_f32_16x16x32_bf16 v[32:35], v[196:199], v[208:211], v[32:35]
	v_mfma_f32_16x16x32_bf16 v[16:19], v[196:199], v[230:233], v[16:19]
	v_mfma_f32_16x16x32_bf16 v[24:27], v[188:191], v[230:233], v[24:27]
	v_mfma_f32_16x16x32_bf16 v[12:15], v[188:191], v[238:241], v[12:15]
	v_mfma_f32_16x16x32_bf16 v[8:11], v[196:199], v[238:241], v[8:11]
	v_mfma_f32_16x16x32_bf16 v[0:3], v[196:199], v[246:249], v[0:3]
	v_mfma_f32_16x16x32_bf16 v[4:7], v[188:191], v[246:249], v[4:7]
	s_setprio 0
	s_barrier
	s_add_i32 vcc_lo, vcc_lo, 2
	s_add_u32 s94, s94, 0x100
	s_addc_u32 s95, s95, 0
	s_cmp_gt_u32 vcc_lo, 5
	s_cbranch_scc0 .LBB0_119
	s_and_b64 vcc, exec, s[30:31]
	s_cbranch_vccz .LBB0_122
	s_barrier

; #define PG8_STAGE(bufoff, gbase, voff) do { _Pragma("unroll") for (int _i = 0; _i < 2; ++_i) \
;         __builtin_amdgcn_global_load_lds((const unsigned*)((const char*)(gbase) + (voff)[_i]), (LAS unsigned*)(lds + (bufoff) + ldsw + _i * 8192), 16, 0, 0); } while (0)
; #define PG8_LDA(dst, b, h) do { _Pragma("unroll") for (int m = 0; m < 4; ++m) _Pragma("unroll") for (int k = 0; k < 2; ++k) dst[m][k] = *(const LAS bf16x8*)(lds + PG8_SA(b, h) + aoff + m * 2048 + k * 1024); } while (0)
; #define PG8_LDB(dst, b, h) do { _Pragma("unroll") for (int n = 0; n < 2; ++n) _Pragma("unroll") for (int k = 0; k < 2; ++k) dst[n][k] = *(const LAS bf16x8*)(lds + PG8_SB(b, h) + boff + n * 2048 + k * 1024); } while (0)
; #define PG8_MMA(ai, bj, At, Bt) do { __builtin_amdgcn_s_setprio(1); _Pragma("unroll") for (int m = 0; m < 4; ++m) _Pragma("unroll") for (int n = 0; n < 2; ++n) _Pragma("unroll") for (int k = 0; k < 2; ++k) \
;         acc[ai][bj][m][n] = __builtin_amdgcn_mfma_f32_16x16x32_bf16(Bt[n][k], At[m][k], acc[ai][bj][m][n], 0, 0, 0); __builtin_amdgcn_s_setprio(0); } while (0)
; #define PG8_WAIT_V(n) asm volatile("s_waitcnt vmcnt(" #n ")" ::: "memory")
; #define PG8_WAIT_L(n) asm volatile("s_waitcnt lgkmcnt(" #n ")" ::: "memory")
; #define PG8_BAR __builtin_amdgcn_s_barrier()
; #define PG8_SCHED __builtin_amdgcn_sched_barrier(0)
;     ...
;             PG8_LDB(B0, 0, 0); PG8_LDB(B1, 0, 1); PG8_SCHED; PG8_LDA(At, 0, 0); PG8_STAGE(PG8_SA(1, 1), a1 + hA, voffA);
;             PG8_WAIT_V(8); PG8_WAIT_L(0); PG8_BAR; PG8_MMA(0, 0, At, B0); PG8_MMA(0, 1, At, B1); PG8_BAR; PG8_SCHED;
;             PG8_LDA(At, 0, 1); PG8_STAGE(PG8_SB(0, 0), b2, voffB); PG8_STAGE(PG8_SB(0, 1), b2 + hB, voffB); PG8_STAGE(PG8_SA(0, 0), a2, voffA);
;             PG8_WAIT_V(8); PG8_WAIT_L(0); PG8_BAR; PG8_MMA(1, 0, At, B0); PG8_MMA(1, 1, At, B1); PG8_BAR; PG8_SCHED;
.LBB0_155:
	s_add_u32 s29, s34, s44
	s_addc_u32 s36, s35, s45
	s_add_u32 s54, s29, 0x800000
	s_addc_u32 s55, s36, 0
	s_add_u32 s29, s29, 0xc00000
	s_addc_u32 s36, s36, 0
	s_add_i32 s82, 0, 0x10000
	s_add_i32 s83, 0, 0x14000
	v_add_u32_e32 v168, s82, v180
	v_add_u32_e32 v183, s83, v180
	ds_read_b128 v[120:123], v168
	ds_read_b128 v[132:135], v168 offset:1024
	ds_read_b128 v[140:143], v168 offset:2048
	ds_read_b128 v[168:171], v168 offset:3072
	ds_read_b128 v[172:175], v183
	ds_read_b128 v[176:179], v183 offset:1024
	ds_read_b128 v[184:187], v183 offset:2048
	ds_read_b128 v[188:191], v183 offset:3072
	s_cmp_eq_u32 s44, 0x3800000
	s_cselect_b32 s53, s8, s36
	s_cselect_b32 s52, s7, s29
	s_cselect_b32 s73, s5, s17
	s_cselect_b32 s72, s6, s9
	s_cselect_b32 s75, s1, s55
	s_cselect_b32 s74, s4, s54
	v_lshl_add_u64 v[204:205], v[110:111], 0, s[44:45]
	s_add_i32 m0, s78, 0xc000
	ds_read_b128 v[192:195], v182
	ds_read_b128 v[196:199], v182 offset:1024
	ds_read_b128 v[200:203], v182 offset:2048
	ds_read_b128 v[208:211], v182 offset:3072
	ds_read_b128 v[214:217], v182 offset:4096
	ds_read_b128 v[230:233], v182 offset:5120
	ds_read_b128 v[234:237], v182 offset:6144
	ds_read_b128 v[238:241], v182 offset:7168
	global_load_lds_dwordx4 v[204:205], off
	v_lshl_add_u64 v[204:205], v[108:109], 0, s[44:45]
	s_add_i32 m0, s78, 0xe000
	s_nop 0
	global_load_lds_dwordx4 v[204:205], off
	s_waitcnt vmcnt(8)
	s_waitcnt lgkmcnt(0)
	s_barrier
	s_setprio 1
	s_waitcnt lgkmcnt(0)
	v_mfma_f32_16x16x32_bf16 v[136:139], v[120:123], v[192:195], v[136:139]
	v_mfma_f32_16x16x32_bf16 v[128:131], v[140:143], v[192:195], v[128:131]
	v_mfma_f32_16x16x32_bf16 v[104:107], v[140:143], v[200:203], v[104:107]
	v_mfma_f32_16x16x32_bf16 v[112:115], v[120:123], v[200:203], v[112:115]
	v_mfma_f32_16x16x32_bf16 v[92:95], v[120:123], v[214:217], v[92:95]
	v_mfma_f32_16x16x32_bf16 v[88:91], v[140:143], v[214:217], v[88:91]
	v_mfma_f32_16x16x32_bf16 v[72:75], v[140:143], v[234:237], v[72:75]
	v_mfma_f32_16x16x32_bf16 v[76:79], v[120:123], v[234:237], v[76:79]
	v_mfma_f32_16x16x32_bf16 v[136:139], v[132:135], v[196:199], v[136:139]
	v_mfma_f32_16x16x32_bf16 v[128:131], v[168:171], v[196:199], v[128:131]
	v_mfma_f32_16x16x32_bf16 v[104:107], v[168:171], v[208:211], v[104:107]
	v_mfma_f32_16x16x32_bf16 v[112:115], v[132:135], v[208:211], v[112:115]
	v_mfma_f32_16x16x32_bf16 v[92:95], v[132:135], v[230:233], v[92:95]
	v_mfma_f32_16x16x32_bf16 v[88:91], v[168:171], v[230:233], v[88:91]
	v_mfma_f32_16x16x32_bf16 v[72:75], v[168:171], v[238:241], v[72:75]
	v_mfma_f32_16x16x32_bf16 v[76:79], v[132:135], v[238:241], v[76:79]
	s_setprio 0
	s_setprio 1
	v_mfma_f32_16x16x32_bf16 v[124:127], v[172:175], v[192:195], v[124:127]
	v_mfma_f32_16x16x32_bf16 v[116:119], v[184:187], v[192:195], v[116:119]
	v_mfma_f32_16x16x32_bf16 v[96:99], v[184:187], v[200:203], v[96:99]
	v_mfma_f32_16x16x32_bf16 v[100:103], v[172:175], v[200:203], v[100:103]
	v_mfma_f32_16x16x32_bf16 v[84:87], v[172:175], v[214:217], v[84:87]
	v_mfma_f32_16x16x32_bf16 v[80:83], v[184:187], v[214:217], v[80:83]
	v_mfma_f32_16x16x32_bf16 v[64:67], v[184:187], v[234:237], v[64:67]
	v_mfma_f32_16x16x32_bf16 v[68:71], v[172:175], v[234:237], v[68:71]
	v_mfma_f32_16x16x32_bf16 v[124:127], v[176:179], v[196:199], v[124:127]
	v_mfma_f32_16x16x32_bf16 v[116:119], v[188:191], v[196:199], v[116:119]
	v_mfma_f32_16x16x32_bf16 v[96:99], v[188:191], v[208:211], v[96:99]
	v_mfma_f32_16x16x32_bf16 v[100:103], v[176:179], v[208:211], v[100:103]
	v_mfma_f32_16x16x32_bf16 v[84:87], v[176:179], v[230:233], v[84:87]
	v_mfma_f32_16x16x32_bf16 v[80:83], v[188:191], v[230:233], v[80:83]
	v_mfma_f32_16x16x32_bf16 v[64:67], v[188:191], v[238:241], v[64:67]
	v_mfma_f32_16x16x32_bf16 v[68:71], v[176:179], v[238:241], v[68:71]
	s_setprio 0
	s_barrier
	s_add_i32 s29, s82, s77
	v_lshl_add_u64 v[204:205], s[72:73], 0, v[146:147]
	s_mov_b32 m0, s29
	ds_read_b128 v[192:195], v182 offset:16384
	ds_read_b128 v[196:199], v182 offset:17408
	ds_read_b128 v[200:203], v182 offset:18432
	ds_read_b128 v[208:211], v182 offset:19456
	ds_read_b128 v[214:217], v182 offset:20480
	ds_read_b128 v[230:233], v182 offset:21504
	ds_read_b128 v[234:237], v182 offset:22528
	ds_read_b128 v[238:241], v182 offset:23552
	global_load_lds_dwordx4 v[204:205], off
	s_add_i32 m0, s29, 0x2000
	s_add_u32 s54, s72, 0x40000
	v_lshl_add_u64 v[206:207], s[72:73], 0, v[150:151]
	s_addc_u32 s55, s73, 0
	s_add_i32 s29, s83, s77
	global_load_lds_dwordx4 v[206:207], off
	v_lshl_add_u64 v[242:243], s[54:55], 0, v[146:147]
	s_mov_b32 m0, s29
	s_nop 0
	global_load_lds_dwordx4 v[242:243], off
	v_lshl_add_u64 v[242:243], s[54:55], 0, v[150:151]
	s_add_i32 m0, s29, 0x2000
	s_nop 0
	global_load_lds_dwordx4 v[242:243], off
	v_lshl_add_u64 v[242:243], s[74:75], 0, v[144:145]
	s_mov_b32 m0, s78
	s_nop 0
	global_load_lds_dwordx4 v[242:243], off
	v_lshl_add_u64 v[242:243], s[74:75], 0, v[148:149]
	s_mov_b32 m0, s79
	s_nop 0
	global_load_lds_dwordx4 v[242:243], off
	s_waitcnt vmcnt(8)
	s_waitcnt lgkmcnt(0)
	s_barrier
; #define PG8_STAGE(bufoff, gbase, voff) do { _Pragma("unroll") for (int _i = 0; _i < 2; ++_i) \
;         __builtin_amdgcn_global_load_lds((const unsigned*)((const char*)(gbase) + (voff)[_i]), (LAS unsigned*)(lds + (bufoff) + ldsw + _i * 8192), 16, 0, 0); } while (0)
; #define PG8_LDA(dst, b, h) do { _Pragma("unroll") for (int m = 0; m < 4; ++m) _Pragma("unroll") for (int k = 0; k < 2; ++k) dst[m][k] = *(const LAS bf16x8*)(lds + PG8_SA(b, h) + aoff + m * 2048 + k * 1024); } while (0)
; #define PG8_LDB(dst, b, h) do { _Pragma("unroll") for (int n = 0; n < 2; ++n) _Pragma("unroll") for (int k = 0; k < 2; ++k) dst[n][k] = *(const LAS bf16x8*)(lds + PG8_SB(b, h) + boff + n * 2048 + k * 1024); } while (0)
; #define PG8_MMA(ai, bj, At, Bt) do { __builtin_amdgcn_s_setprio(1); _Pragma("unroll") for (int m = 0; m < 4; ++m) _Pragma("unroll") for (int n = 0; n < 2; ++n) _Pragma("unroll") for (int k = 0; k < 2; ++k) \
;         acc[ai][bj][m][n] = __builtin_amdgcn_mfma_f32_16x16x32_bf16(Bt[n][k], At[m][k], acc[ai][bj][m][n], 0, 0, 0); __builtin_amdgcn_s_setprio(0); } while (0)
; #define PG8_WAIT_V(n) asm volatile("s_waitcnt vmcnt(" #n ")" ::: "memory")
; #define PG8_WAIT_L(n) asm volatile("s_waitcnt lgkmcnt(" #n ")" ::: "memory")
; #define PG8_BAR __builtin_amdgcn_s_barrier()
; #define PG8_SCHED __builtin_amdgcn_sched_barrier(0)
;     ...
;             PG8_WAIT_V(8); PG8_WAIT_L(0); PG8_BAR; PG8_MMA(1, 0, At, B0); PG8_MMA(1, 1, At, B1); PG8_BAR; PG8_SCHED;
;             PG8_LDB(B0, 1, 0); PG8_LDB(B1, 1, 1); PG8_SCHED; PG8_LDA(At, 1, 0); PG8_STAGE(PG8_SA(0, 1), a2 + hA, voffA);
;             PG8_WAIT_V(8); PG8_WAIT_L(0); PG8_BAR; PG8_MMA(0, 0, At, B0); PG8_MMA(0, 1, At, B1); PG8_BAR; PG8_SCHED;
	s_setprio 1
	s_waitcnt lgkmcnt(0)
	v_mfma_f32_16x16x32_bf16 v[60:63], v[120:123], v[192:195], v[60:63]
	v_mfma_f32_16x16x32_bf16 v[56:59], v[140:143], v[192:195], v[56:59]
	v_mfma_f32_16x16x32_bf16 v[40:43], v[140:143], v[200:203], v[40:43]
	v_mfma_f32_16x16x32_bf16 v[44:47], v[120:123], v[200:203], v[44:47]
	v_mfma_f32_16x16x32_bf16 v[28:31], v[120:123], v[214:217], v[28:31]
	v_mfma_f32_16x16x32_bf16 v[24:27], v[140:143], v[214:217], v[24:27]
	v_mfma_f32_16x16x32_bf16 v[8:11], v[140:143], v[234:237], v[8:11]
	v_mfma_f32_16x16x32_bf16 v[12:15], v[120:123], v[234:237], v[12:15]
	v_mfma_f32_16x16x32_bf16 v[60:63], v[132:135], v[196:199], v[60:63]
	v_mfma_f32_16x16x32_bf16 v[56:59], v[168:171], v[196:199], v[56:59]
	v_mfma_f32_16x16x32_bf16 v[40:43], v[168:171], v[208:211], v[40:43]
	v_mfma_f32_16x16x32_bf16 v[44:47], v[132:135], v[208:211], v[44:47]
	v_mfma_f32_16x16x32_bf16 v[28:31], v[132:135], v[230:233], v[28:31]
	v_mfma_f32_16x16x32_bf16 v[24:27], v[168:171], v[230:233], v[24:27]
	v_mfma_f32_16x16x32_bf16 v[8:11], v[168:171], v[238:241], v[8:11]
	v_mfma_f32_16x16x32_bf16 v[12:15], v[132:135], v[238:241], v[12:15]
	s_setprio 0
	s_setprio 1
	v_mfma_f32_16x16x32_bf16 v[52:55], v[172:175], v[192:195], v[52:55]
	v_mfma_f32_16x16x32_bf16 v[48:51], v[184:187], v[192:195], v[48:51]
	v_mfma_f32_16x16x32_bf16 v[32:35], v[184:187], v[200:203], v[32:35]
	v_mfma_f32_16x16x32_bf16 v[36:39], v[172:175], v[200:203], v[36:39]
	v_mfma_f32_16x16x32_bf16 v[20:23], v[172:175], v[214:217], v[20:23]
	v_mfma_f32_16x16x32_bf16 v[16:19], v[184:187], v[214:217], v[16:19]
	v_mfma_f32_16x16x32_bf16 v[0:3], v[184:187], v[234:237], v[0:3]
	v_mfma_f32_16x16x32_bf16 v[4:7], v[172:175], v[234:237], v[4:7]
	v_mfma_f32_16x16x32_bf16 v[52:55], v[176:179], v[196:199], v[52:55]
	v_mfma_f32_16x16x32_bf16 v[48:51], v[188:191], v[196:199], v[48:51]
	v_mfma_f32_16x16x32_bf16 v[32:35], v[188:191], v[208:211], v[32:35]
	v_mfma_f32_16x16x32_bf16 v[36:39], v[176:179], v[208:211], v[36:39]
	v_mfma_f32_16x16x32_bf16 v[20:23], v[176:179], v[230:233], v[20:23]
	v_mfma_f32_16x16x32_bf16 v[16:19], v[188:191], v[230:233], v[16:19]
	v_mfma_f32_16x16x32_bf16 v[0:3], v[188:191], v[238:241], v[0:3]
	v_mfma_f32_16x16x32_bf16 v[4:7], v[176:179], v[238:241], v[4:7]
	s_setprio 0
	s_barrier
	s_add_i32 s29, 0, 0x18000
	s_add_i32 s36, 0, 0x1c000
	v_add_u32_e32 v168, s29, v180
	v_add_u32_e32 v183, s36, v180
	ds_read_b128 v[120:123], v168
	ds_read_b128 v[132:135], v168 offset:1024
	ds_read_b128 v[140:143], v168 offset:2048
	ds_read_b128 v[168:171], v168 offset:3072
	ds_read_b128 v[172:175], v183
	ds_read_b128 v[176:179], v183 offset:1024
	ds_read_b128 v[184:187], v183 offset:2048
	ds_read_b128 v[188:191], v183 offset:3072
	s_add_u32 s54, s74, 0x1000
	s_addc_u32 s55, s75, 0
	s_mov_b32 m0, s80
	v_lshl_add_u64 v[242:243], s[54:55], 0, v[144:145]
	ds_read_b128 v[192:195], v182 offset:32768
	ds_read_b128 v[196:199], v182 offset:33792
	ds_read_b128 v[200:203], v182 offset:34816
	ds_read_b128 v[208:211], v182 offset:35840
	ds_read_b128 v[214:217], v182 offset:36864
	ds_read_b128 v[230:233], v182 offset:37888
	ds_read_b128 v[234:237], v182 offset:38912
	ds_read_b128 v[238:241], v182 offset:39936
	global_load_lds_dwordx4 v[242:243], off
	v_lshl_add_u64 v[242:243], s[54:55], 0, v[148:149]
	s_mov_b32 m0, s81
	s_nop 0
	global_load_lds_dwordx4 v[242:243], off
	s_waitcnt vmcnt(8)
	s_waitcnt lgkmcnt(0)
	s_barrier
	s_setprio 1
	s_waitcnt lgkmcnt(0)
	v_mfma_f32_16x16x32_bf16 v[136:139], v[120:123], v[192:195], v[136:139]
	v_mfma_f32_16x16x32_bf16 v[128:131], v[140:143], v[192:195], v[128:131]
	v_mfma_f32_16x16x32_bf16 v[104:107], v[140:143], v[200:203], v[104:107]
	v_mfma_f32_16x16x32_bf16 v[112:115], v[120:123], v[200:203], v[112:115]
	v_mfma_f32_16x16x32_bf16 v[92:95], v[120:123], v[214:217], v[92:95]
	v_mfma_f32_16x16x32_bf16 v[88:91], v[140:143], v[214:217], v[88:91]
	v_mfma_f32_16x16x32_bf16 v[72:75], v[140:143], v[234:237], v[72:75]
	v_mfma_f32_16x16x32_bf16 v[76:79], v[120:123], v[234:237], v[76:79]
	v_mfma_f32_16x16x32_bf16 v[136:139], v[132:135], v[196:199], v[136:139]
	v_mfma_f32_16x16x32_bf16 v[128:131], v[168:171], v[196:199], v[128:131]
	v_mfma_f32_16x16x32_bf16 v[104:107], v[168:171], v[208:211], v[104:107]
	v_mfma_f32_16x16x32_bf16 v[112:115], v[132:135], v[208:211], v[112:115]
	v_mfma_f32_16x16x32_bf16 v[92:95], v[132:135], v[230:233], v[92:95]
	v_mfma_f32_16x16x32_bf16 v[88:91], v[168:171], v[230:233], v[88:91]
	v_mfma_f32_16x16x32_bf16 v[72:75], v[168:171], v[238:241], v[72:75]
	v_mfma_f32_16x16x32_bf16 v[76:79], v[132:135], v[238:241], v[76:79]
	s_setprio 0
	s_setprio 1
	v_mfma_f32_16x16x32_bf16 v[124:127], v[172:175], v[192:195], v[124:127]
	v_mfma_f32_16x16x32_bf16 v[116:119], v[184:187], v[192:195], v[116:119]
	v_mfma_f32_16x16x32_bf16 v[96:99], v[184:187], v[200:203], v[96:99]
	v_mfma_f32_16x16x32_bf16 v[100:103], v[172:175], v[200:203], v[100:103]
	v_mfma_f32_16x16x32_bf16 v[84:87], v[172:175], v[214:217], v[84:87]
	v_mfma_f32_16x16x32_bf16 v[80:83], v[184:187], v[214:217], v[80:83]
	v_mfma_f32_16x16x32_bf16 v[64:67], v[184:187], v[234:237], v[64:67]
	v_mfma_f32_16x16x32_bf16 v[68:71], v[172:175], v[234:237], v[68:71]
	v_mfma_f32_16x16x32_bf16 v[124:127], v[176:179], v[196:199], v[124:127]
	v_mfma_f32_16x16x32_bf16 v[116:119], v[188:191], v[196:199], v[116:119]
	v_mfma_f32_16x16x32_bf16 v[96:99], v[188:191], v[208:211], v[96:99]
	v_mfma_f32_16x16x32_bf16 v[100:103], v[176:179], v[208:211], v[100:103]
	v_mfma_f32_16x16x32_bf16 v[84:87], v[176:179], v[230:233], v[84:87]
	v_mfma_f32_16x16x32_bf16 v[80:83], v[188:191], v[230:233], v[80:83]
	v_mfma_f32_16x16x32_bf16 v[64:67], v[188:191], v[238:241], v[64:67]
	v_mfma_f32_16x16x32_bf16 v[68:71], v[176:179], v[238:241], v[68:71]
	s_setprio 0
	s_barrier
; #define PG8_STAGE(bufoff, gbase, voff) do { _Pragma("unroll") for (int _i = 0; _i < 2; ++_i) \
;         __builtin_amdgcn_global_load_lds((const unsigned*)((const char*)(gbase) + (voff)[_i]), (LAS unsigned*)(lds + (bufoff) + ldsw + _i * 8192), 16, 0, 0); } while (0)
; #define PG8_LDA(dst, b, h) do { _Pragma("unroll") for (int m = 0; m < 4; ++m) _Pragma("unroll") for (int k = 0; k < 2; ++k) dst[m][k] = *(const LAS bf16x8*)(lds + PG8_SA(b, h) + aoff + m * 2048 + k * 1024); } while (0)
; #define PG8_MMA(ai, bj, At, Bt) do { __builtin_amdgcn_s_setprio(1); _Pragma("unroll") for (int m = 0; m < 4; ++m) _Pragma("unroll") for (int n = 0; n < 2; ++n) _Pragma("unroll") for (int k = 0; k < 2; ++k) \
;         acc[ai][bj][m][n] = __builtin_amdgcn_mfma_f32_16x16x32_bf16(Bt[n][k], At[m][k], acc[ai][bj][m][n], 0, 0, 0); __builtin_amdgcn_s_setprio(0); } while (0)
; #define PG8_WAIT_V(n) asm volatile("s_waitcnt vmcnt(" #n ")" ::: "memory")
; #define PG8_WAIT_L(n) asm volatile("s_waitcnt lgkmcnt(" #n ")" ::: "memory")
; #define PG8_BAR __builtin_amdgcn_s_barrier()
; #define PG8_SCHED __builtin_amdgcn_sched_barrier(0)
;     ...
;         for (int t = 0; t < nt; t += 2) {
;     ...
;             PG8_LDA(At, 1, 1); PG8_STAGE(PG8_SB(1, 0), b3, voffB); PG8_STAGE(PG8_SB(1, 1), b3 + hB, voffB); PG8_STAGE(PG8_SA(1, 0), a3, voffA);
;             PG8_WAIT_V(8); PG8_WAIT_L(0); PG8_BAR; PG8_MMA(1, 0, At, B0); PG8_MMA(1, 1, At, B1); PG8_BAR; PG8_SCHED;
	s_add_i32 s29, s29, s77
	v_lshl_add_u64 v[204:205], v[204:205], 0, s[38:39]
	s_mov_b32 m0, s29
	ds_read_b128 v[192:195], v182 offset:49152
	ds_read_b128 v[196:199], v182 offset:50176
	ds_read_b128 v[200:203], v182 offset:51200
	ds_read_b128 v[208:211], v182 offset:52224
	ds_read_b128 v[214:217], v182 offset:53248
	ds_read_b128 v[230:233], v182 offset:54272
	ds_read_b128 v[234:237], v182 offset:55296
	ds_read_b128 v[238:241], v182 offset:56320
	global_load_lds_dwordx4 v[204:205], off
	s_add_i32 m0, s29, 0x2000
	s_add_u32 s54, s72, 0x40080
	v_lshl_add_u64 v[204:205], v[206:207], 0, s[38:39]
	s_addc_u32 s55, s73, 0
	s_add_i32 s29, s36, s77
	global_load_lds_dwordx4 v[204:205], off
	v_lshl_add_u64 v[204:205], s[54:55], 0, v[146:147]
	s_mov_b32 m0, s29
	s_nop 0
	global_load_lds_dwordx4 v[204:205], off
	v_lshl_add_u64 v[204:205], s[54:55], 0, v[150:151]
	s_add_i32 m0, s29, 0x2000
	s_nop 0
	global_load_lds_dwordx4 v[204:205], off
	v_lshl_add_u64 v[204:205], s[52:53], 0, v[144:145]
	s_mov_b32 m0, s89
	s_nop 0
	global_load_lds_dwordx4 v[204:205], off
	v_lshl_add_u64 v[204:205], s[52:53], 0, v[148:149]
	s_mov_b32 m0, s90
	s_nop 0
	global_load_lds_dwordx4 v[204:205], off
	s_waitcnt vmcnt(8)
	s_waitcnt lgkmcnt(0)
	s_barrier
	s_setprio 1
	s_waitcnt lgkmcnt(0)
	v_mfma_f32_16x16x32_bf16 v[60:63], v[120:123], v[192:195], v[60:63]
	v_mfma_f32_16x16x32_bf16 v[56:59], v[140:143], v[192:195], v[56:59]
	v_mfma_f32_16x16x32_bf16 v[40:43], v[140:143], v[200:203], v[40:43]
	v_mfma_f32_16x16x32_bf16 v[44:47], v[120:123], v[200:203], v[44:47]
	v_mfma_f32_16x16x32_bf16 v[28:31], v[120:123], v[214:217], v[28:31]
	v_mfma_f32_16x16x32_bf16 v[24:27], v[140:143], v[214:217], v[24:27]
	v_mfma_f32_16x16x32_bf16 v[8:11], v[140:143], v[234:237], v[8:11]
	v_mfma_f32_16x16x32_bf16 v[12:15], v[120:123], v[234:237], v[12:15]
	v_mfma_f32_16x16x32_bf16 v[60:63], v[132:135], v[196:199], v[60:63]
	v_mfma_f32_16x16x32_bf16 v[56:59], v[168:171], v[196:199], v[56:59]
	v_mfma_f32_16x16x32_bf16 v[40:43], v[168:171], v[208:211], v[40:43]
	v_mfma_f32_16x16x32_bf16 v[44:47], v[132:135], v[208:211], v[44:47]
	v_mfma_f32_16x16x32_bf16 v[28:31], v[132:135], v[230:233], v[28:31]
	v_mfma_f32_16x16x32_bf16 v[24:27], v[168:171], v[230:233], v[24:27]
	v_mfma_f32_16x16x32_bf16 v[8:11], v[168:171], v[238:241], v[8:11]
	v_mfma_f32_16x16x32_bf16 v[12:15], v[132:135], v[238:241], v[12:15]
	s_setprio 0
	s_setprio 1
	v_mfma_f32_16x16x32_bf16 v[52:55], v[172:175], v[192:195], v[52:55]
	v_mfma_f32_16x16x32_bf16 v[48:51], v[184:187], v[192:195], v[48:51]
	v_mfma_f32_16x16x32_bf16 v[32:35], v[184:187], v[200:203], v[32:35]
	v_mfma_f32_16x16x32_bf16 v[36:39], v[172:175], v[200:203], v[36:39]
	v_mfma_f32_16x16x32_bf16 v[20:23], v[172:175], v[214:217], v[20:23]
	v_mfma_f32_16x16x32_bf16 v[16:19], v[184:187], v[214:217], v[16:19]
	v_mfma_f32_16x16x32_bf16 v[0:3], v[184:187], v[234:237], v[0:3]
	v_mfma_f32_16x16x32_bf16 v[4:7], v[172:175], v[234:237], v[4:7]
	v_mfma_f32_16x16x32_bf16 v[52:55], v[176:179], v[196:199], v[52:55]
	v_mfma_f32_16x16x32_bf16 v[48:51], v[188:191], v[196:199], v[48:51]
	v_mfma_f32_16x16x32_bf16 v[32:35], v[188:191], v[208:211], v[32:35]
	v_mfma_f32_16x16x32_bf16 v[36:39], v[176:179], v[208:211], v[36:39]
	v_mfma_f32_16x16x32_bf16 v[20:23], v[176:179], v[230:233], v[20:23]
	v_mfma_f32_16x16x32_bf16 v[16:19], v[188:191], v[230:233], v[16:19]
	v_mfma_f32_16x16x32_bf16 v[0:3], v[188:191], v[238:241], v[0:3]
	v_mfma_f32_16x16x32_bf16 v[4:7], v[176:179], v[238:241], v[4:7]
	s_setprio 0
	s_barrier
	s_add_i32 s27, s27, 2
	s_add_u32 s9, s9, 0x100
	s_addc_u32 s17, s17, 0
	s_add_u32 s44, s44, 0x800000
	s_addc_u32 s45, s45, 0
	s_cmp_gt_u32 s27, 13
	s_cbranch_scc0 .LBB0_155
	s_and_b64 vcc, exec, s[14:15]
	s_cbranch_vccz .LBB0_158
	s_barrier

; #define PG8_STAGE(bufoff, gbase, voff) do { _Pragma("unroll") for (int _i = 0; _i < 2; ++_i) \
;         __builtin_amdgcn_global_load_lds((const unsigned*)((const char*)(gbase) + (voff)[_i]), (LAS unsigned*)(lds + (bufoff) + ldsw + _i * 8192), 16, 0, 0); } while (0)
; #define PG8_LDA(dst, b, h) do { _Pragma("unroll") for (int m = 0; m < 4; ++m) _Pragma("unroll") for (int k = 0; k < 2; ++k) dst[m][k] = *(const LAS bf16x8*)(lds + PG8_SA(b, h) + aoff + m * 2048 + k * 1024); } while (0)
; #define PG8_LDB(dst, b, h) do { _Pragma("unroll") for (int n = 0; n < 2; ++n) _Pragma("unroll") for (int k = 0; k < 2; ++k) dst[n][k] = *(const LAS bf16x8*)(lds + PG8_SB(b, h) + boff + n * 2048 + k * 1024); } while (0)
; #define PG8_MMA(ai, bj, At, Bt) do { __builtin_amdgcn_s_setprio(1); _Pragma("unroll") for (int m = 0; m < 4; ++m) _Pragma("unroll") for (int n = 0; n < 2; ++n) _Pragma("unroll") for (int k = 0; k < 2; ++k) \
;         acc[ai][bj][m][n] = __builtin_amdgcn_mfma_f32_16x16x32_bf16(Bt[n][k], At[m][k], acc[ai][bj][m][n], 0, 0, 0); __builtin_amdgcn_s_setprio(0); } while (0)
; #define PG8_WAIT_V(n) asm volatile("s_waitcnt vmcnt(" #n ")" ::: "memory")
; #define PG8_WAIT_L(n) asm volatile("s_waitcnt lgkmcnt(" #n ")" ::: "memory")
; #define PG8_BAR __builtin_amdgcn_s_barrier()
; #define PG8_SCHED __builtin_amdgcn_sched_barrier(0)
;     ...
;             PG8_LDB(B0, 0, 0); PG8_LDB(B1, 0, 1); PG8_SCHED; PG8_LDA(At, 0, 0); PG8_STAGE(PG8_SA(1, 1), a1 + hA, voffA);
;             PG8_WAIT_V(8); PG8_WAIT_L(0); PG8_BAR; PG8_MMA(0, 0, At, B0); PG8_MMA(0, 1, At, B1); PG8_BAR; PG8_SCHED;
;             PG8_LDA(At, 0, 1); PG8_STAGE(PG8_SB(0, 0), b2, voffB); PG8_STAGE(PG8_SB(0, 1), b2 + hB, voffB); PG8_STAGE(PG8_SA(0, 0), a2, voffA);
;             PG8_WAIT_V(8); PG8_WAIT_L(0); PG8_BAR; PG8_MMA(1, 0, At, B0); PG8_MMA(1, 1, At, B1); PG8_BAR; PG8_SCHED;
.LBB0_191:
	s_add_u32 s72, s44, s52
	s_addc_u32 s73, s45, s53
	s_add_u32 s76, s72, 0x100
	s_addc_u32 s77, s73, 0
	s_add_u32 s74, s80, s52
	s_addc_u32 s75, s81, s53
	s_add_u32 s72, s72, 0x180
	s_addc_u32 s73, s73, 0
	s_add_i32 s83, 0, 0x10000
	s_add_i32 s89, 0, 0x14000
	v_add_u32_e32 v146, s83, v150
	ds_read_b128 v[100:103], v146
	ds_read_b128 v[168:171], v146 offset:1024
	ds_read_b128 v[172:175], v146 offset:2048
	ds_read_b128 v[176:179], v146 offset:3072
	v_add_u32_e32 v146, s89, v150
	ds_read_b128 v[180:183], v146
	ds_read_b128 v[184:187], v146 offset:1024
	ds_read_b128 v[188:191], v146 offset:2048
	ds_read_b128 v[192:195], v146 offset:3072
	s_cmpk_eq_i32 s52, 0x700
	s_cselect_b32 s73, s79, s73
	s_cselect_b32 s72, s78, s72
	s_cselect_b32 s75, s17, s75
	s_cselect_b32 s74, s55, s74
	s_cselect_b32 s77, s27, s77
	s_cselect_b32 s76, s54, s76
	v_lshl_add_u64 v[146:147], v[96:97], 0, s[52:53]
	s_add_i32 m0, s6, 0xc000
	ds_read_b128 v[196:199], v154
	ds_read_b128 v[200:203], v154 offset:1024
	ds_read_b128 v[208:211], v154 offset:2048
	ds_read_b128 v[214:217], v154 offset:3072
	ds_read_b128 v[230:233], v154 offset:4096
	ds_read_b128 v[234:237], v154 offset:5120
	ds_read_b128 v[238:241], v154 offset:6144
	ds_read_b128 v[242:245], v154 offset:7168
	global_load_lds_dwordx4 v[146:147], off
	v_lshl_add_u64 v[146:147], v[98:99], 0, s[52:53]
	s_add_i32 m0, s6, 0xe000
	s_nop 0
	global_load_lds_dwordx4 v[146:147], off
	s_waitcnt vmcnt(8)
	s_waitcnt lgkmcnt(0)
	s_barrier
	s_setprio 1
	s_waitcnt lgkmcnt(0)
	v_mfma_f32_16x16x32_bf16 v[132:135], v[100:103], v[196:199], v[132:135]
	v_mfma_f32_16x16x32_bf16 v[128:131], v[172:175], v[196:199], v[128:131]
	v_mfma_f32_16x16x32_bf16 v[120:123], v[172:175], v[208:211], v[120:123]
	v_mfma_f32_16x16x32_bf16 v[124:127], v[100:103], v[208:211], v[124:127]
	v_mfma_f32_16x16x32_bf16 v[116:119], v[100:103], v[230:233], v[116:119]
	v_mfma_f32_16x16x32_bf16 v[112:115], v[172:175], v[230:233], v[112:115]
	v_mfma_f32_16x16x32_bf16 v[104:107], v[172:175], v[238:241], v[104:107]
	v_mfma_f32_16x16x32_bf16 v[108:111], v[100:103], v[238:241], v[108:111]
	v_mfma_f32_16x16x32_bf16 v[132:135], v[168:171], v[200:203], v[132:135]
	v_mfma_f32_16x16x32_bf16 v[128:131], v[176:179], v[200:203], v[128:131]
	v_mfma_f32_16x16x32_bf16 v[120:123], v[176:179], v[214:217], v[120:123]
	v_mfma_f32_16x16x32_bf16 v[124:127], v[168:171], v[214:217], v[124:127]
	v_mfma_f32_16x16x32_bf16 v[116:119], v[168:171], v[234:237], v[116:119]
	v_mfma_f32_16x16x32_bf16 v[112:115], v[176:179], v[234:237], v[112:115]
	v_mfma_f32_16x16x32_bf16 v[104:107], v[176:179], v[242:245], v[104:107]
	v_mfma_f32_16x16x32_bf16 v[108:111], v[168:171], v[242:245], v[108:111]
	s_setprio 0
	s_setprio 1
	v_mfma_f32_16x16x32_bf16 v[68:71], v[180:183], v[196:199], v[68:71]
	v_mfma_f32_16x16x32_bf16 v[56:59], v[188:191], v[196:199], v[56:59]
	v_mfma_f32_16x16x32_bf16 v[48:51], v[188:191], v[208:211], v[48:51]
	v_mfma_f32_16x16x32_bf16 v[52:55], v[180:183], v[208:211], v[52:55]
	v_mfma_f32_16x16x32_bf16 v[44:47], v[180:183], v[230:233], v[44:47]
	v_mfma_f32_16x16x32_bf16 v[40:43], v[188:191], v[230:233], v[40:43]
	v_mfma_f32_16x16x32_bf16 v[32:35], v[188:191], v[238:241], v[32:35]
	v_mfma_f32_16x16x32_bf16 v[36:39], v[180:183], v[238:241], v[36:39]
	v_mfma_f32_16x16x32_bf16 v[68:71], v[184:187], v[200:203], v[68:71]
	v_mfma_f32_16x16x32_bf16 v[56:59], v[192:195], v[200:203], v[56:59]
	v_mfma_f32_16x16x32_bf16 v[48:51], v[192:195], v[214:217], v[48:51]
	v_mfma_f32_16x16x32_bf16 v[52:55], v[184:187], v[214:217], v[52:55]
	v_mfma_f32_16x16x32_bf16 v[44:47], v[184:187], v[234:237], v[44:47]
	v_mfma_f32_16x16x32_bf16 v[40:43], v[192:195], v[234:237], v[40:43]
	v_mfma_f32_16x16x32_bf16 v[32:35], v[192:195], v[242:245], v[32:35]
	v_mfma_f32_16x16x32_bf16 v[36:39], v[184:187], v[242:245], v[36:39]
	s_setprio 0
	s_barrier
	s_add_i32 s83, s83, s5
	v_lshl_add_u64 v[146:147], s[74:75], 0, v[156:157]
	s_mov_b32 m0, s83
	ds_read_b128 v[196:199], v154 offset:16384
	ds_read_b128 v[200:203], v154 offset:17408
	ds_read_b128 v[208:211], v154 offset:18432
	ds_read_b128 v[214:217], v154 offset:19456
	ds_read_b128 v[230:233], v154 offset:20480
	ds_read_b128 v[234:237], v154 offset:21504
	ds_read_b128 v[238:241], v154 offset:22528
	ds_read_b128 v[242:245], v154 offset:23552
	global_load_lds_dwordx4 v[146:147], off
	s_add_i32 m0, s83, 0x2000
	s_add_u32 s90, s74, 0x40000
	v_lshl_add_u64 v[204:205], s[74:75], 0, v[140:141]
	s_addc_u32 s91, s75, 0
	s_add_i32 s83, s89, s5
	global_load_lds_dwordx4 v[204:205], off
	v_lshl_add_u64 v[206:207], s[90:91], 0, v[156:157]
	s_mov_b32 m0, s83
	s_nop 0
	global_load_lds_dwordx4 v[206:207], off
	v_lshl_add_u64 v[206:207], s[90:91], 0, v[140:141]
	s_add_i32 m0, s83, 0x2000
	s_nop 0
	global_load_lds_dwordx4 v[206:207], off
	v_lshl_add_u64 v[206:207], s[76:77], 0, v[136:137]
	s_mov_b32 m0, s6
	s_nop 0
	global_load_lds_dwordx4 v[206:207], off
	v_lshl_add_u64 v[206:207], s[76:77], 0, v[138:139]
	s_mov_b32 m0, s7
	s_nop 0
	global_load_lds_dwordx4 v[206:207], off
	s_waitcnt vmcnt(8)
	s_waitcnt lgkmcnt(0)
	s_barrier
; #define PG8_STAGE(bufoff, gbase, voff) do { _Pragma("unroll") for (int _i = 0; _i < 2; ++_i) \
;         __builtin_amdgcn_global_load_lds((const unsigned*)((const char*)(gbase) + (voff)[_i]), (LAS unsigned*)(lds + (bufoff) + ldsw + _i * 8192), 16, 0, 0); } while (0)
; #define PG8_LDA(dst, b, h) do { _Pragma("unroll") for (int m = 0; m < 4; ++m) _Pragma("unroll") for (int k = 0; k < 2; ++k) dst[m][k] = *(const LAS bf16x8*)(lds + PG8_SA(b, h) + aoff + m * 2048 + k * 1024); } while (0)
; #define PG8_LDB(dst, b, h) do { _Pragma("unroll") for (int n = 0; n < 2; ++n) _Pragma("unroll") for (int k = 0; k < 2; ++k) dst[n][k] = *(const LAS bf16x8*)(lds + PG8_SB(b, h) + boff + n * 2048 + k * 1024); } while (0)
; #define PG8_MMA(ai, bj, At, Bt) do { __builtin_amdgcn_s_setprio(1); _Pragma("unroll") for (int m = 0; m < 4; ++m) _Pragma("unroll") for (int n = 0; n < 2; ++n) _Pragma("unroll") for (int k = 0; k < 2; ++k) \
;         acc[ai][bj][m][n] = __builtin_amdgcn_mfma_f32_16x16x32_bf16(Bt[n][k], At[m][k], acc[ai][bj][m][n], 0, 0, 0); __builtin_amdgcn_s_setprio(0); } while (0)
; #define PG8_WAIT_V(n) asm volatile("s_waitcnt vmcnt(" #n ")" ::: "memory")
; #define PG8_WAIT_L(n) asm volatile("s_waitcnt lgkmcnt(" #n ")" ::: "memory")
; #define PG8_BAR __builtin_amdgcn_s_barrier()
; #define PG8_SCHED __builtin_amdgcn_sched_barrier(0)
;     ...
;             PG8_WAIT_V(8); PG8_WAIT_L(0); PG8_BAR; PG8_MMA(1, 0, At, B0); PG8_MMA(1, 1, At, B1); PG8_BAR; PG8_SCHED;
;             PG8_LDB(B0, 1, 0); PG8_LDB(B1, 1, 1); PG8_SCHED; PG8_LDA(At, 1, 0); PG8_STAGE(PG8_SA(0, 1), a2 + hA, voffA);
;             PG8_WAIT_V(8); PG8_WAIT_L(0); PG8_BAR; PG8_MMA(0, 0, At, B0); PG8_MMA(0, 1, At, B1); PG8_BAR; PG8_SCHED;
	s_setprio 1
	s_waitcnt lgkmcnt(0)
	v_mfma_f32_16x16x32_bf16 v[92:95], v[100:103], v[196:199], v[92:95]
	v_mfma_f32_16x16x32_bf16 v[88:91], v[172:175], v[196:199], v[88:91]
	v_mfma_f32_16x16x32_bf16 v[80:83], v[172:175], v[208:211], v[80:83]
	v_mfma_f32_16x16x32_bf16 v[84:87], v[100:103], v[208:211], v[84:87]
	v_mfma_f32_16x16x32_bf16 v[76:79], v[100:103], v[230:233], v[76:79]
	v_mfma_f32_16x16x32_bf16 v[72:75], v[172:175], v[230:233], v[72:75]
	v_mfma_f32_16x16x32_bf16 v[60:63], v[172:175], v[238:241], v[60:63]
	v_mfma_f32_16x16x32_bf16 v[64:67], v[100:103], v[238:241], v[64:67]
	v_mfma_f32_16x16x32_bf16 v[92:95], v[168:171], v[200:203], v[92:95]
	v_mfma_f32_16x16x32_bf16 v[88:91], v[176:179], v[200:203], v[88:91]
	v_mfma_f32_16x16x32_bf16 v[80:83], v[176:179], v[214:217], v[80:83]
	v_mfma_f32_16x16x32_bf16 v[84:87], v[168:171], v[214:217], v[84:87]
	v_mfma_f32_16x16x32_bf16 v[76:79], v[168:171], v[234:237], v[76:79]
	v_mfma_f32_16x16x32_bf16 v[72:75], v[176:179], v[234:237], v[72:75]
	v_mfma_f32_16x16x32_bf16 v[60:63], v[176:179], v[242:245], v[60:63]
	v_mfma_f32_16x16x32_bf16 v[64:67], v[168:171], v[242:245], v[64:67]
	s_setprio 0
	s_setprio 1
	v_mfma_f32_16x16x32_bf16 v[28:31], v[180:183], v[196:199], v[28:31]
	v_mfma_f32_16x16x32_bf16 v[24:27], v[188:191], v[196:199], v[24:27]
	v_mfma_f32_16x16x32_bf16 v[16:19], v[188:191], v[208:211], v[16:19]
	v_mfma_f32_16x16x32_bf16 v[20:23], v[180:183], v[208:211], v[20:23]
	v_mfma_f32_16x16x32_bf16 v[12:15], v[180:183], v[230:233], v[12:15]
	v_mfma_f32_16x16x32_bf16 v[8:11], v[188:191], v[230:233], v[8:11]
	v_mfma_f32_16x16x32_bf16 v[0:3], v[188:191], v[238:241], v[0:3]
	v_mfma_f32_16x16x32_bf16 v[4:7], v[180:183], v[238:241], v[4:7]
	v_mfma_f32_16x16x32_bf16 v[28:31], v[184:187], v[200:203], v[28:31]
	v_mfma_f32_16x16x32_bf16 v[24:27], v[192:195], v[200:203], v[24:27]
	v_mfma_f32_16x16x32_bf16 v[16:19], v[192:195], v[214:217], v[16:19]
	v_mfma_f32_16x16x32_bf16 v[20:23], v[184:187], v[214:217], v[20:23]
	v_mfma_f32_16x16x32_bf16 v[12:15], v[184:187], v[234:237], v[12:15]
	v_mfma_f32_16x16x32_bf16 v[8:11], v[192:195], v[234:237], v[8:11]
	v_mfma_f32_16x16x32_bf16 v[0:3], v[192:195], v[242:245], v[0:3]
	v_mfma_f32_16x16x32_bf16 v[4:7], v[184:187], v[242:245], v[4:7]
	s_setprio 0
	s_barrier
	s_add_i32 s83, 0, 0x18000
	v_add_u32_e32 v155, s83, v150
	s_add_i32 s89, 0, 0x1c000
	ds_read_b128 v[100:103], v155
	ds_read_b128 v[168:171], v155 offset:1024
	ds_read_b128 v[172:175], v155 offset:2048
	ds_read_b128 v[176:179], v155 offset:3072
	v_add_u32_e32 v155, s89, v150
	ds_read_b128 v[180:183], v155
	ds_read_b128 v[184:187], v155 offset:1024
	ds_read_b128 v[188:191], v155 offset:2048
	ds_read_b128 v[192:195], v155 offset:3072
	s_add_u32 s76, s76, 0x40000
	s_addc_u32 s77, s77, 0
	s_mov_b32 m0, s8
	v_lshl_add_u64 v[206:207], s[76:77], 0, v[136:137]
	ds_read_b128 v[196:199], v154 offset:32768
	ds_read_b128 v[200:203], v154 offset:33792
	ds_read_b128 v[208:211], v154 offset:34816
	ds_read_b128 v[214:217], v154 offset:35840
	ds_read_b128 v[230:233], v154 offset:36864
	ds_read_b128 v[234:237], v154 offset:37888
	ds_read_b128 v[238:241], v154 offset:38912
	ds_read_b128 v[242:245], v154 offset:39936
	global_load_lds_dwordx4 v[206:207], off
	v_lshl_add_u64 v[206:207], s[76:77], 0, v[138:139]
	s_mov_b32 m0, s9
	s_nop 0
	global_load_lds_dwordx4 v[206:207], off
	s_waitcnt vmcnt(8)
	s_waitcnt lgkmcnt(0)
	s_barrier
	s_setprio 1
	s_waitcnt lgkmcnt(0)
	v_mfma_f32_16x16x32_bf16 v[132:135], v[100:103], v[196:199], v[132:135]
	v_mfma_f32_16x16x32_bf16 v[128:131], v[172:175], v[196:199], v[128:131]
	v_mfma_f32_16x16x32_bf16 v[120:123], v[172:175], v[208:211], v[120:123]
	v_mfma_f32_16x16x32_bf16 v[124:127], v[100:103], v[208:211], v[124:127]
	v_mfma_f32_16x16x32_bf16 v[116:119], v[100:103], v[230:233], v[116:119]
	v_mfma_f32_16x16x32_bf16 v[112:115], v[172:175], v[230:233], v[112:115]
	v_mfma_f32_16x16x32_bf16 v[104:107], v[172:175], v[238:241], v[104:107]
	v_mfma_f32_16x16x32_bf16 v[108:111], v[100:103], v[238:241], v[108:111]
	v_mfma_f32_16x16x32_bf16 v[132:135], v[168:171], v[200:203], v[132:135]
	v_mfma_f32_16x16x32_bf16 v[128:131], v[176:179], v[200:203], v[128:131]
	v_mfma_f32_16x16x32_bf16 v[120:123], v[176:179], v[214:217], v[120:123]
	v_mfma_f32_16x16x32_bf16 v[124:127], v[168:171], v[214:217], v[124:127]
	v_mfma_f32_16x16x32_bf16 v[116:119], v[168:171], v[234:237], v[116:119]
	v_mfma_f32_16x16x32_bf16 v[112:115], v[176:179], v[234:237], v[112:115]
	v_mfma_f32_16x16x32_bf16 v[104:107], v[176:179], v[242:245], v[104:107]
	v_mfma_f32_16x16x32_bf16 v[108:111], v[168:171], v[242:245], v[108:111]
	s_setprio 0
	s_setprio 1
	v_mfma_f32_16x16x32_bf16 v[68:71], v[180:183], v[196:199], v[68:71]
	v_mfma_f32_16x16x32_bf16 v[56:59], v[188:191], v[196:199], v[56:59]
	v_mfma_f32_16x16x32_bf16 v[48:51], v[188:191], v[208:211], v[48:51]
	v_mfma_f32_16x16x32_bf16 v[52:55], v[180:183], v[208:211], v[52:55]
	v_mfma_f32_16x16x32_bf16 v[44:47], v[180:183], v[230:233], v[44:47]
	v_mfma_f32_16x16x32_bf16 v[40:43], v[188:191], v[230:233], v[40:43]
	v_mfma_f32_16x16x32_bf16 v[32:35], v[188:191], v[238:241], v[32:35]
	v_mfma_f32_16x16x32_bf16 v[36:39], v[180:183], v[238:241], v[36:39]
	v_mfma_f32_16x16x32_bf16 v[68:71], v[184:187], v[200:203], v[68:71]
	v_mfma_f32_16x16x32_bf16 v[56:59], v[192:195], v[200:203], v[56:59]
	v_mfma_f32_16x16x32_bf16 v[48:51], v[192:195], v[214:217], v[48:51]
	v_mfma_f32_16x16x32_bf16 v[52:55], v[184:187], v[214:217], v[52:55]
	v_mfma_f32_16x16x32_bf16 v[44:47], v[184:187], v[234:237], v[44:47]
	v_mfma_f32_16x16x32_bf16 v[40:43], v[192:195], v[234:237], v[40:43]
	v_mfma_f32_16x16x32_bf16 v[32:35], v[192:195], v[242:245], v[32:35]
	v_mfma_f32_16x16x32_bf16 v[36:39], v[184:187], v[242:245], v[36:39]
	s_setprio 0
	s_barrier
; #define PG8_STAGE(bufoff, gbase, voff) do { _Pragma("unroll") for (int _i = 0; _i < 2; ++_i) \
;         __builtin_amdgcn_global_load_lds((const unsigned*)((const char*)(gbase) + (voff)[_i]), (LAS unsigned*)(lds + (bufoff) + ldsw + _i * 8192), 16, 0, 0); } while (0)
; #define PG8_LDA(dst, b, h) do { _Pragma("unroll") for (int m = 0; m < 4; ++m) _Pragma("unroll") for (int k = 0; k < 2; ++k) dst[m][k] = *(const LAS bf16x8*)(lds + PG8_SA(b, h) + aoff + m * 2048 + k * 1024); } while (0)
; #define PG8_MMA(ai, bj, At, Bt) do { __builtin_amdgcn_s_setprio(1); _Pragma("unroll") for (int m = 0; m < 4; ++m) _Pragma("unroll") for (int n = 0; n < 2; ++n) _Pragma("unroll") for (int k = 0; k < 2; ++k) \
;         acc[ai][bj][m][n] = __builtin_amdgcn_mfma_f32_16x16x32_bf16(Bt[n][k], At[m][k], acc[ai][bj][m][n], 0, 0, 0); __builtin_amdgcn_s_setprio(0); } while (0)
; #define PG8_WAIT_V(n) asm volatile("s_waitcnt vmcnt(" #n ")" ::: "memory")
; #define PG8_WAIT_L(n) asm volatile("s_waitcnt lgkmcnt(" #n ")" ::: "memory")
; #define PG8_BAR __builtin_amdgcn_s_barrier()
; #define PG8_SCHED __builtin_amdgcn_sched_barrier(0)
;     ...
;         for (int t = 0; t < nt; t += 2) {
;     ...
;             PG8_LDA(At, 1, 1); PG8_STAGE(PG8_SB(1, 0), b3, voffB); PG8_STAGE(PG8_SB(1, 1), b3 + hB, voffB); PG8_STAGE(PG8_SA(1, 0), a3, voffA);
;             PG8_WAIT_V(8); PG8_WAIT_L(0); PG8_BAR; PG8_MMA(1, 0, At, B0); PG8_MMA(1, 1, At, B1); PG8_BAR; PG8_SCHED;
	s_add_i32 s76, s83, s5
	v_lshl_add_u64 v[146:147], v[146:147], 0, s[38:39]
	s_mov_b32 m0, s76
	ds_read_b128 v[196:199], v154 offset:49152
	ds_read_b128 v[200:203], v154 offset:50176
	ds_read_b128 v[208:211], v154 offset:51200
	ds_read_b128 v[214:217], v154 offset:52224
	ds_read_b128 v[230:233], v154 offset:53248
	ds_read_b128 v[234:237], v154 offset:54272
	ds_read_b128 v[238:241], v154 offset:55296
	ds_read_b128 v[242:245], v154 offset:56320
	global_load_lds_dwordx4 v[146:147], off
	s_add_i32 m0, s76, 0x2000
	s_add_u32 s74, s74, 0x40080
	v_lshl_add_u64 v[146:147], v[204:205], 0, s[38:39]
	s_addc_u32 s75, s75, 0
	s_add_i32 s76, s89, s5
	global_load_lds_dwordx4 v[146:147], off
	v_lshl_add_u64 v[146:147], s[74:75], 0, v[156:157]
	s_mov_b32 m0, s76
	s_nop 0
	global_load_lds_dwordx4 v[146:147], off
	v_lshl_add_u64 v[146:147], s[74:75], 0, v[140:141]
	s_add_i32 m0, s76, 0x2000
	s_nop 0
	global_load_lds_dwordx4 v[146:147], off
	v_lshl_add_u64 v[146:147], s[72:73], 0, v[136:137]
	s_mov_b32 m0, s42
	s_nop 0
	global_load_lds_dwordx4 v[146:147], off
	v_lshl_add_u64 v[146:147], s[72:73], 0, v[138:139]
	s_mov_b32 m0, s43
	s_nop 0
	global_load_lds_dwordx4 v[146:147], off
	s_waitcnt vmcnt(8)
	s_waitcnt lgkmcnt(0)
	s_barrier
	s_setprio 1
	s_waitcnt lgkmcnt(0)
	v_mfma_f32_16x16x32_bf16 v[92:95], v[100:103], v[196:199], v[92:95]
	v_mfma_f32_16x16x32_bf16 v[88:91], v[172:175], v[196:199], v[88:91]
	v_mfma_f32_16x16x32_bf16 v[80:83], v[172:175], v[208:211], v[80:83]
	v_mfma_f32_16x16x32_bf16 v[84:87], v[100:103], v[208:211], v[84:87]
	v_mfma_f32_16x16x32_bf16 v[76:79], v[100:103], v[230:233], v[76:79]
	v_mfma_f32_16x16x32_bf16 v[72:75], v[172:175], v[230:233], v[72:75]
	v_mfma_f32_16x16x32_bf16 v[60:63], v[172:175], v[238:241], v[60:63]
	v_mfma_f32_16x16x32_bf16 v[64:67], v[100:103], v[238:241], v[64:67]
	v_mfma_f32_16x16x32_bf16 v[92:95], v[168:171], v[200:203], v[92:95]
	v_mfma_f32_16x16x32_bf16 v[88:91], v[176:179], v[200:203], v[88:91]
	v_mfma_f32_16x16x32_bf16 v[80:83], v[176:179], v[214:217], v[80:83]
	v_mfma_f32_16x16x32_bf16 v[84:87], v[168:171], v[214:217], v[84:87]
	v_mfma_f32_16x16x32_bf16 v[76:79], v[168:171], v[234:237], v[76:79]
	v_mfma_f32_16x16x32_bf16 v[72:75], v[176:179], v[234:237], v[72:75]
	v_mfma_f32_16x16x32_bf16 v[60:63], v[176:179], v[242:245], v[60:63]
	v_mfma_f32_16x16x32_bf16 v[64:67], v[168:171], v[242:245], v[64:67]
	s_setprio 0
	s_setprio 1
	v_mfma_f32_16x16x32_bf16 v[28:31], v[180:183], v[196:199], v[28:31]
	v_mfma_f32_16x16x32_bf16 v[24:27], v[188:191], v[196:199], v[24:27]
	v_mfma_f32_16x16x32_bf16 v[16:19], v[188:191], v[208:211], v[16:19]
	v_mfma_f32_16x16x32_bf16 v[20:23], v[180:183], v[208:211], v[20:23]
	v_mfma_f32_16x16x32_bf16 v[12:15], v[180:183], v[230:233], v[12:15]
	v_mfma_f32_16x16x32_bf16 v[8:11], v[188:191], v[230:233], v[8:11]
	v_mfma_f32_16x16x32_bf16 v[0:3], v[188:191], v[238:241], v[0:3]
	v_mfma_f32_16x16x32_bf16 v[4:7], v[180:183], v[238:241], v[4:7]
	v_mfma_f32_16x16x32_bf16 v[28:31], v[184:187], v[200:203], v[28:31]
	v_mfma_f32_16x16x32_bf16 v[24:27], v[192:195], v[200:203], v[24:27]
	v_mfma_f32_16x16x32_bf16 v[16:19], v[192:195], v[214:217], v[16:19]
	v_mfma_f32_16x16x32_bf16 v[20:23], v[184:187], v[214:217], v[20:23]
	v_mfma_f32_16x16x32_bf16 v[12:15], v[184:187], v[234:237], v[12:15]
	v_mfma_f32_16x16x32_bf16 v[8:11], v[192:195], v[234:237], v[8:11]
	v_mfma_f32_16x16x32_bf16 v[0:3], v[192:195], v[242:245], v[0:3]
	v_mfma_f32_16x16x32_bf16 v[4:7], v[184:187], v[242:245], v[4:7]
	s_setprio 0
	s_barrier
	s_add_i32 s82, s82, 2
	s_add_u32 s52, s52, 0x100
	s_addc_u32 s53, s53, 0
	s_cmp_gt_u32 s82, 13
	s_cbranch_scc0 .LBB0_191
	s_and_b64 vcc, exec, s[14:15]
	s_cbranch_vccz .LBB0_194
	s_barrier

; #define PG8_STAGE(bufoff, gbase, voff) do { _Pragma("unroll") for (int _i = 0; _i < 2; ++_i) \
;         __builtin_amdgcn_global_load_lds((const unsigned*)((const char*)(gbase) + (voff)[_i]), (LAS unsigned*)(lds + (bufoff) + ldsw + _i * 8192), 16, 0, 0); } while (0)
; #define PG8_LDA(dst, b, h) do { _Pragma("unroll") for (int m = 0; m < 4; ++m) _Pragma("unroll") for (int k = 0; k < 2; ++k) dst[m][k] = *(const LAS bf16x8*)(lds + PG8_SA(b, h) + aoff + m * 2048 + k * 1024); } while (0)
; #define PG8_LDB(dst, b, h) do { _Pragma("unroll") for (int n = 0; n < 2; ++n) _Pragma("unroll") for (int k = 0; k < 2; ++k) dst[n][k] = *(const LAS bf16x8*)(lds + PG8_SB(b, h) + boff + n * 2048 + k * 1024); } while (0)
; #define PG8_MMA(ai, bj, At, Bt) do { __builtin_amdgcn_s_setprio(1); _Pragma("unroll") for (int m = 0; m < 4; ++m) _Pragma("unroll") for (int n = 0; n < 2; ++n) _Pragma("unroll") for (int k = 0; k < 2; ++k) \
;         acc[ai][bj][m][n] = __builtin_amdgcn_mfma_f32_16x16x32_bf16(Bt[n][k], At[m][k], acc[ai][bj][m][n], 0, 0, 0); __builtin_amdgcn_s_setprio(0); } while (0)
; #define PG8_WAIT_V(n) asm volatile("s_waitcnt vmcnt(" #n ")" ::: "memory")
; #define PG8_WAIT_L(n) asm volatile("s_waitcnt lgkmcnt(" #n ")" ::: "memory")
; #define PG8_BAR __builtin_amdgcn_s_barrier()
; #define PG8_SCHED __builtin_amdgcn_sched_barrier(0)
;     ...
;             PG8_LDB(B0, 0, 0); PG8_LDB(B1, 0, 1); PG8_SCHED; PG8_LDA(At, 0, 0); PG8_STAGE(PG8_SA(1, 1), a1 + hA, voffA);
;             PG8_WAIT_V(8); PG8_WAIT_L(0); PG8_BAR; PG8_MMA(0, 0, At, B0); PG8_MMA(0, 1, At, B1); PG8_BAR; PG8_SCHED;
;             PG8_LDA(At, 0, 1); PG8_STAGE(PG8_SB(0, 0), b2, voffB); PG8_STAGE(PG8_SB(0, 1), b2 + hB, voffB); PG8_STAGE(PG8_SA(0, 0), a2, voffA);
;             PG8_WAIT_V(8); PG8_WAIT_L(0); PG8_BAR; PG8_MMA(1, 0, At, B0); PG8_MMA(1, 1, At, B1); PG8_BAR; PG8_SCHED;
.LBB0_271:
	s_add_u32 s31, s52, s90
	s_addc_u32 s36, s53, s91
	s_add_u32 s45, s31, 0x100
	s_addc_u32 s54, s36, 0
	s_add_u32 s55, s8, s90
	s_addc_u32 s74, s9, s91
	s_add_u32 s31, s31, 0x180
	s_addc_u32 s36, s36, 0
	s_add_i32 s82, 0, 0x10000
	s_add_i32 s83, 0, 0x14000
	v_add_u32_e32 v144, s82, v231
	v_add_u32_e32 v156, s83, v231
	ds_read_b128 v[132:135], v144
	ds_read_b128 v[136:139], v144 offset:1024
	ds_read_b128 v[140:143], v144 offset:2048
	ds_read_b128 v[144:147], v144 offset:3072
	ds_read_b128 v[148:151], v156
	ds_read_b128 v[152:155], v156 offset:1024
	ds_read_b128 v[182:185], v156 offset:2048
	ds_read_b128 v[186:189], v156 offset:3072
	s_cmpk_eq_i32 s90, 0x700
	s_cselect_b32 s73, s7, s36
	s_cselect_b32 s72, s6, s31
	s_cselect_b32 s75, s4, s74
	s_cselect_b32 s74, s5, s55
	s_cselect_b32 s77, s1, s54
	s_cselect_b32 s76, s3, s45
	v_lshl_add_u64 v[206:207], v[128:129], 0, s[90:91]
	s_add_i32 m0, s80, 0xc000
	ds_read_b128 v[190:193], v233
	ds_read_b128 v[194:197], v233 offset:1024
	ds_read_b128 v[198:201], v233 offset:2048
	ds_read_b128 v[202:205], v233 offset:3072
	ds_read_b128 v[208:211], v233 offset:4096
	ds_read_b128 v[214:217], v233 offset:5120
	ds_read_b128 v[234:237], v233 offset:6144
	ds_read_b128 v[238:241], v233 offset:7168
	global_load_lds_dwordx4 v[206:207], off
	v_lshl_add_u64 v[206:207], v[130:131], 0, s[90:91]
	s_add_i32 m0, s80, 0xe000
	s_nop 0
	global_load_lds_dwordx4 v[206:207], off
	s_waitcnt vmcnt(8)
	s_waitcnt lgkmcnt(0)
	s_barrier
	s_setprio 1
	s_waitcnt lgkmcnt(0)
	v_mfma_f32_16x16x32_bf16 v[124:127], v[132:135], v[190:193], v[124:127]
	v_mfma_f32_16x16x32_bf16 v[120:123], v[140:143], v[190:193], v[120:123]
	v_mfma_f32_16x16x32_bf16 v[104:107], v[140:143], v[198:201], v[104:107]
	v_mfma_f32_16x16x32_bf16 v[108:111], v[132:135], v[198:201], v[108:111]
	v_mfma_f32_16x16x32_bf16 v[92:95], v[132:135], v[208:211], v[92:95]
	v_mfma_f32_16x16x32_bf16 v[88:91], v[140:143], v[208:211], v[88:91]
	v_mfma_f32_16x16x32_bf16 v[72:75], v[140:143], v[234:237], v[72:75]
	v_mfma_f32_16x16x32_bf16 v[76:79], v[132:135], v[234:237], v[76:79]
	v_mfma_f32_16x16x32_bf16 v[124:127], v[136:139], v[194:197], v[124:127]
	v_mfma_f32_16x16x32_bf16 v[120:123], v[144:147], v[194:197], v[120:123]
	v_mfma_f32_16x16x32_bf16 v[104:107], v[144:147], v[202:205], v[104:107]
	v_mfma_f32_16x16x32_bf16 v[108:111], v[136:139], v[202:205], v[108:111]
	v_mfma_f32_16x16x32_bf16 v[92:95], v[136:139], v[214:217], v[92:95]
	v_mfma_f32_16x16x32_bf16 v[88:91], v[144:147], v[214:217], v[88:91]
	v_mfma_f32_16x16x32_bf16 v[72:75], v[144:147], v[238:241], v[72:75]
	v_mfma_f32_16x16x32_bf16 v[76:79], v[136:139], v[238:241], v[76:79]
	s_setprio 0
	s_setprio 1
	v_mfma_f32_16x16x32_bf16 v[116:119], v[148:151], v[190:193], v[116:119]
	v_mfma_f32_16x16x32_bf16 v[112:115], v[182:185], v[190:193], v[112:115]
	v_mfma_f32_16x16x32_bf16 v[96:99], v[182:185], v[198:201], v[96:99]
	v_mfma_f32_16x16x32_bf16 v[100:103], v[148:151], v[198:201], v[100:103]
	v_mfma_f32_16x16x32_bf16 v[84:87], v[148:151], v[208:211], v[84:87]
	v_mfma_f32_16x16x32_bf16 v[80:83], v[182:185], v[208:211], v[80:83]
	v_mfma_f32_16x16x32_bf16 v[64:67], v[182:185], v[234:237], v[64:67]
	v_mfma_f32_16x16x32_bf16 v[68:71], v[148:151], v[234:237], v[68:71]
	v_mfma_f32_16x16x32_bf16 v[116:119], v[152:155], v[194:197], v[116:119]
	v_mfma_f32_16x16x32_bf16 v[112:115], v[186:189], v[194:197], v[112:115]
	v_mfma_f32_16x16x32_bf16 v[96:99], v[186:189], v[202:205], v[96:99]
	v_mfma_f32_16x16x32_bf16 v[100:103], v[152:155], v[202:205], v[100:103]
	v_mfma_f32_16x16x32_bf16 v[84:87], v[152:155], v[214:217], v[84:87]
	v_mfma_f32_16x16x32_bf16 v[80:83], v[186:189], v[214:217], v[80:83]
	v_mfma_f32_16x16x32_bf16 v[64:67], v[186:189], v[238:241], v[64:67]
	v_mfma_f32_16x16x32_bf16 v[68:71], v[152:155], v[238:241], v[68:71]
	s_setprio 0
	s_barrier
	s_add_i32 s31, s82, s79
	v_lshl_add_u64 v[206:207], s[74:75], 0, v[170:171]
	s_mov_b32 m0, s31
	ds_read_b128 v[190:193], v233 offset:16384
	ds_read_b128 v[194:197], v233 offset:17408
	ds_read_b128 v[198:201], v233 offset:18432
	ds_read_b128 v[202:205], v233 offset:19456
	ds_read_b128 v[208:211], v233 offset:20480
	ds_read_b128 v[214:217], v233 offset:21504
	ds_read_b128 v[234:237], v233 offset:22528
	ds_read_b128 v[238:241], v233 offset:23552
	global_load_lds_dwordx4 v[206:207], off
	s_add_i32 m0, s31, 0x2000
	s_add_u32 s54, s74, 0x40000
	v_lshl_add_u64 v[242:243], s[74:75], 0, v[174:175]
	s_addc_u32 s55, s75, 0
	s_add_i32 s31, s83, s79
	global_load_lds_dwordx4 v[242:243], off
	v_lshl_add_u64 v[244:245], s[54:55], 0, v[170:171]
	s_mov_b32 m0, s31
	s_nop 0
	global_load_lds_dwordx4 v[244:245], off
	v_lshl_add_u64 v[244:245], s[54:55], 0, v[174:175]
	s_add_i32 m0, s31, 0x2000
	s_nop 0
	global_load_lds_dwordx4 v[244:245], off
	v_lshl_add_u64 v[244:245], s[76:77], 0, v[168:169]
	s_mov_b32 m0, s80
	s_nop 0
	global_load_lds_dwordx4 v[244:245], off
	v_lshl_add_u64 v[244:245], s[76:77], 0, v[172:173]
	s_mov_b32 m0, s81
	s_nop 0
	global_load_lds_dwordx4 v[244:245], off
	s_waitcnt vmcnt(8)
	s_waitcnt lgkmcnt(0)
	s_barrier
; #define PG8_STAGE(bufoff, gbase, voff) do { _Pragma("unroll") for (int _i = 0; _i < 2; ++_i) \
;         __builtin_amdgcn_global_load_lds((const unsigned*)((const char*)(gbase) + (voff)[_i]), (LAS unsigned*)(lds + (bufoff) + ldsw + _i * 8192), 16, 0, 0); } while (0)
; #define PG8_LDA(dst, b, h) do { _Pragma("unroll") for (int m = 0; m < 4; ++m) _Pragma("unroll") for (int k = 0; k < 2; ++k) dst[m][k] = *(const LAS bf16x8*)(lds + PG8_SA(b, h) + aoff + m * 2048 + k * 1024); } while (0)
; #define PG8_LDB(dst, b, h) do { _Pragma("unroll") for (int n = 0; n < 2; ++n) _Pragma("unroll") for (int k = 0; k < 2; ++k) dst[n][k] = *(const LAS bf16x8*)(lds + PG8_SB(b, h) + boff + n * 2048 + k * 1024); } while (0)
; #define PG8_MMA(ai, bj, At, Bt) do { __builtin_amdgcn_s_setprio(1); _Pragma("unroll") for (int m = 0; m < 4; ++m) _Pragma("unroll") for (int n = 0; n < 2; ++n) _Pragma("unroll") for (int k = 0; k < 2; ++k) \
;         acc[ai][bj][m][n] = __builtin_amdgcn_mfma_f32_16x16x32_bf16(Bt[n][k], At[m][k], acc[ai][bj][m][n], 0, 0, 0); __builtin_amdgcn_s_setprio(0); } while (0)
; #define PG8_WAIT_V(n) asm volatile("s_waitcnt vmcnt(" #n ")" ::: "memory")
; #define PG8_WAIT_L(n) asm volatile("s_waitcnt lgkmcnt(" #n ")" ::: "memory")
; #define PG8_BAR __builtin_amdgcn_s_barrier()
; #define PG8_SCHED __builtin_amdgcn_sched_barrier(0)
;     ...
;             PG8_WAIT_V(8); PG8_WAIT_L(0); PG8_BAR; PG8_MMA(1, 0, At, B0); PG8_MMA(1, 1, At, B1); PG8_BAR; PG8_SCHED;
;             PG8_LDB(B0, 1, 0); PG8_LDB(B1, 1, 1); PG8_SCHED; PG8_LDA(At, 1, 0); PG8_STAGE(PG8_SA(0, 1), a2 + hA, voffA);
;             PG8_WAIT_V(8); PG8_WAIT_L(0); PG8_BAR; PG8_MMA(0, 0, At, B0); PG8_MMA(0, 1, At, B1); PG8_BAR; PG8_SCHED;
	s_setprio 1
	s_waitcnt lgkmcnt(0)
	v_mfma_f32_16x16x32_bf16 v[60:63], v[132:135], v[190:193], v[60:63]
	v_mfma_f32_16x16x32_bf16 v[56:59], v[140:143], v[190:193], v[56:59]
	v_mfma_f32_16x16x32_bf16 v[40:43], v[140:143], v[198:201], v[40:43]
	v_mfma_f32_16x16x32_bf16 v[44:47], v[132:135], v[198:201], v[44:47]
	v_mfma_f32_16x16x32_bf16 v[28:31], v[132:135], v[208:211], v[28:31]
	v_mfma_f32_16x16x32_bf16 v[24:27], v[140:143], v[208:211], v[24:27]
	v_mfma_f32_16x16x32_bf16 v[8:11], v[140:143], v[234:237], v[8:11]
	v_mfma_f32_16x16x32_bf16 v[12:15], v[132:135], v[234:237], v[12:15]
	v_mfma_f32_16x16x32_bf16 v[60:63], v[136:139], v[194:197], v[60:63]
	v_mfma_f32_16x16x32_bf16 v[56:59], v[144:147], v[194:197], v[56:59]
	v_mfma_f32_16x16x32_bf16 v[40:43], v[144:147], v[202:205], v[40:43]
	v_mfma_f32_16x16x32_bf16 v[44:47], v[136:139], v[202:205], v[44:47]
	v_mfma_f32_16x16x32_bf16 v[28:31], v[136:139], v[214:217], v[28:31]
	v_mfma_f32_16x16x32_bf16 v[24:27], v[144:147], v[214:217], v[24:27]
	v_mfma_f32_16x16x32_bf16 v[8:11], v[144:147], v[238:241], v[8:11]
	v_mfma_f32_16x16x32_bf16 v[12:15], v[136:139], v[238:241], v[12:15]
	s_setprio 0
	s_setprio 1
	v_mfma_f32_16x16x32_bf16 v[52:55], v[148:151], v[190:193], v[52:55]
	v_mfma_f32_16x16x32_bf16 v[48:51], v[182:185], v[190:193], v[48:51]
	v_mfma_f32_16x16x32_bf16 v[32:35], v[182:185], v[198:201], v[32:35]
	v_mfma_f32_16x16x32_bf16 v[36:39], v[148:151], v[198:201], v[36:39]
	v_mfma_f32_16x16x32_bf16 v[20:23], v[148:151], v[208:211], v[20:23]
	v_mfma_f32_16x16x32_bf16 v[16:19], v[182:185], v[208:211], v[16:19]
	v_mfma_f32_16x16x32_bf16 v[0:3], v[182:185], v[234:237], v[0:3]
	v_mfma_f32_16x16x32_bf16 v[4:7], v[148:151], v[234:237], v[4:7]
	v_mfma_f32_16x16x32_bf16 v[52:55], v[152:155], v[194:197], v[52:55]
	v_mfma_f32_16x16x32_bf16 v[48:51], v[186:189], v[194:197], v[48:51]
	v_mfma_f32_16x16x32_bf16 v[32:35], v[186:189], v[202:205], v[32:35]
	v_mfma_f32_16x16x32_bf16 v[36:39], v[152:155], v[202:205], v[36:39]
	v_mfma_f32_16x16x32_bf16 v[20:23], v[152:155], v[214:217], v[20:23]
	v_mfma_f32_16x16x32_bf16 v[16:19], v[186:189], v[214:217], v[16:19]
	v_mfma_f32_16x16x32_bf16 v[0:3], v[186:189], v[238:241], v[0:3]
	v_mfma_f32_16x16x32_bf16 v[4:7], v[152:155], v[238:241], v[4:7]
	s_setprio 0
	s_barrier
	s_add_i32 s31, 0, 0x18000
	s_add_i32 s36, 0, 0x1c000
	v_add_u32_e32 v144, s31, v231
	v_add_u32_e32 v156, s36, v231
	ds_read_b128 v[132:135], v144
	ds_read_b128 v[136:139], v144 offset:1024
	ds_read_b128 v[140:143], v144 offset:2048
	ds_read_b128 v[144:147], v144 offset:3072
	ds_read_b128 v[148:151], v156
	ds_read_b128 v[152:155], v156 offset:1024
	ds_read_b128 v[182:185], v156 offset:2048
	ds_read_b128 v[186:189], v156 offset:3072
	s_add_u32 s54, s76, 0x40000
	s_addc_u32 s55, s77, 0
	s_mov_b32 m0, s89
	v_lshl_add_u64 v[244:245], s[54:55], 0, v[168:169]
	ds_read_b128 v[190:193], v233 offset:32768
	ds_read_b128 v[194:197], v233 offset:33792
	ds_read_b128 v[198:201], v233 offset:34816
	ds_read_b128 v[202:205], v233 offset:35840
	ds_read_b128 v[208:211], v233 offset:36864
	ds_read_b128 v[214:217], v233 offset:37888
	ds_read_b128 v[234:237], v233 offset:38912
	ds_read_b128 v[238:241], v233 offset:39936
	global_load_lds_dwordx4 v[244:245], off
	v_lshl_add_u64 v[244:245], s[54:55], 0, v[172:173]
	s_mov_b32 m0, s92
	s_nop 0
	global_load_lds_dwordx4 v[244:245], off
	s_waitcnt vmcnt(8)
	s_waitcnt lgkmcnt(0)
	s_barrier
	s_setprio 1
	s_waitcnt lgkmcnt(0)
	v_mfma_f32_16x16x32_bf16 v[124:127], v[132:135], v[190:193], v[124:127]
	v_mfma_f32_16x16x32_bf16 v[120:123], v[140:143], v[190:193], v[120:123]
	v_mfma_f32_16x16x32_bf16 v[104:107], v[140:143], v[198:201], v[104:107]
	v_mfma_f32_16x16x32_bf16 v[108:111], v[132:135], v[198:201], v[108:111]
	v_mfma_f32_16x16x32_bf16 v[92:95], v[132:135], v[208:211], v[92:95]
	v_mfma_f32_16x16x32_bf16 v[88:91], v[140:143], v[208:211], v[88:91]
	v_mfma_f32_16x16x32_bf16 v[72:75], v[140:143], v[234:237], v[72:75]
	v_mfma_f32_16x16x32_bf16 v[76:79], v[132:135], v[234:237], v[76:79]
	v_mfma_f32_16x16x32_bf16 v[124:127], v[136:139], v[194:197], v[124:127]
	v_mfma_f32_16x16x32_bf16 v[120:123], v[144:147], v[194:197], v[120:123]
	v_mfma_f32_16x16x32_bf16 v[104:107], v[144:147], v[202:205], v[104:107]
	v_mfma_f32_16x16x32_bf16 v[108:111], v[136:139], v[202:205], v[108:111]
	v_mfma_f32_16x16x32_bf16 v[92:95], v[136:139], v[214:217], v[92:95]
	v_mfma_f32_16x16x32_bf16 v[88:91], v[144:147], v[214:217], v[88:91]
	v_mfma_f32_16x16x32_bf16 v[72:75], v[144:147], v[238:241], v[72:75]
	v_mfma_f32_16x16x32_bf16 v[76:79], v[136:139], v[238:241], v[76:79]
	s_setprio 0
	s_setprio 1
	v_mfma_f32_16x16x32_bf16 v[116:119], v[148:151], v[190:193], v[116:119]
	v_mfma_f32_16x16x32_bf16 v[112:115], v[182:185], v[190:193], v[112:115]
	v_mfma_f32_16x16x32_bf16 v[96:99], v[182:185], v[198:201], v[96:99]
	v_mfma_f32_16x16x32_bf16 v[100:103], v[148:151], v[198:201], v[100:103]
	v_mfma_f32_16x16x32_bf16 v[84:87], v[148:151], v[208:211], v[84:87]
	v_mfma_f32_16x16x32_bf16 v[80:83], v[182:185], v[208:211], v[80:83]
	v_mfma_f32_16x16x32_bf16 v[64:67], v[182:185], v[234:237], v[64:67]
	v_mfma_f32_16x16x32_bf16 v[68:71], v[148:151], v[234:237], v[68:71]
	v_mfma_f32_16x16x32_bf16 v[116:119], v[152:155], v[194:197], v[116:119]
	v_mfma_f32_16x16x32_bf16 v[112:115], v[186:189], v[194:197], v[112:115]
	v_mfma_f32_16x16x32_bf16 v[96:99], v[186:189], v[202:205], v[96:99]
	v_mfma_f32_16x16x32_bf16 v[100:103], v[152:155], v[202:205], v[100:103]
	v_mfma_f32_16x16x32_bf16 v[84:87], v[152:155], v[214:217], v[84:87]
	v_mfma_f32_16x16x32_bf16 v[80:83], v[186:189], v[214:217], v[80:83]
	v_mfma_f32_16x16x32_bf16 v[64:67], v[186:189], v[238:241], v[64:67]
	v_mfma_f32_16x16x32_bf16 v[68:71], v[152:155], v[238:241], v[68:71]
	s_setprio 0
	s_barrier
; #define PG8_STAGE(bufoff, gbase, voff) do { _Pragma("unroll") for (int _i = 0; _i < 2; ++_i) \
;         __builtin_amdgcn_global_load_lds((const unsigned*)((const char*)(gbase) + (voff)[_i]), (LAS unsigned*)(lds + (bufoff) + ldsw + _i * 8192), 16, 0, 0); } while (0)
; #define PG8_LDA(dst, b, h) do { _Pragma("unroll") for (int m = 0; m < 4; ++m) _Pragma("unroll") for (int k = 0; k < 2; ++k) dst[m][k] = *(const LAS bf16x8*)(lds + PG8_SA(b, h) + aoff + m * 2048 + k * 1024); } while (0)
; #define PG8_MMA(ai, bj, At, Bt) do { __builtin_amdgcn_s_setprio(1); _Pragma("unroll") for (int m = 0; m < 4; ++m) _Pragma("unroll") for (int n = 0; n < 2; ++n) _Pragma("unroll") for (int k = 0; k < 2; ++k) \
;         acc[ai][bj][m][n] = __builtin_amdgcn_mfma_f32_16x16x32_bf16(Bt[n][k], At[m][k], acc[ai][bj][m][n], 0, 0, 0); __builtin_amdgcn_s_setprio(0); } while (0)
; #define PG8_WAIT_V(n) asm volatile("s_waitcnt vmcnt(" #n ")" ::: "memory")
; #define PG8_WAIT_L(n) asm volatile("s_waitcnt lgkmcnt(" #n ")" ::: "memory")
; #define PG8_BAR __builtin_amdgcn_s_barrier()
; #define PG8_SCHED __builtin_amdgcn_sched_barrier(0)
;     ...
;         for (int t = 0; t < nt; t += 2) {
;     ...
;             PG8_LDA(At, 1, 1); PG8_STAGE(PG8_SB(1, 0), b3, voffB); PG8_STAGE(PG8_SB(1, 1), b3 + hB, voffB); PG8_STAGE(PG8_SA(1, 0), a3, voffA);
;             PG8_WAIT_V(8); PG8_WAIT_L(0); PG8_BAR; PG8_MMA(1, 0, At, B0); PG8_MMA(1, 1, At, B1); PG8_BAR; PG8_SCHED;
	s_add_i32 s31, s31, s79
	v_lshl_add_u64 v[206:207], v[206:207], 0, s[38:39]
	s_mov_b32 m0, s31
	ds_read_b128 v[190:193], v233 offset:49152
	ds_read_b128 v[194:197], v233 offset:50176
	ds_read_b128 v[198:201], v233 offset:51200
	ds_read_b128 v[202:205], v233 offset:52224
	ds_read_b128 v[208:211], v233 offset:53248
	ds_read_b128 v[214:217], v233 offset:54272
	ds_read_b128 v[234:237], v233 offset:55296
	ds_read_b128 v[238:241], v233 offset:56320
	global_load_lds_dwordx4 v[206:207], off
	s_add_i32 m0, s31, 0x2000
	s_add_u32 s54, s74, 0x40080
	v_lshl_add_u64 v[206:207], v[242:243], 0, s[38:39]
	s_addc_u32 s55, s75, 0
	s_add_i32 s31, s36, s79
	global_load_lds_dwordx4 v[206:207], off
	v_lshl_add_u64 v[206:207], s[54:55], 0, v[170:171]
	s_mov_b32 m0, s31
	s_nop 0
	global_load_lds_dwordx4 v[206:207], off
	v_lshl_add_u64 v[206:207], s[54:55], 0, v[174:175]
	s_add_i32 m0, s31, 0x2000
	s_nop 0
	global_load_lds_dwordx4 v[206:207], off
	v_lshl_add_u64 v[206:207], s[72:73], 0, v[168:169]
	s_mov_b32 m0, s95
	s_nop 0
	global_load_lds_dwordx4 v[206:207], off
	v_lshl_add_u64 v[206:207], s[72:73], 0, v[172:173]
	s_mov_b32 m0, s42
	s_nop 0
	global_load_lds_dwordx4 v[206:207], off
	s_waitcnt vmcnt(8)
	s_waitcnt lgkmcnt(0)
	s_barrier
	s_setprio 1
	s_waitcnt lgkmcnt(0)
	v_mfma_f32_16x16x32_bf16 v[60:63], v[132:135], v[190:193], v[60:63]
	v_mfma_f32_16x16x32_bf16 v[56:59], v[140:143], v[190:193], v[56:59]
	v_mfma_f32_16x16x32_bf16 v[40:43], v[140:143], v[198:201], v[40:43]
	v_mfma_f32_16x16x32_bf16 v[44:47], v[132:135], v[198:201], v[44:47]
	v_mfma_f32_16x16x32_bf16 v[28:31], v[132:135], v[208:211], v[28:31]
	v_mfma_f32_16x16x32_bf16 v[24:27], v[140:143], v[208:211], v[24:27]
	v_mfma_f32_16x16x32_bf16 v[8:11], v[140:143], v[234:237], v[8:11]
	v_mfma_f32_16x16x32_bf16 v[12:15], v[132:135], v[234:237], v[12:15]
	v_mfma_f32_16x16x32_bf16 v[60:63], v[136:139], v[194:197], v[60:63]
	v_mfma_f32_16x16x32_bf16 v[56:59], v[144:147], v[194:197], v[56:59]
	v_mfma_f32_16x16x32_bf16 v[40:43], v[144:147], v[202:205], v[40:43]
	v_mfma_f32_16x16x32_bf16 v[44:47], v[136:139], v[202:205], v[44:47]
	v_mfma_f32_16x16x32_bf16 v[28:31], v[136:139], v[214:217], v[28:31]
	v_mfma_f32_16x16x32_bf16 v[24:27], v[144:147], v[214:217], v[24:27]
	v_mfma_f32_16x16x32_bf16 v[8:11], v[144:147], v[238:241], v[8:11]
	v_mfma_f32_16x16x32_bf16 v[12:15], v[136:139], v[238:241], v[12:15]
	s_setprio 0
	s_setprio 1
	v_mfma_f32_16x16x32_bf16 v[52:55], v[148:151], v[190:193], v[52:55]
	v_mfma_f32_16x16x32_bf16 v[48:51], v[182:185], v[190:193], v[48:51]
	v_mfma_f32_16x16x32_bf16 v[32:35], v[182:185], v[198:201], v[32:35]
	v_mfma_f32_16x16x32_bf16 v[36:39], v[148:151], v[198:201], v[36:39]
	v_mfma_f32_16x16x32_bf16 v[20:23], v[148:151], v[208:211], v[20:23]
	v_mfma_f32_16x16x32_bf16 v[16:19], v[182:185], v[208:211], v[16:19]
	v_mfma_f32_16x16x32_bf16 v[0:3], v[182:185], v[234:237], v[0:3]
	v_mfma_f32_16x16x32_bf16 v[4:7], v[148:151], v[234:237], v[4:7]
	v_mfma_f32_16x16x32_bf16 v[52:55], v[152:155], v[194:197], v[52:55]
	v_mfma_f32_16x16x32_bf16 v[48:51], v[186:189], v[194:197], v[48:51]
	v_mfma_f32_16x16x32_bf16 v[32:35], v[186:189], v[202:205], v[32:35]
	v_mfma_f32_16x16x32_bf16 v[36:39], v[152:155], v[202:205], v[36:39]
	v_mfma_f32_16x16x32_bf16 v[20:23], v[152:155], v[214:217], v[20:23]
	v_mfma_f32_16x16x32_bf16 v[16:19], v[186:189], v[214:217], v[16:19]
	v_mfma_f32_16x16x32_bf16 v[0:3], v[186:189], v[238:241], v[0:3]
	v_mfma_f32_16x16x32_bf16 v[4:7], v[152:155], v[238:241], v[4:7]
	s_setprio 0
	s_barrier
	s_add_i32 s13, s13, 2
	s_add_u32 s90, s90, 0x100
	s_addc_u32 s91, s91, 0
	s_cmp_gt_u32 s13, 13
	s_cbranch_scc0 .LBB0_271
	s_and_b64 vcc, exec, s[28:29]
	s_cbranch_vccz .LBB0_274
	s_barrier

; #define PG8_STAGE(bufoff, gbase, voff) do { _Pragma("unroll") for (int _i = 0; _i < 2; ++_i) \
;         __builtin_amdgcn_global_load_lds((const unsigned*)((const char*)(gbase) + (voff)[_i]), (LAS unsigned*)(lds + (bufoff) + ldsw + _i * 8192), 16, 0, 0); } while (0)
; #define PG8_LDA(dst, b, h) do { _Pragma("unroll") for (int m = 0; m < 4; ++m) _Pragma("unroll") for (int k = 0; k < 2; ++k) dst[m][k] = *(const LAS bf16x8*)(lds + PG8_SA(b, h) + aoff + m * 2048 + k * 1024); } while (0)
; #define PG8_LDB(dst, b, h) do { _Pragma("unroll") for (int n = 0; n < 2; ++n) _Pragma("unroll") for (int k = 0; k < 2; ++k) dst[n][k] = *(const LAS bf16x8*)(lds + PG8_SB(b, h) + boff + n * 2048 + k * 1024); } while (0)
; #define PG8_MMA(ai, bj, At, Bt) do { __builtin_amdgcn_s_setprio(1); _Pragma("unroll") for (int m = 0; m < 4; ++m) _Pragma("unroll") for (int n = 0; n < 2; ++n) _Pragma("unroll") for (int k = 0; k < 2; ++k) \
;         acc[ai][bj][m][n] = __builtin_amdgcn_mfma_f32_16x16x32_bf16(Bt[n][k], At[m][k], acc[ai][bj][m][n], 0, 0, 0); __builtin_amdgcn_s_setprio(0); } while (0)
; #define PG8_WAIT_V(n) asm volatile("s_waitcnt vmcnt(" #n ")" ::: "memory")
; #define PG8_WAIT_L(n) asm volatile("s_waitcnt lgkmcnt(" #n ")" ::: "memory")
; #define PG8_BAR __builtin_amdgcn_s_barrier()
; #define PG8_SCHED __builtin_amdgcn_sched_barrier(0)
;     ...
;             PG8_LDB(B0, 0, 0); PG8_LDB(B1, 0, 1); PG8_SCHED; PG8_LDA(At, 0, 0); PG8_STAGE(PG8_SA(1, 1), a1 + hA, voffA);
;             PG8_WAIT_V(8); PG8_WAIT_L(0); PG8_BAR; PG8_MMA(0, 0, At, B0); PG8_MMA(0, 1, At, B1); PG8_BAR; PG8_SCHED;
;             PG8_LDA(At, 0, 1); PG8_STAGE(PG8_SB(0, 0), b2, voffB); PG8_STAGE(PG8_SB(0, 1), b2 + hB, voffB); PG8_STAGE(PG8_SA(0, 0), a2, voffA);
;             PG8_WAIT_V(8); PG8_WAIT_L(0); PG8_BAR; PG8_MMA(1, 0, At, B0); PG8_MMA(1, 1, At, B1); PG8_BAR; PG8_SCHED;
.LBB0_299:
	s_add_u32 s72, s44, s52
	s_addc_u32 s73, s45, s53
	s_add_u32 s98, s72, 0x40080
	s_addc_u32 s99, s73, 0
	s_add_u32 s76, s72, 0x100
	s_addc_u32 s77, s73, 0
	s_add_u32 s74, s79, s52
	s_addc_u32 s75, s80, s53
	s_add_u32 s72, s72, 0x180
	s_addc_u32 s73, s73, 0
	s_add_i32 s82, 0, 0x10000
	s_add_i32 s89, 0, 0x14000
	v_add_u32_e32 v144, s82, v193
	v_add_u32_e32 v184, s89, v193
	ds_read_b128 v[132:135], v144
	ds_read_b128 v[136:139], v144 offset:1024
	ds_read_b128 v[140:143], v144 offset:2048
	ds_read_b128 v[144:147], v144 offset:3072
	ds_read_b128 v[148:151], v184
	ds_read_b128 v[176:179], v184 offset:1024
	ds_read_b128 v[180:183], v184 offset:2048
	ds_read_b128 v[184:187], v184 offset:3072
	s_cmpk_eq_i32 s52, 0x700
	s_cselect_b32 s73, s78, s73
	s_cselect_b32 s72, s55, s72
	s_cselect_b32 s75, s27, s75
	s_cselect_b32 s74, s54, s74
	s_cselect_b32 s77, s3, s77
	s_cselect_b32 s76, s29, s76
	s_add_i32 m0, s6, 0xc000
	ds_read_b128 v[188:191], v198
	ds_read_b128 v[200:203], v198 offset:1024
	ds_read_b128 v[208:211], v198 offset:2048
	ds_read_b128 v[214:217], v198 offset:3072
	ds_read_b128 v[230:233], v198 offset:4096
	ds_read_b128 v[234:237], v198 offset:5120
	ds_read_b128 v[238:241], v198 offset:6144
	ds_read_b128 v[242:245], v198 offset:7168
	global_load_lds_dwordx4 v172, s[98:99]
	s_add_i32 m0, s6, 0xe000
	s_nop 0
	global_load_lds_dwordx4 v174, s[98:99]
	s_waitcnt vmcnt(8)
	s_waitcnt lgkmcnt(0)
	s_barrier
	s_setprio 1
	s_waitcnt lgkmcnt(0)
	v_mfma_f32_16x16x32_bf16 v[124:127], v[132:135], v[188:191], v[124:127]
	v_mfma_f32_16x16x32_bf16 v[120:123], v[140:143], v[188:191], v[120:123]
	v_mfma_f32_16x16x32_bf16 v[104:107], v[140:143], v[208:211], v[104:107]
	v_mfma_f32_16x16x32_bf16 v[108:111], v[132:135], v[208:211], v[108:111]
	v_mfma_f32_16x16x32_bf16 v[92:95], v[132:135], v[230:233], v[92:95]
	v_mfma_f32_16x16x32_bf16 v[88:91], v[140:143], v[230:233], v[88:91]
	v_mfma_f32_16x16x32_bf16 v[72:75], v[140:143], v[238:241], v[72:75]
	v_mfma_f32_16x16x32_bf16 v[76:79], v[132:135], v[238:241], v[76:79]
	v_mfma_f32_16x16x32_bf16 v[124:127], v[136:139], v[200:203], v[124:127]
	v_mfma_f32_16x16x32_bf16 v[120:123], v[144:147], v[200:203], v[120:123]
	v_mfma_f32_16x16x32_bf16 v[104:107], v[144:147], v[214:217], v[104:107]
	v_mfma_f32_16x16x32_bf16 v[108:111], v[136:139], v[214:217], v[108:111]
	v_mfma_f32_16x16x32_bf16 v[92:95], v[136:139], v[234:237], v[92:95]
	v_mfma_f32_16x16x32_bf16 v[88:91], v[144:147], v[234:237], v[88:91]
	v_mfma_f32_16x16x32_bf16 v[72:75], v[144:147], v[242:245], v[72:75]
	v_mfma_f32_16x16x32_bf16 v[76:79], v[136:139], v[242:245], v[76:79]
	s_setprio 0
	s_setprio 1
	v_mfma_f32_16x16x32_bf16 v[116:119], v[148:151], v[188:191], v[116:119]
	v_mfma_f32_16x16x32_bf16 v[112:115], v[180:183], v[188:191], v[112:115]
	v_mfma_f32_16x16x32_bf16 v[96:99], v[180:183], v[208:211], v[96:99]
	v_mfma_f32_16x16x32_bf16 v[100:103], v[148:151], v[208:211], v[100:103]
	v_mfma_f32_16x16x32_bf16 v[84:87], v[148:151], v[230:233], v[84:87]
	v_mfma_f32_16x16x32_bf16 v[80:83], v[180:183], v[230:233], v[80:83]
	v_mfma_f32_16x16x32_bf16 v[64:67], v[180:183], v[238:241], v[64:67]
	v_mfma_f32_16x16x32_bf16 v[68:71], v[148:151], v[238:241], v[68:71]
	v_mfma_f32_16x16x32_bf16 v[116:119], v[176:179], v[200:203], v[116:119]
	v_mfma_f32_16x16x32_bf16 v[112:115], v[184:187], v[200:203], v[112:115]
	v_mfma_f32_16x16x32_bf16 v[96:99], v[184:187], v[214:217], v[96:99]
	v_mfma_f32_16x16x32_bf16 v[100:103], v[176:179], v[214:217], v[100:103]
	v_mfma_f32_16x16x32_bf16 v[84:87], v[176:179], v[234:237], v[84:87]
	v_mfma_f32_16x16x32_bf16 v[80:83], v[184:187], v[234:237], v[80:83]
	v_mfma_f32_16x16x32_bf16 v[64:67], v[184:187], v[242:245], v[64:67]
	v_mfma_f32_16x16x32_bf16 v[68:71], v[176:179], v[242:245], v[68:71]
	s_setprio 0
	s_barrier
	s_add_i32 s82, s82, s5
	s_mov_b32 m0, s82
	ds_read_b128 v[188:191], v198 offset:16384
	ds_read_b128 v[200:203], v198 offset:17408
	ds_read_b128 v[208:211], v198 offset:18432
	ds_read_b128 v[214:217], v198 offset:19456
	ds_read_b128 v[230:233], v198 offset:20480
	ds_read_b128 v[234:237], v198 offset:21504
	ds_read_b128 v[238:241], v198 offset:22528
	ds_read_b128 v[242:245], v198 offset:23552
	global_load_lds_dwordx4 v156, s[74:75]
	s_add_i32 m0, s82, 0x2000
	s_add_u32 s82, s74, 0x40000
	s_addc_u32 s83, s75, 0
	s_add_i32 s89, s89, s5
	global_load_lds_dwordx4 v168, s[74:75]
	s_mov_b32 m0, s89
	s_nop 0
	global_load_lds_dwordx4 v156, s[82:83]
	s_add_i32 m0, s89, 0x2000
	s_nop 0
	global_load_lds_dwordx4 v168, s[82:83]
	s_mov_b32 m0, s6
	s_nop 0
	global_load_lds_dwordx4 v152, s[76:77]
	s_mov_b32 m0, s7
	s_nop 0
	global_load_lds_dwordx4 v154, s[76:77]
	s_waitcnt vmcnt(8)
	s_waitcnt lgkmcnt(0)
	s_barrier
; #define PG8_STAGE(bufoff, gbase, voff) do { _Pragma("unroll") for (int _i = 0; _i < 2; ++_i) \
;         __builtin_amdgcn_global_load_lds((const unsigned*)((const char*)(gbase) + (voff)[_i]), (LAS unsigned*)(lds + (bufoff) + ldsw + _i * 8192), 16, 0, 0); } while (0)
; #define PG8_LDA(dst, b, h) do { _Pragma("unroll") for (int m = 0; m < 4; ++m) _Pragma("unroll") for (int k = 0; k < 2; ++k) dst[m][k] = *(const LAS bf16x8*)(lds + PG8_SA(b, h) + aoff + m * 2048 + k * 1024); } while (0)
; #define PG8_LDB(dst, b, h) do { _Pragma("unroll") for (int n = 0; n < 2; ++n) _Pragma("unroll") for (int k = 0; k < 2; ++k) dst[n][k] = *(const LAS bf16x8*)(lds + PG8_SB(b, h) + boff + n * 2048 + k * 1024); } while (0)
; #define PG8_MMA(ai, bj, At, Bt) do { __builtin_amdgcn_s_setprio(1); _Pragma("unroll") for (int m = 0; m < 4; ++m) _Pragma("unroll") for (int n = 0; n < 2; ++n) _Pragma("unroll") for (int k = 0; k < 2; ++k) \
;         acc[ai][bj][m][n] = __builtin_amdgcn_mfma_f32_16x16x32_bf16(Bt[n][k], At[m][k], acc[ai][bj][m][n], 0, 0, 0); __builtin_amdgcn_s_setprio(0); } while (0)
; #define PG8_WAIT_V(n) asm volatile("s_waitcnt vmcnt(" #n ")" ::: "memory")
; #define PG8_WAIT_L(n) asm volatile("s_waitcnt lgkmcnt(" #n ")" ::: "memory")
; #define PG8_BAR __builtin_amdgcn_s_barrier()
; #define PG8_SCHED __builtin_amdgcn_sched_barrier(0)
;     ...
;             PG8_WAIT_V(8); PG8_WAIT_L(0); PG8_BAR; PG8_MMA(1, 0, At, B0); PG8_MMA(1, 1, At, B1); PG8_BAR; PG8_SCHED;
;             PG8_LDB(B0, 1, 0); PG8_LDB(B1, 1, 1); PG8_SCHED; PG8_LDA(At, 1, 0); PG8_STAGE(PG8_SA(0, 1), a2 + hA, voffA);
;             PG8_WAIT_V(8); PG8_WAIT_L(0); PG8_BAR; PG8_MMA(0, 0, At, B0); PG8_MMA(0, 1, At, B1); PG8_BAR; PG8_SCHED;
	s_setprio 1
	s_waitcnt lgkmcnt(0)
	v_mfma_f32_16x16x32_bf16 v[60:63], v[132:135], v[188:191], v[60:63]
	v_mfma_f32_16x16x32_bf16 v[56:59], v[140:143], v[188:191], v[56:59]
	v_mfma_f32_16x16x32_bf16 v[40:43], v[140:143], v[208:211], v[40:43]
	v_mfma_f32_16x16x32_bf16 v[44:47], v[132:135], v[208:211], v[44:47]
	v_mfma_f32_16x16x32_bf16 v[28:31], v[132:135], v[230:233], v[28:31]
	v_mfma_f32_16x16x32_bf16 v[24:27], v[140:143], v[230:233], v[24:27]
	v_mfma_f32_16x16x32_bf16 v[8:11], v[140:143], v[238:241], v[8:11]
	v_mfma_f32_16x16x32_bf16 v[12:15], v[132:135], v[238:241], v[12:15]
	v_mfma_f32_16x16x32_bf16 v[60:63], v[136:139], v[200:203], v[60:63]
	v_mfma_f32_16x16x32_bf16 v[56:59], v[144:147], v[200:203], v[56:59]
	v_mfma_f32_16x16x32_bf16 v[40:43], v[144:147], v[214:217], v[40:43]
	v_mfma_f32_16x16x32_bf16 v[44:47], v[136:139], v[214:217], v[44:47]
	v_mfma_f32_16x16x32_bf16 v[28:31], v[136:139], v[234:237], v[28:31]
	v_mfma_f32_16x16x32_bf16 v[24:27], v[144:147], v[234:237], v[24:27]
	v_mfma_f32_16x16x32_bf16 v[8:11], v[144:147], v[242:245], v[8:11]
	v_mfma_f32_16x16x32_bf16 v[12:15], v[136:139], v[242:245], v[12:15]
	s_setprio 0
	s_setprio 1
	v_mfma_f32_16x16x32_bf16 v[52:55], v[148:151], v[188:191], v[52:55]
	v_mfma_f32_16x16x32_bf16 v[48:51], v[180:183], v[188:191], v[48:51]
	v_mfma_f32_16x16x32_bf16 v[32:35], v[180:183], v[208:211], v[32:35]
	v_mfma_f32_16x16x32_bf16 v[36:39], v[148:151], v[208:211], v[36:39]
	v_mfma_f32_16x16x32_bf16 v[20:23], v[148:151], v[230:233], v[20:23]
	v_mfma_f32_16x16x32_bf16 v[16:19], v[180:183], v[230:233], v[16:19]
	v_mfma_f32_16x16x32_bf16 v[0:3], v[180:183], v[238:241], v[0:3]
	v_mfma_f32_16x16x32_bf16 v[4:7], v[148:151], v[238:241], v[4:7]
	v_mfma_f32_16x16x32_bf16 v[52:55], v[176:179], v[200:203], v[52:55]
	v_mfma_f32_16x16x32_bf16 v[48:51], v[184:187], v[200:203], v[48:51]
	v_mfma_f32_16x16x32_bf16 v[32:35], v[184:187], v[214:217], v[32:35]
	v_mfma_f32_16x16x32_bf16 v[36:39], v[176:179], v[214:217], v[36:39]
	v_mfma_f32_16x16x32_bf16 v[20:23], v[176:179], v[234:237], v[20:23]
	v_mfma_f32_16x16x32_bf16 v[16:19], v[184:187], v[234:237], v[16:19]
	v_mfma_f32_16x16x32_bf16 v[0:3], v[184:187], v[242:245], v[0:3]
	v_mfma_f32_16x16x32_bf16 v[4:7], v[176:179], v[242:245], v[4:7]
	s_setprio 0
	s_barrier
	s_add_i32 s82, 0, 0x18000
	s_add_i32 s83, 0, 0x1c000
	v_add_u32_e32 v144, s82, v193
	v_add_u32_e32 v184, s83, v193
	ds_read_b128 v[132:135], v144
	ds_read_b128 v[136:139], v144 offset:1024
	ds_read_b128 v[140:143], v144 offset:2048
	ds_read_b128 v[144:147], v144 offset:3072
	ds_read_b128 v[148:151], v184
	ds_read_b128 v[176:179], v184 offset:1024
	ds_read_b128 v[180:183], v184 offset:2048
	ds_read_b128 v[184:187], v184 offset:3072
	s_add_u32 s76, s76, 0x40000
	s_addc_u32 s77, s77, 0
	s_mov_b32 m0, s8
	ds_read_b128 v[188:191], v198 offset:32768
	ds_read_b128 v[200:203], v198 offset:33792
	ds_read_b128 v[208:211], v198 offset:34816
	ds_read_b128 v[214:217], v198 offset:35840
	ds_read_b128 v[230:233], v198 offset:36864
	ds_read_b128 v[234:237], v198 offset:37888
	ds_read_b128 v[238:241], v198 offset:38912
	ds_read_b128 v[242:245], v198 offset:39936
	global_load_lds_dwordx4 v152, s[76:77]
	s_mov_b32 m0, s9
	s_nop 0
	global_load_lds_dwordx4 v154, s[76:77]
	s_waitcnt vmcnt(8)
	s_waitcnt lgkmcnt(0)
	s_barrier
	s_setprio 1
	s_waitcnt lgkmcnt(0)
	v_mfma_f32_16x16x32_bf16 v[124:127], v[132:135], v[188:191], v[124:127]
	v_mfma_f32_16x16x32_bf16 v[120:123], v[140:143], v[188:191], v[120:123]
	v_mfma_f32_16x16x32_bf16 v[104:107], v[140:143], v[208:211], v[104:107]
	v_mfma_f32_16x16x32_bf16 v[108:111], v[132:135], v[208:211], v[108:111]
	v_mfma_f32_16x16x32_bf16 v[92:95], v[132:135], v[230:233], v[92:95]
	v_mfma_f32_16x16x32_bf16 v[88:91], v[140:143], v[230:233], v[88:91]
	v_mfma_f32_16x16x32_bf16 v[72:75], v[140:143], v[238:241], v[72:75]
	v_mfma_f32_16x16x32_bf16 v[76:79], v[132:135], v[238:241], v[76:79]
	v_mfma_f32_16x16x32_bf16 v[124:127], v[136:139], v[200:203], v[124:127]
	v_mfma_f32_16x16x32_bf16 v[120:123], v[144:147], v[200:203], v[120:123]
	v_mfma_f32_16x16x32_bf16 v[104:107], v[144:147], v[214:217], v[104:107]
	v_mfma_f32_16x16x32_bf16 v[108:111], v[136:139], v[214:217], v[108:111]
	v_mfma_f32_16x16x32_bf16 v[92:95], v[136:139], v[234:237], v[92:95]
	v_mfma_f32_16x16x32_bf16 v[88:91], v[144:147], v[234:237], v[88:91]
	v_mfma_f32_16x16x32_bf16 v[72:75], v[144:147], v[242:245], v[72:75]
	v_mfma_f32_16x16x32_bf16 v[76:79], v[136:139], v[242:245], v[76:79]
	s_setprio 0
	s_setprio 1
	v_mfma_f32_16x16x32_bf16 v[116:119], v[148:151], v[188:191], v[116:119]
	v_mfma_f32_16x16x32_bf16 v[112:115], v[180:183], v[188:191], v[112:115]
	v_mfma_f32_16x16x32_bf16 v[96:99], v[180:183], v[208:211], v[96:99]
	v_mfma_f32_16x16x32_bf16 v[100:103], v[148:151], v[208:211], v[100:103]
	v_mfma_f32_16x16x32_bf16 v[84:87], v[148:151], v[230:233], v[84:87]
	v_mfma_f32_16x16x32_bf16 v[80:83], v[180:183], v[230:233], v[80:83]
	v_mfma_f32_16x16x32_bf16 v[64:67], v[180:183], v[238:241], v[64:67]
	v_mfma_f32_16x16x32_bf16 v[68:71], v[148:151], v[238:241], v[68:71]
	v_mfma_f32_16x16x32_bf16 v[116:119], v[176:179], v[200:203], v[116:119]
	v_mfma_f32_16x16x32_bf16 v[112:115], v[184:187], v[200:203], v[112:115]
	v_mfma_f32_16x16x32_bf16 v[96:99], v[184:187], v[214:217], v[96:99]
	v_mfma_f32_16x16x32_bf16 v[100:103], v[176:179], v[214:217], v[100:103]
	v_mfma_f32_16x16x32_bf16 v[84:87], v[176:179], v[234:237], v[84:87]
	v_mfma_f32_16x16x32_bf16 v[80:83], v[184:187], v[234:237], v[80:83]
	v_mfma_f32_16x16x32_bf16 v[64:67], v[184:187], v[242:245], v[64:67]
	v_mfma_f32_16x16x32_bf16 v[68:71], v[176:179], v[242:245], v[68:71]
	s_setprio 0
	s_barrier
; #define PG8_STAGE(bufoff, gbase, voff) do { _Pragma("unroll") for (int _i = 0; _i < 2; ++_i) \
;         __builtin_amdgcn_global_load_lds((const unsigned*)((const char*)(gbase) + (voff)[_i]), (LAS unsigned*)(lds + (bufoff) + ldsw + _i * 8192), 16, 0, 0); } while (0)
; #define PG8_LDA(dst, b, h) do { _Pragma("unroll") for (int m = 0; m < 4; ++m) _Pragma("unroll") for (int k = 0; k < 2; ++k) dst[m][k] = *(const LAS bf16x8*)(lds + PG8_SA(b, h) + aoff + m * 2048 + k * 1024); } while (0)
; #define PG8_MMA(ai, bj, At, Bt) do { __builtin_amdgcn_s_setprio(1); _Pragma("unroll") for (int m = 0; m < 4; ++m) _Pragma("unroll") for (int n = 0; n < 2; ++n) _Pragma("unroll") for (int k = 0; k < 2; ++k) \
;         acc[ai][bj][m][n] = __builtin_amdgcn_mfma_f32_16x16x32_bf16(Bt[n][k], At[m][k], acc[ai][bj][m][n], 0, 0, 0); __builtin_amdgcn_s_setprio(0); } while (0)
; #define PG8_WAIT_V(n) asm volatile("s_waitcnt vmcnt(" #n ")" ::: "memory")
; #define PG8_WAIT_L(n) asm volatile("s_waitcnt lgkmcnt(" #n ")" ::: "memory")
; #define PG8_BAR __builtin_amdgcn_s_barrier()
; #define PG8_SCHED __builtin_amdgcn_sched_barrier(0)
;     ...
;         for (int t = 0; t < nt; t += 2) {
;     ...
;             PG8_LDA(At, 1, 1); PG8_STAGE(PG8_SB(1, 0), b3, voffB); PG8_STAGE(PG8_SB(1, 1), b3 + hB, voffB); PG8_STAGE(PG8_SA(1, 0), a3, voffA);
;             PG8_WAIT_V(8); PG8_WAIT_L(0); PG8_BAR; PG8_MMA(1, 0, At, B0); PG8_MMA(1, 1, At, B1); PG8_BAR; PG8_SCHED;
	s_add_i32 s76, s82, s5
	s_add_u32 s100, s74, s38
	s_addc_u32 s101, s75, s39
	s_mov_b32 m0, s76
	ds_read_b128 v[188:191], v198 offset:49152
	ds_read_b128 v[200:203], v198 offset:50176
	ds_read_b128 v[208:211], v198 offset:51200
	ds_read_b128 v[214:217], v198 offset:52224
	ds_read_b128 v[230:233], v198 offset:53248
	ds_read_b128 v[234:237], v198 offset:54272
	ds_read_b128 v[238:241], v198 offset:55296
	ds_read_b128 v[242:245], v198 offset:56320
	global_load_lds_dwordx4 v156, s[100:101]
	s_add_i32 m0, s76, 0x2000
	s_add_u32 s74, s74, 0x40080
	s_addc_u32 s75, s75, 0
	s_add_i32 s76, s83, s5
	global_load_lds_dwordx4 v168, s[100:101]
	s_mov_b32 m0, s76
	s_nop 0
	global_load_lds_dwordx4 v156, s[74:75]
	s_add_i32 m0, s76, 0x2000
	s_nop 0
	global_load_lds_dwordx4 v168, s[74:75]
	s_mov_b32 m0, s36
	s_nop 0
	global_load_lds_dwordx4 v152, s[72:73]
	s_mov_b32 m0, s42
	s_nop 0
	global_load_lds_dwordx4 v154, s[72:73]
	s_waitcnt vmcnt(8)
	s_waitcnt lgkmcnt(0)
	s_barrier
	s_setprio 1
	s_waitcnt lgkmcnt(0)
	v_mfma_f32_16x16x32_bf16 v[60:63], v[132:135], v[188:191], v[60:63]
	v_mfma_f32_16x16x32_bf16 v[56:59], v[140:143], v[188:191], v[56:59]
	v_mfma_f32_16x16x32_bf16 v[40:43], v[140:143], v[208:211], v[40:43]
	v_mfma_f32_16x16x32_bf16 v[44:47], v[132:135], v[208:211], v[44:47]
	v_mfma_f32_16x16x32_bf16 v[28:31], v[132:135], v[230:233], v[28:31]
	v_mfma_f32_16x16x32_bf16 v[24:27], v[140:143], v[230:233], v[24:27]
	v_mfma_f32_16x16x32_bf16 v[8:11], v[140:143], v[238:241], v[8:11]
	v_mfma_f32_16x16x32_bf16 v[12:15], v[132:135], v[238:241], v[12:15]
	v_mfma_f32_16x16x32_bf16 v[60:63], v[136:139], v[200:203], v[60:63]
	v_mfma_f32_16x16x32_bf16 v[56:59], v[144:147], v[200:203], v[56:59]
	v_mfma_f32_16x16x32_bf16 v[40:43], v[144:147], v[214:217], v[40:43]
	v_mfma_f32_16x16x32_bf16 v[44:47], v[136:139], v[214:217], v[44:47]
	v_mfma_f32_16x16x32_bf16 v[28:31], v[136:139], v[234:237], v[28:31]
	v_mfma_f32_16x16x32_bf16 v[24:27], v[144:147], v[234:237], v[24:27]
	v_mfma_f32_16x16x32_bf16 v[8:11], v[144:147], v[242:245], v[8:11]
	v_mfma_f32_16x16x32_bf16 v[12:15], v[136:139], v[242:245], v[12:15]
	s_setprio 0
	s_setprio 1
	v_mfma_f32_16x16x32_bf16 v[52:55], v[148:151], v[188:191], v[52:55]
	v_mfma_f32_16x16x32_bf16 v[48:51], v[180:183], v[188:191], v[48:51]
	v_mfma_f32_16x16x32_bf16 v[32:35], v[180:183], v[208:211], v[32:35]
	v_mfma_f32_16x16x32_bf16 v[36:39], v[148:151], v[208:211], v[36:39]
	v_mfma_f32_16x16x32_bf16 v[20:23], v[148:151], v[230:233], v[20:23]
	v_mfma_f32_16x16x32_bf16 v[16:19], v[180:183], v[230:233], v[16:19]
	v_mfma_f32_16x16x32_bf16 v[0:3], v[180:183], v[238:241], v[0:3]
	v_mfma_f32_16x16x32_bf16 v[4:7], v[148:151], v[238:241], v[4:7]
	v_mfma_f32_16x16x32_bf16 v[52:55], v[176:179], v[200:203], v[52:55]
	v_mfma_f32_16x16x32_bf16 v[48:51], v[184:187], v[200:203], v[48:51]
	v_mfma_f32_16x16x32_bf16 v[32:35], v[184:187], v[214:217], v[32:35]
	v_mfma_f32_16x16x32_bf16 v[36:39], v[176:179], v[214:217], v[36:39]
	v_mfma_f32_16x16x32_bf16 v[20:23], v[176:179], v[234:237], v[20:23]
	v_mfma_f32_16x16x32_bf16 v[16:19], v[184:187], v[234:237], v[16:19]
	v_mfma_f32_16x16x32_bf16 v[0:3], v[184:187], v[242:245], v[0:3]
	v_mfma_f32_16x16x32_bf16 v[4:7], v[176:179], v[242:245], v[4:7]
	s_setprio 0
	s_barrier
	s_add_i32 s81, s81, 2
	s_add_u32 s52, s52, 0x100
	s_addc_u32 s53, s53, 0
	s_cmp_gt_u32 s81, 13
	s_cbranch_scc0 .LBB0_299
	s_and_b64 vcc, exec, s[16:17]
	s_cbranch_vccz .LBB0_302
	s_barrier

; #define PG8_STAGE(bufoff, gbase, voff) do { _Pragma("unroll") for (int _i = 0; _i < 2; ++_i) \
;         __builtin_amdgcn_global_load_lds((const unsigned*)((const char*)(gbase) + (voff)[_i]), (LAS unsigned*)(lds + (bufoff) + ldsw + _i * 8192), 16, 0, 0); } while (0)
; #define PG8_LDA(dst, b, h) do { _Pragma("unroll") for (int m = 0; m < 4; ++m) _Pragma("unroll") for (int k = 0; k < 2; ++k) dst[m][k] = *(const LAS bf16x8*)(lds + PG8_SA(b, h) + aoff + m * 2048 + k * 1024); } while (0)
; #define PG8_LDB(dst, b, h) do { _Pragma("unroll") for (int n = 0; n < 2; ++n) _Pragma("unroll") for (int k = 0; k < 2; ++k) dst[n][k] = *(const LAS bf16x8*)(lds + PG8_SB(b, h) + boff + n * 2048 + k * 1024); } while (0)
; #define PG8_MMA(ai, bj, At, Bt) do { __builtin_amdgcn_s_setprio(1); _Pragma("unroll") for (int m = 0; m < 4; ++m) _Pragma("unroll") for (int n = 0; n < 2; ++n) _Pragma("unroll") for (int k = 0; k < 2; ++k) \
;         acc[ai][bj][m][n] = __builtin_amdgcn_mfma_f32_16x16x32_bf16(Bt[n][k], At[m][k], acc[ai][bj][m][n], 0, 0, 0); __builtin_amdgcn_s_setprio(0); } while (0)
; #define PG8_WAIT_V(n) asm volatile("s_waitcnt vmcnt(" #n ")" ::: "memory")
; #define PG8_WAIT_L(n) asm volatile("s_waitcnt lgkmcnt(" #n ")" ::: "memory")
; #define PG8_BAR __builtin_amdgcn_s_barrier()
; #define PG8_SCHED __builtin_amdgcn_sched_barrier(0)
;     ...
;             PG8_LDB(B0, 0, 0); PG8_LDB(B1, 0, 1); PG8_SCHED; PG8_LDA(At, 0, 0); PG8_STAGE(PG8_SA(1, 1), a1 + hA, voffA);
;             PG8_WAIT_V(8); PG8_WAIT_L(0); PG8_BAR; PG8_MMA(0, 0, At, B0); PG8_MMA(0, 1, At, B1); PG8_BAR; PG8_SCHED;
;             PG8_LDA(At, 0, 1); PG8_STAGE(PG8_SB(0, 0), b2, voffB); PG8_STAGE(PG8_SB(0, 1), b2 + hB, voffB); PG8_STAGE(PG8_SA(0, 0), a2, voffA);
;             PG8_WAIT_V(8); PG8_WAIT_L(0); PG8_BAR; PG8_MMA(1, 0, At, B0); PG8_MMA(1, 1, At, B1); PG8_BAR; PG8_SCHED;
.LBB0_364:
	s_add_i32 s6, s74, 2
	s_add_u32 s26, s92, vcc_lo
	s_addc_u32 s27, s93, vcc_hi
	s_add_u32 s98, s26, 0x80
	s_addc_u32 s99, s27, 0
	s_add_u32 s76, s26, 0x100
	s_addc_u32 s77, s27, 0
	s_add_u32 s9, s94, vcc_lo
	s_addc_u32 s8, s95, vcc_hi
	s_add_u32 s26, s26, 0x180
	s_addc_u32 s27, s27, 0
	s_add_i32 s50, 0, 0x10000
	s_add_i32 s51, 0, 0x14000
	v_add_u32_e32 v154, s50, v168
	ds_read_b128 v[132:135], v154
	ds_read_b128 v[146:149], v154 offset:1024
	ds_read_b128 v[150:153], v154 offset:2048
	ds_read_b128 v[172:175], v154 offset:3072
	v_add_u32_e32 v154, s51, v168
	ds_read_b128 v[176:179], v154
	ds_read_b128 v[180:183], v154 offset:1024
	ds_read_b128 v[184:187], v154 offset:2048
	ds_read_b128 v[188:191], v154 offset:3072
	s_cmp_eq_u32 s5, s74
	s_cselect_b32 s74, s97, s26
	s_cselect_b32 s75, s79, s27
	s_cselect_b32 s27, s45, s8
	s_cselect_b32 s26, s96, s9
	s_cselect_b32 s77, s43, s77
	s_cselect_b32 s76, s82, s76
	s_add_i32 m0, s83, 0xc000
	ds_read_b128 v[192:195], v170
	ds_read_b128 v[196:199], v170 offset:1024
	ds_read_b128 v[200:203], v170 offset:2048
	ds_read_b128 v[208:211], v170 offset:3072
	ds_read_b128 v[214:217], v170 offset:4096
	ds_read_b128 v[230:233], v170 offset:5120
	ds_read_b128 v[234:237], v170 offset:6144
	ds_read_b128 v[238:241], v170 offset:7168
	global_load_lds_dwordx4 v144, s[98:99]
	s_add_i32 m0, s83, 0xe000
	s_nop 0
	global_load_lds_dwordx4 v142, s[98:99]
	s_waitcnt vmcnt(8)
	s_waitcnt lgkmcnt(0)
	s_barrier
	s_setprio 1
	s_waitcnt lgkmcnt(0)
	v_mfma_f32_16x16x32_bf16 v[124:127], v[132:135], v[192:195], v[124:127]
	v_mfma_f32_16x16x32_bf16 v[120:123], v[150:153], v[192:195], v[120:123]
	v_mfma_f32_16x16x32_bf16 v[104:107], v[150:153], v[200:203], v[104:107]
	v_mfma_f32_16x16x32_bf16 v[108:111], v[132:135], v[200:203], v[108:111]
	v_mfma_f32_16x16x32_bf16 v[92:95], v[132:135], v[214:217], v[92:95]
	v_mfma_f32_16x16x32_bf16 v[88:91], v[150:153], v[214:217], v[88:91]
	v_mfma_f32_16x16x32_bf16 v[72:75], v[150:153], v[234:237], v[72:75]
	v_mfma_f32_16x16x32_bf16 v[76:79], v[132:135], v[234:237], v[76:79]
	v_mfma_f32_16x16x32_bf16 v[124:127], v[146:149], v[196:199], v[124:127]
	v_mfma_f32_16x16x32_bf16 v[120:123], v[172:175], v[196:199], v[120:123]
	v_mfma_f32_16x16x32_bf16 v[104:107], v[172:175], v[208:211], v[104:107]
	v_mfma_f32_16x16x32_bf16 v[108:111], v[146:149], v[208:211], v[108:111]
	v_mfma_f32_16x16x32_bf16 v[92:95], v[146:149], v[230:233], v[92:95]
	v_mfma_f32_16x16x32_bf16 v[88:91], v[172:175], v[230:233], v[88:91]
	v_mfma_f32_16x16x32_bf16 v[72:75], v[172:175], v[238:241], v[72:75]
	v_mfma_f32_16x16x32_bf16 v[76:79], v[146:149], v[238:241], v[76:79]
	s_setprio 0
	s_setprio 1
	v_mfma_f32_16x16x32_bf16 v[116:119], v[176:179], v[192:195], v[116:119]
	v_mfma_f32_16x16x32_bf16 v[112:115], v[184:187], v[192:195], v[112:115]
	v_mfma_f32_16x16x32_bf16 v[96:99], v[184:187], v[200:203], v[96:99]
	v_mfma_f32_16x16x32_bf16 v[100:103], v[176:179], v[200:203], v[100:103]
	v_mfma_f32_16x16x32_bf16 v[84:87], v[176:179], v[214:217], v[84:87]
	v_mfma_f32_16x16x32_bf16 v[80:83], v[184:187], v[214:217], v[80:83]
	v_mfma_f32_16x16x32_bf16 v[64:67], v[184:187], v[234:237], v[64:67]
	v_mfma_f32_16x16x32_bf16 v[68:71], v[176:179], v[234:237], v[68:71]
	v_mfma_f32_16x16x32_bf16 v[116:119], v[180:183], v[196:199], v[116:119]
	v_mfma_f32_16x16x32_bf16 v[112:115], v[188:191], v[196:199], v[112:115]
	v_mfma_f32_16x16x32_bf16 v[96:99], v[188:191], v[208:211], v[96:99]
	v_mfma_f32_16x16x32_bf16 v[100:103], v[180:183], v[208:211], v[100:103]
	v_mfma_f32_16x16x32_bf16 v[84:87], v[180:183], v[230:233], v[84:87]
	v_mfma_f32_16x16x32_bf16 v[80:83], v[188:191], v[230:233], v[80:83]
	v_mfma_f32_16x16x32_bf16 v[64:67], v[188:191], v[238:241], v[64:67]
	v_mfma_f32_16x16x32_bf16 v[68:71], v[180:183], v[238:241], v[68:71]
	s_setprio 0
	s_barrier
	s_add_i32 s8, s50, s81
	s_mov_b32 m0, s8
	ds_read_b128 v[192:195], v170 offset:16384
	ds_read_b128 v[196:199], v170 offset:17408
	ds_read_b128 v[200:203], v170 offset:18432
	ds_read_b128 v[208:211], v170 offset:19456
	ds_read_b128 v[214:217], v170 offset:20480
	ds_read_b128 v[230:233], v170 offset:21504
	ds_read_b128 v[234:237], v170 offset:22528
	ds_read_b128 v[238:241], v170 offset:23552
	global_load_lds_dwordx4 v156, s[26:27]
	s_add_i32 m0, s8, 0x2000
	s_mov_b64 s[100:101], s[26:27]
	s_add_u32 s26, s26, s16
	s_addc_u32 s27, s27, 0
	s_add_i32 s8, s51, s81
	global_load_lds_dwordx4 v140, s[100:101]
	s_mov_b32 m0, s8
	s_nop 0
	global_load_lds_dwordx4 v156, s[26:27]
	s_add_i32 m0, s8, 0x2000
	s_nop 0
	global_load_lds_dwordx4 v140, s[26:27]
	s_mov_b32 m0, s83
	s_nop 0
	global_load_lds_dwordx4 v136, s[76:77]
	s_mov_b32 m0, s2
	s_nop 0
	global_load_lds_dwordx4 v138, s[76:77]
	s_waitcnt vmcnt(8)
	s_waitcnt lgkmcnt(0)
	s_barrier
; #define PG8_STAGE(bufoff, gbase, voff) do { _Pragma("unroll") for (int _i = 0; _i < 2; ++_i) \
;         __builtin_amdgcn_global_load_lds((const unsigned*)((const char*)(gbase) + (voff)[_i]), (LAS unsigned*)(lds + (bufoff) + ldsw + _i * 8192), 16, 0, 0); } while (0)
; #define PG8_LDA(dst, b, h) do { _Pragma("unroll") for (int m = 0; m < 4; ++m) _Pragma("unroll") for (int k = 0; k < 2; ++k) dst[m][k] = *(const LAS bf16x8*)(lds + PG8_SA(b, h) + aoff + m * 2048 + k * 1024); } while (0)
; #define PG8_LDB(dst, b, h) do { _Pragma("unroll") for (int n = 0; n < 2; ++n) _Pragma("unroll") for (int k = 0; k < 2; ++k) dst[n][k] = *(const LAS bf16x8*)(lds + PG8_SB(b, h) + boff + n * 2048 + k * 1024); } while (0)
; #define PG8_MMA(ai, bj, At, Bt) do { __builtin_amdgcn_s_setprio(1); _Pragma("unroll") for (int m = 0; m < 4; ++m) _Pragma("unroll") for (int n = 0; n < 2; ++n) _Pragma("unroll") for (int k = 0; k < 2; ++k) \
;         acc[ai][bj][m][n] = __builtin_amdgcn_mfma_f32_16x16x32_bf16(Bt[n][k], At[m][k], acc[ai][bj][m][n], 0, 0, 0); __builtin_amdgcn_s_setprio(0); } while (0)
; #define PG8_WAIT_V(n) asm volatile("s_waitcnt vmcnt(" #n ")" ::: "memory")
; #define PG8_WAIT_L(n) asm volatile("s_waitcnt lgkmcnt(" #n ")" ::: "memory")
; #define PG8_BAR __builtin_amdgcn_s_barrier()
; #define PG8_SCHED __builtin_amdgcn_sched_barrier(0)
;     ...
;             PG8_WAIT_V(8); PG8_WAIT_L(0); PG8_BAR; PG8_MMA(1, 0, At, B0); PG8_MMA(1, 1, At, B1); PG8_BAR; PG8_SCHED;
;             PG8_LDB(B0, 1, 0); PG8_LDB(B1, 1, 1); PG8_SCHED; PG8_LDA(At, 1, 0); PG8_STAGE(PG8_SA(0, 1), a2 + hA, voffA);
;             PG8_WAIT_V(8); PG8_WAIT_L(0); PG8_BAR; PG8_MMA(0, 0, At, B0); PG8_MMA(0, 1, At, B1); PG8_BAR; PG8_SCHED;
	s_setprio 1
	s_waitcnt lgkmcnt(0)
	v_mfma_f32_16x16x32_bf16 v[60:63], v[132:135], v[192:195], v[60:63]
	v_mfma_f32_16x16x32_bf16 v[56:59], v[150:153], v[192:195], v[56:59]
	v_mfma_f32_16x16x32_bf16 v[40:43], v[150:153], v[200:203], v[40:43]
	v_mfma_f32_16x16x32_bf16 v[44:47], v[132:135], v[200:203], v[44:47]
	v_mfma_f32_16x16x32_bf16 v[28:31], v[132:135], v[214:217], v[28:31]
	v_mfma_f32_16x16x32_bf16 v[24:27], v[150:153], v[214:217], v[24:27]
	v_mfma_f32_16x16x32_bf16 v[8:11], v[150:153], v[234:237], v[8:11]
	v_mfma_f32_16x16x32_bf16 v[12:15], v[132:135], v[234:237], v[12:15]
	v_mfma_f32_16x16x32_bf16 v[60:63], v[146:149], v[196:199], v[60:63]
	v_mfma_f32_16x16x32_bf16 v[56:59], v[172:175], v[196:199], v[56:59]
	v_mfma_f32_16x16x32_bf16 v[40:43], v[172:175], v[208:211], v[40:43]
	v_mfma_f32_16x16x32_bf16 v[44:47], v[146:149], v[208:211], v[44:47]
	v_mfma_f32_16x16x32_bf16 v[28:31], v[146:149], v[230:233], v[28:31]
	v_mfma_f32_16x16x32_bf16 v[24:27], v[172:175], v[230:233], v[24:27]
	v_mfma_f32_16x16x32_bf16 v[8:11], v[172:175], v[238:241], v[8:11]
	v_mfma_f32_16x16x32_bf16 v[12:15], v[146:149], v[238:241], v[12:15]
	s_setprio 0
	s_setprio 1
	v_mfma_f32_16x16x32_bf16 v[52:55], v[176:179], v[192:195], v[52:55]
	v_mfma_f32_16x16x32_bf16 v[48:51], v[184:187], v[192:195], v[48:51]
	v_mfma_f32_16x16x32_bf16 v[32:35], v[184:187], v[200:203], v[32:35]
	v_mfma_f32_16x16x32_bf16 v[36:39], v[176:179], v[200:203], v[36:39]
	v_mfma_f32_16x16x32_bf16 v[20:23], v[176:179], v[214:217], v[20:23]
	v_mfma_f32_16x16x32_bf16 v[16:19], v[184:187], v[214:217], v[16:19]
	v_mfma_f32_16x16x32_bf16 v[0:3], v[184:187], v[234:237], v[0:3]
	v_mfma_f32_16x16x32_bf16 v[4:7], v[176:179], v[234:237], v[4:7]
	v_mfma_f32_16x16x32_bf16 v[52:55], v[180:183], v[196:199], v[52:55]
	v_mfma_f32_16x16x32_bf16 v[48:51], v[188:191], v[196:199], v[48:51]
	v_mfma_f32_16x16x32_bf16 v[32:35], v[188:191], v[208:211], v[32:35]
	v_mfma_f32_16x16x32_bf16 v[36:39], v[180:183], v[208:211], v[36:39]
	v_mfma_f32_16x16x32_bf16 v[20:23], v[180:183], v[230:233], v[20:23]
	v_mfma_f32_16x16x32_bf16 v[16:19], v[188:191], v[230:233], v[16:19]
	v_mfma_f32_16x16x32_bf16 v[0:3], v[188:191], v[238:241], v[0:3]
	v_mfma_f32_16x16x32_bf16 v[4:7], v[180:183], v[238:241], v[4:7]
	s_setprio 0
	s_barrier
	s_add_i32 s8, 0, 0x18000
	v_add_u32_e32 v171, s8, v168
	s_add_i32 s9, 0, 0x1c000
	ds_read_b128 v[132:135], v171
	ds_read_b128 v[146:149], v171 offset:1024
	ds_read_b128 v[150:153], v171 offset:2048
	ds_read_b128 v[172:175], v171 offset:3072
	v_add_u32_e32 v171, s9, v168
	ds_read_b128 v[176:179], v171
	ds_read_b128 v[180:183], v171 offset:1024
	ds_read_b128 v[184:187], v171 offset:2048
	ds_read_b128 v[188:191], v171 offset:3072
	s_add_u32 s26, s76, s16
	s_addc_u32 s27, s77, 0
	s_mov_b32 m0, s3
	ds_read_b128 v[192:195], v170 offset:32768
	ds_read_b128 v[196:199], v170 offset:33792
	ds_read_b128 v[200:203], v170 offset:34816
	ds_read_b128 v[208:211], v170 offset:35840
	ds_read_b128 v[214:217], v170 offset:36864
	ds_read_b128 v[230:233], v170 offset:37888
	ds_read_b128 v[234:237], v170 offset:38912
	ds_read_b128 v[238:241], v170 offset:39936
	global_load_lds_dwordx4 v136, s[26:27]
	s_mov_b32 m0, s0
	s_nop 0
	global_load_lds_dwordx4 v138, s[26:27]
	s_waitcnt vmcnt(8)
	s_waitcnt lgkmcnt(0)
	s_barrier
	s_setprio 1
	s_waitcnt lgkmcnt(0)
	v_mfma_f32_16x16x32_bf16 v[124:127], v[132:135], v[192:195], v[124:127]
	v_mfma_f32_16x16x32_bf16 v[120:123], v[150:153], v[192:195], v[120:123]
	v_mfma_f32_16x16x32_bf16 v[104:107], v[150:153], v[200:203], v[104:107]
	v_mfma_f32_16x16x32_bf16 v[108:111], v[132:135], v[200:203], v[108:111]
	v_mfma_f32_16x16x32_bf16 v[92:95], v[132:135], v[214:217], v[92:95]
	v_mfma_f32_16x16x32_bf16 v[88:91], v[150:153], v[214:217], v[88:91]
	v_mfma_f32_16x16x32_bf16 v[72:75], v[150:153], v[234:237], v[72:75]
	v_mfma_f32_16x16x32_bf16 v[76:79], v[132:135], v[234:237], v[76:79]
	v_mfma_f32_16x16x32_bf16 v[124:127], v[146:149], v[196:199], v[124:127]
	v_mfma_f32_16x16x32_bf16 v[120:123], v[172:175], v[196:199], v[120:123]
	v_mfma_f32_16x16x32_bf16 v[104:107], v[172:175], v[208:211], v[104:107]
	v_mfma_f32_16x16x32_bf16 v[108:111], v[146:149], v[208:211], v[108:111]
	v_mfma_f32_16x16x32_bf16 v[92:95], v[146:149], v[230:233], v[92:95]
	v_mfma_f32_16x16x32_bf16 v[88:91], v[172:175], v[230:233], v[88:91]
	v_mfma_f32_16x16x32_bf16 v[72:75], v[172:175], v[238:241], v[72:75]
	v_mfma_f32_16x16x32_bf16 v[76:79], v[146:149], v[238:241], v[76:79]
	s_setprio 0
	s_setprio 1
	v_mfma_f32_16x16x32_bf16 v[116:119], v[176:179], v[192:195], v[116:119]
	v_mfma_f32_16x16x32_bf16 v[112:115], v[184:187], v[192:195], v[112:115]
	v_mfma_f32_16x16x32_bf16 v[96:99], v[184:187], v[200:203], v[96:99]
	v_mfma_f32_16x16x32_bf16 v[100:103], v[176:179], v[200:203], v[100:103]
	v_mfma_f32_16x16x32_bf16 v[84:87], v[176:179], v[214:217], v[84:87]
	v_mfma_f32_16x16x32_bf16 v[80:83], v[184:187], v[214:217], v[80:83]
	v_mfma_f32_16x16x32_bf16 v[64:67], v[184:187], v[234:237], v[64:67]
	v_mfma_f32_16x16x32_bf16 v[68:71], v[176:179], v[234:237], v[68:71]
	v_mfma_f32_16x16x32_bf16 v[116:119], v[180:183], v[196:199], v[116:119]
	v_mfma_f32_16x16x32_bf16 v[112:115], v[188:191], v[196:199], v[112:115]
	v_mfma_f32_16x16x32_bf16 v[96:99], v[188:191], v[208:211], v[96:99]
	v_mfma_f32_16x16x32_bf16 v[100:103], v[180:183], v[208:211], v[100:103]
	v_mfma_f32_16x16x32_bf16 v[84:87], v[180:183], v[230:233], v[84:87]
	v_mfma_f32_16x16x32_bf16 v[80:83], v[188:191], v[230:233], v[80:83]
	v_mfma_f32_16x16x32_bf16 v[64:67], v[188:191], v[238:241], v[64:67]
	v_mfma_f32_16x16x32_bf16 v[68:71], v[180:183], v[238:241], v[68:71]
	s_setprio 0
	s_barrier
; #define PG8_STAGE(bufoff, gbase, voff) do { _Pragma("unroll") for (int _i = 0; _i < 2; ++_i) \
;         __builtin_amdgcn_global_load_lds((const unsigned*)((const char*)(gbase) + (voff)[_i]), (LAS unsigned*)(lds + (bufoff) + ldsw + _i * 8192), 16, 0, 0); } while (0)
; #define PG8_LDA(dst, b, h) do { _Pragma("unroll") for (int m = 0; m < 4; ++m) _Pragma("unroll") for (int k = 0; k < 2; ++k) dst[m][k] = *(const LAS bf16x8*)(lds + PG8_SA(b, h) + aoff + m * 2048 + k * 1024); } while (0)
; #define PG8_MMA(ai, bj, At, Bt) do { __builtin_amdgcn_s_setprio(1); _Pragma("unroll") for (int m = 0; m < 4; ++m) _Pragma("unroll") for (int n = 0; n < 2; ++n) _Pragma("unroll") for (int k = 0; k < 2; ++k) \
;         acc[ai][bj][m][n] = __builtin_amdgcn_mfma_f32_16x16x32_bf16(Bt[n][k], At[m][k], acc[ai][bj][m][n], 0, 0, 0); __builtin_amdgcn_s_setprio(0); } while (0)
; #define PG8_WAIT_V(n) asm volatile("s_waitcnt vmcnt(" #n ")" ::: "memory")
; #define PG8_WAIT_L(n) asm volatile("s_waitcnt lgkmcnt(" #n ")" ::: "memory")
; #define PG8_BAR __builtin_amdgcn_s_barrier()
; #define PG8_SCHED __builtin_amdgcn_sched_barrier(0)
;     ...
;         for (int t = 0; t < nt; t += 2) {
;     ...
;             PG8_LDA(At, 1, 1); PG8_STAGE(PG8_SB(1, 0), b3, voffB); PG8_STAGE(PG8_SB(1, 1), b3 + hB, voffB); PG8_STAGE(PG8_SA(1, 0), a3, voffA);
;             PG8_WAIT_V(8); PG8_WAIT_L(0); PG8_BAR; PG8_MMA(1, 0, At, B0); PG8_MMA(1, 1, At, B1); PG8_BAR; PG8_SCHED;
	s_add_i32 s8, s8, s81
	s_add_u32 s98, s100, s38
	s_addc_u32 s99, s101, s39
	s_add_u32 s100, s98, s16
	s_addc_u32 s101, s99, 0
	s_mov_b32 m0, s8
	ds_read_b128 v[192:195], v170 offset:49152
	ds_read_b128 v[196:199], v170 offset:50176
	ds_read_b128 v[200:203], v170 offset:51200
	ds_read_b128 v[208:211], v170 offset:52224
	ds_read_b128 v[214:217], v170 offset:53248
	ds_read_b128 v[230:233], v170 offset:54272
	ds_read_b128 v[234:237], v170 offset:55296
	ds_read_b128 v[238:241], v170 offset:56320
	global_load_lds_dwordx4 v156, s[98:99]
	s_add_i32 m0, s8, 0x2000
	s_add_i32 s8, s9, s81
	global_load_lds_dwordx4 v140, s[98:99]
	s_mov_b32 m0, s8
	s_nop 0
	global_load_lds_dwordx4 v156, s[100:101]
	s_add_i32 m0, s8, 0x2000
	s_nop 0
	global_load_lds_dwordx4 v140, s[100:101]
	s_mov_b32 m0, s1
	s_nop 0
	global_load_lds_dwordx4 v136, s[74:75]
	s_mov_b32 m0, s54
	s_nop 0
	global_load_lds_dwordx4 v138, s[74:75]
	s_waitcnt vmcnt(8)
	s_waitcnt lgkmcnt(0)
	s_barrier
	s_setprio 1
	s_waitcnt lgkmcnt(0)
	v_mfma_f32_16x16x32_bf16 v[60:63], v[132:135], v[192:195], v[60:63]
	v_mfma_f32_16x16x32_bf16 v[56:59], v[150:153], v[192:195], v[56:59]
	v_mfma_f32_16x16x32_bf16 v[40:43], v[150:153], v[200:203], v[40:43]
	v_mfma_f32_16x16x32_bf16 v[44:47], v[132:135], v[200:203], v[44:47]
	v_mfma_f32_16x16x32_bf16 v[28:31], v[132:135], v[214:217], v[28:31]
	v_mfma_f32_16x16x32_bf16 v[24:27], v[150:153], v[214:217], v[24:27]
	v_mfma_f32_16x16x32_bf16 v[8:11], v[150:153], v[234:237], v[8:11]
	v_mfma_f32_16x16x32_bf16 v[12:15], v[132:135], v[234:237], v[12:15]
	v_mfma_f32_16x16x32_bf16 v[60:63], v[146:149], v[196:199], v[60:63]
	v_mfma_f32_16x16x32_bf16 v[56:59], v[172:175], v[196:199], v[56:59]
	v_mfma_f32_16x16x32_bf16 v[40:43], v[172:175], v[208:211], v[40:43]
	v_mfma_f32_16x16x32_bf16 v[44:47], v[146:149], v[208:211], v[44:47]
	v_mfma_f32_16x16x32_bf16 v[28:31], v[146:149], v[230:233], v[28:31]
	v_mfma_f32_16x16x32_bf16 v[24:27], v[172:175], v[230:233], v[24:27]
	v_mfma_f32_16x16x32_bf16 v[8:11], v[172:175], v[238:241], v[8:11]
	v_mfma_f32_16x16x32_bf16 v[12:15], v[146:149], v[238:241], v[12:15]
	s_setprio 0
	s_setprio 1
	v_mfma_f32_16x16x32_bf16 v[52:55], v[176:179], v[192:195], v[52:55]
	v_mfma_f32_16x16x32_bf16 v[48:51], v[184:187], v[192:195], v[48:51]
	v_mfma_f32_16x16x32_bf16 v[32:35], v[184:187], v[200:203], v[32:35]
	v_mfma_f32_16x16x32_bf16 v[36:39], v[176:179], v[200:203], v[36:39]
	v_mfma_f32_16x16x32_bf16 v[20:23], v[176:179], v[214:217], v[20:23]
	v_mfma_f32_16x16x32_bf16 v[16:19], v[184:187], v[214:217], v[16:19]
	v_mfma_f32_16x16x32_bf16 v[0:3], v[184:187], v[234:237], v[0:3]
	v_mfma_f32_16x16x32_bf16 v[4:7], v[176:179], v[234:237], v[4:7]
	v_mfma_f32_16x16x32_bf16 v[52:55], v[180:183], v[196:199], v[52:55]
	v_mfma_f32_16x16x32_bf16 v[48:51], v[188:191], v[196:199], v[48:51]
	v_mfma_f32_16x16x32_bf16 v[32:35], v[188:191], v[208:211], v[32:35]
	v_mfma_f32_16x16x32_bf16 v[36:39], v[180:183], v[208:211], v[36:39]
	v_mfma_f32_16x16x32_bf16 v[20:23], v[180:183], v[230:233], v[20:23]
	v_mfma_f32_16x16x32_bf16 v[16:19], v[188:191], v[230:233], v[16:19]
	v_mfma_f32_16x16x32_bf16 v[0:3], v[188:191], v[238:241], v[0:3]
	v_mfma_f32_16x16x32_bf16 v[4:7], v[180:183], v[238:241], v[4:7]
	s_setprio 0
	s_barrier
	s_add_u32 vcc_lo, vcc_lo, 0x100
	s_addc_u32 vcc_hi, vcc_hi, 0
	s_cmp_ge_u32 s6, s4
	s_mov_b32 s74, s6
	s_cbranch_scc0 .LBB0_364
	s_and_b64 vcc, exec, s[30:31]
	s_cbranch_vccz .LBB0_367
	s_barrier

; #define PG8_STAGE(bufoff, gbase, voff) do { _Pragma("unroll") for (int _i = 0; _i < 2; ++_i) \
;         __builtin_amdgcn_global_load_lds((const unsigned*)((const char*)(gbase) + (voff)[_i]), (LAS unsigned*)(lds + (bufoff) + ldsw + _i * 8192), 16, 0, 0); } while (0)
; #define PG8_LDA(dst, b, h) do { _Pragma("unroll") for (int m = 0; m < 4; ++m) _Pragma("unroll") for (int k = 0; k < 2; ++k) dst[m][k] = *(const LAS bf16x8*)(lds + PG8_SA(b, h) + aoff + m * 2048 + k * 1024); } while (0)
; #define PG8_LDB(dst, b, h) do { _Pragma("unroll") for (int n = 0; n < 2; ++n) _Pragma("unroll") for (int k = 0; k < 2; ++k) dst[n][k] = *(const LAS bf16x8*)(lds + PG8_SB(b, h) + boff + n * 2048 + k * 1024); } while (0)
; #define PG8_MMA(ai, bj, At, Bt) do { __builtin_amdgcn_s_setprio(1); _Pragma("unroll") for (int m = 0; m < 4; ++m) _Pragma("unroll") for (int n = 0; n < 2; ++n) _Pragma("unroll") for (int k = 0; k < 2; ++k) \
;         acc[ai][bj][m][n] = __builtin_amdgcn_mfma_f32_16x16x32_bf16(Bt[n][k], At[m][k], acc[ai][bj][m][n], 0, 0, 0); __builtin_amdgcn_s_setprio(0); } while (0)
; #define PG8_WAIT_V(n) asm volatile("s_waitcnt vmcnt(" #n ")" ::: "memory")
; #define PG8_WAIT_L(n) asm volatile("s_waitcnt lgkmcnt(" #n ")" ::: "memory")
; #define PG8_BAR __builtin_amdgcn_s_barrier()
; #define PG8_SCHED __builtin_amdgcn_sched_barrier(0)
;     ...
;             PG8_LDB(B0, 0, 0); PG8_LDB(B1, 0, 1); PG8_SCHED; PG8_LDA(At, 0, 0); PG8_STAGE(PG8_SA(1, 1), a1 + hA, voffA);
;             PG8_WAIT_V(8); PG8_WAIT_L(0); PG8_BAR; PG8_MMA(0, 0, At, B0); PG8_MMA(0, 1, At, B1); PG8_BAR; PG8_SCHED;
;             PG8_LDA(At, 0, 1); PG8_STAGE(PG8_SB(0, 0), b2, voffB); PG8_STAGE(PG8_SB(0, 1), b2 + hB, voffB); PG8_STAGE(PG8_SA(0, 0), a2, voffA);
;             PG8_WAIT_V(8); PG8_WAIT_L(0); PG8_BAR; PG8_MMA(1, 0, At, B0); PG8_MMA(1, 1, At, B1); PG8_BAR; PG8_SCHED;
.LBB0_406:
	s_add_u32 s42, s30, s34
	s_addc_u32 s43, s31, s35
	s_add_u32 s48, s42, 0x100
	s_addc_u32 s49, s43, 0
	s_add_u32 s44, s74, s34
	s_addc_u32 s45, s75, s35
	s_add_u32 s42, s42, 0x180
	s_addc_u32 s43, s43, 0
	s_add_i32 s77, 0, 0x10000
	s_add_i32 s80, 0, 0x14000
	v_add_u32_e32 v144, s77, v179
	v_add_u32_e32 v178, s80, v179
	ds_read_b128 v[132:135], v144
	ds_read_b128 v[136:139], v144 offset:1024
	ds_read_b128 v[140:143], v144 offset:2048
	ds_read_b128 v[144:147], v144 offset:3072
	ds_read_b128 v[148:151], v178
	ds_read_b128 v[186:189], v178 offset:1024
	ds_read_b128 v[190:193], v178 offset:2048
	ds_read_b128 v[194:197], v178 offset:3072
	s_cmpk_eq_i32 s34, 0x700
	s_cselect_b32 s43, s73, s43
	s_cselect_b32 s42, s72, s42
	s_cselect_b32 s45, s17, s45
	s_cselect_b32 s44, s55, s44
	s_cselect_b32 s49, s3, s49
	s_cselect_b32 s48, s25, s48
	v_lshl_add_u64 v[182:183], v[128:129], 0, s[34:35]
	s_add_i32 m0, s6, 0xc000
	ds_read_b128 v[208:211], v181
	ds_read_b128 v[230:233], v181 offset:1024
	ds_read_b128 v[234:237], v181 offset:2048
	ds_read_b128 v[238:241], v181 offset:3072
	ds_read_b128 v[242:245], v181 offset:4096
	ds_read_b128 v[246:249], v181 offset:5120
	ds_read_b128 v[214:217], v181 offset:6144
	ds_read_b128 v[198:201], v181 offset:7168
	global_load_lds_dwordx4 v[182:183], off
	v_lshl_add_u64 v[182:183], v[130:131], 0, s[34:35]
	s_add_i32 m0, s6, 0xe000
	s_nop 0
	global_load_lds_dwordx4 v[182:183], off
	s_waitcnt vmcnt(8)
	s_waitcnt lgkmcnt(0)
	s_barrier
	s_setprio 1
	s_waitcnt lgkmcnt(0)
	v_mfma_f32_16x16x32_bf16 v[124:127], v[132:135], v[208:211], v[124:127]
	v_mfma_f32_16x16x32_bf16 v[120:123], v[140:143], v[208:211], v[120:123]
	v_mfma_f32_16x16x32_bf16 v[104:107], v[140:143], v[234:237], v[104:107]
	v_mfma_f32_16x16x32_bf16 v[108:111], v[132:135], v[234:237], v[108:111]
	v_mfma_f32_16x16x32_bf16 v[92:95], v[132:135], v[242:245], v[92:95]
	v_mfma_f32_16x16x32_bf16 v[88:91], v[140:143], v[242:245], v[88:91]
	v_mfma_f32_16x16x32_bf16 v[72:75], v[140:143], v[214:217], v[72:75]
	v_mfma_f32_16x16x32_bf16 v[76:79], v[132:135], v[214:217], v[76:79]
	v_mfma_f32_16x16x32_bf16 v[124:127], v[136:139], v[230:233], v[124:127]
	v_mfma_f32_16x16x32_bf16 v[120:123], v[144:147], v[230:233], v[120:123]
	v_mfma_f32_16x16x32_bf16 v[104:107], v[144:147], v[238:241], v[104:107]
	v_mfma_f32_16x16x32_bf16 v[108:111], v[136:139], v[238:241], v[108:111]
	v_mfma_f32_16x16x32_bf16 v[92:95], v[136:139], v[246:249], v[92:95]
	v_mfma_f32_16x16x32_bf16 v[88:91], v[144:147], v[246:249], v[88:91]
	v_mfma_f32_16x16x32_bf16 v[72:75], v[144:147], v[198:201], v[72:75]
	v_mfma_f32_16x16x32_bf16 v[76:79], v[136:139], v[198:201], v[76:79]
	s_setprio 0
	s_setprio 1
	v_mfma_f32_16x16x32_bf16 v[116:119], v[148:151], v[208:211], v[116:119]
	v_mfma_f32_16x16x32_bf16 v[112:115], v[190:193], v[208:211], v[112:115]
	v_mfma_f32_16x16x32_bf16 v[96:99], v[190:193], v[234:237], v[96:99]
	v_mfma_f32_16x16x32_bf16 v[100:103], v[148:151], v[234:237], v[100:103]
	v_mfma_f32_16x16x32_bf16 v[84:87], v[148:151], v[242:245], v[84:87]
	v_mfma_f32_16x16x32_bf16 v[80:83], v[190:193], v[242:245], v[80:83]
	v_mfma_f32_16x16x32_bf16 v[64:67], v[190:193], v[214:217], v[64:67]
	v_mfma_f32_16x16x32_bf16 v[68:71], v[148:151], v[214:217], v[68:71]
	v_mfma_f32_16x16x32_bf16 v[116:119], v[186:189], v[230:233], v[116:119]
	v_mfma_f32_16x16x32_bf16 v[112:115], v[194:197], v[230:233], v[112:115]
	v_mfma_f32_16x16x32_bf16 v[96:99], v[194:197], v[238:241], v[96:99]
	v_mfma_f32_16x16x32_bf16 v[100:103], v[186:189], v[238:241], v[100:103]
	v_mfma_f32_16x16x32_bf16 v[84:87], v[186:189], v[246:249], v[84:87]
	v_mfma_f32_16x16x32_bf16 v[80:83], v[194:197], v[246:249], v[80:83]
	v_mfma_f32_16x16x32_bf16 v[64:67], v[194:197], v[198:201], v[64:67]
	v_mfma_f32_16x16x32_bf16 v[68:71], v[186:189], v[198:201], v[68:71]
	s_setprio 0
	s_barrier
	s_add_i32 s77, s77, s5
	v_lshl_add_u64 v[182:183], s[44:45], 0, v[156:157]
	s_mov_b32 m0, s77
	ds_read_b128 v[198:201], v181 offset:16384
	ds_read_b128 v[208:211], v181 offset:17408
	ds_read_b128 v[214:217], v181 offset:18432
	ds_read_b128 v[230:233], v181 offset:19456
	ds_read_b128 v[234:237], v181 offset:20480
	ds_read_b128 v[238:241], v181 offset:21504
	ds_read_b128 v[242:245], v181 offset:22528
	ds_read_b128 v[246:249], v181 offset:23552
	global_load_lds_dwordx4 v[182:183], off
	s_add_i32 m0, s77, 0x2000
	s_add_u32 s78, s44, 0x40000
	v_lshl_add_u64 v[202:203], s[44:45], 0, v[168:169]
	s_addc_u32 s79, s45, 0
	s_add_i32 s77, s80, s5
	global_load_lds_dwordx4 v[202:203], off
	v_lshl_add_u64 v[204:205], s[78:79], 0, v[156:157]
	s_mov_b32 m0, s77
	s_nop 0
	global_load_lds_dwordx4 v[204:205], off
	v_lshl_add_u64 v[204:205], s[78:79], 0, v[168:169]
	s_add_i32 m0, s77, 0x2000
	s_nop 0
	global_load_lds_dwordx4 v[204:205], off
	v_lshl_add_u64 v[204:205], s[48:49], 0, v[152:153]
	s_mov_b32 m0, s6
	s_nop 0
	global_load_lds_dwordx4 v[204:205], off
	v_lshl_add_u64 v[204:205], s[48:49], 0, v[154:155]
	s_mov_b32 m0, s7
	s_nop 0
	global_load_lds_dwordx4 v[204:205], off
	s_waitcnt vmcnt(8)
	s_waitcnt lgkmcnt(0)
	s_barrier
; #define PG8_STAGE(bufoff, gbase, voff) do { _Pragma("unroll") for (int _i = 0; _i < 2; ++_i) \
;         __builtin_amdgcn_global_load_lds((const unsigned*)((const char*)(gbase) + (voff)[_i]), (LAS unsigned*)(lds + (bufoff) + ldsw + _i * 8192), 16, 0, 0); } while (0)
; #define PG8_LDA(dst, b, h) do { _Pragma("unroll") for (int m = 0; m < 4; ++m) _Pragma("unroll") for (int k = 0; k < 2; ++k) dst[m][k] = *(const LAS bf16x8*)(lds + PG8_SA(b, h) + aoff + m * 2048 + k * 1024); } while (0)
; #define PG8_LDB(dst, b, h) do { _Pragma("unroll") for (int n = 0; n < 2; ++n) _Pragma("unroll") for (int k = 0; k < 2; ++k) dst[n][k] = *(const LAS bf16x8*)(lds + PG8_SB(b, h) + boff + n * 2048 + k * 1024); } while (0)
; #define PG8_MMA(ai, bj, At, Bt) do { __builtin_amdgcn_s_setprio(1); _Pragma("unroll") for (int m = 0; m < 4; ++m) _Pragma("unroll") for (int n = 0; n < 2; ++n) _Pragma("unroll") for (int k = 0; k < 2; ++k) \
;         acc[ai][bj][m][n] = __builtin_amdgcn_mfma_f32_16x16x32_bf16(Bt[n][k], At[m][k], acc[ai][bj][m][n], 0, 0, 0); __builtin_amdgcn_s_setprio(0); } while (0)
; #define PG8_WAIT_V(n) asm volatile("s_waitcnt vmcnt(" #n ")" ::: "memory")
; #define PG8_WAIT_L(n) asm volatile("s_waitcnt lgkmcnt(" #n ")" ::: "memory")
; #define PG8_BAR __builtin_amdgcn_s_barrier()
; #define PG8_SCHED __builtin_amdgcn_sched_barrier(0)
;     ...
;             PG8_WAIT_V(8); PG8_WAIT_L(0); PG8_BAR; PG8_MMA(1, 0, At, B0); PG8_MMA(1, 1, At, B1); PG8_BAR; PG8_SCHED;
;             PG8_LDB(B0, 1, 0); PG8_LDB(B1, 1, 1); PG8_SCHED; PG8_LDA(At, 1, 0); PG8_STAGE(PG8_SA(0, 1), a2 + hA, voffA);
;             PG8_WAIT_V(8); PG8_WAIT_L(0); PG8_BAR; PG8_MMA(0, 0, At, B0); PG8_MMA(0, 1, At, B1); PG8_BAR; PG8_SCHED;
	s_setprio 1
	s_waitcnt lgkmcnt(0)
	v_mfma_f32_16x16x32_bf16 v[60:63], v[132:135], v[198:201], v[60:63]
	v_mfma_f32_16x16x32_bf16 v[56:59], v[140:143], v[198:201], v[56:59]
	v_mfma_f32_16x16x32_bf16 v[40:43], v[140:143], v[214:217], v[40:43]
	v_mfma_f32_16x16x32_bf16 v[44:47], v[132:135], v[214:217], v[44:47]
	v_mfma_f32_16x16x32_bf16 v[28:31], v[132:135], v[234:237], v[28:31]
	v_mfma_f32_16x16x32_bf16 v[24:27], v[140:143], v[234:237], v[24:27]
	v_mfma_f32_16x16x32_bf16 v[8:11], v[140:143], v[242:245], v[8:11]
	v_mfma_f32_16x16x32_bf16 v[12:15], v[132:135], v[242:245], v[12:15]
	v_mfma_f32_16x16x32_bf16 v[60:63], v[136:139], v[208:211], v[60:63]
	v_mfma_f32_16x16x32_bf16 v[56:59], v[144:147], v[208:211], v[56:59]
	v_mfma_f32_16x16x32_bf16 v[40:43], v[144:147], v[230:233], v[40:43]
	v_mfma_f32_16x16x32_bf16 v[44:47], v[136:139], v[230:233], v[44:47]
	v_mfma_f32_16x16x32_bf16 v[28:31], v[136:139], v[238:241], v[28:31]
	v_mfma_f32_16x16x32_bf16 v[24:27], v[144:147], v[238:241], v[24:27]
	v_mfma_f32_16x16x32_bf16 v[8:11], v[144:147], v[246:249], v[8:11]
	v_mfma_f32_16x16x32_bf16 v[12:15], v[136:139], v[246:249], v[12:15]
	s_setprio 0
	s_setprio 1
	v_mfma_f32_16x16x32_bf16 v[52:55], v[148:151], v[198:201], v[52:55]
	v_mfma_f32_16x16x32_bf16 v[48:51], v[190:193], v[198:201], v[48:51]
	v_mfma_f32_16x16x32_bf16 v[32:35], v[190:193], v[214:217], v[32:35]
	v_mfma_f32_16x16x32_bf16 v[36:39], v[148:151], v[214:217], v[36:39]
	v_mfma_f32_16x16x32_bf16 v[20:23], v[148:151], v[234:237], v[20:23]
	v_mfma_f32_16x16x32_bf16 v[16:19], v[190:193], v[234:237], v[16:19]
	v_mfma_f32_16x16x32_bf16 v[0:3], v[190:193], v[242:245], v[0:3]
	v_mfma_f32_16x16x32_bf16 v[4:7], v[148:151], v[242:245], v[4:7]
	v_mfma_f32_16x16x32_bf16 v[52:55], v[186:189], v[208:211], v[52:55]
	v_mfma_f32_16x16x32_bf16 v[48:51], v[194:197], v[208:211], v[48:51]
	v_mfma_f32_16x16x32_bf16 v[32:35], v[194:197], v[230:233], v[32:35]
	v_mfma_f32_16x16x32_bf16 v[36:39], v[186:189], v[230:233], v[36:39]
	v_mfma_f32_16x16x32_bf16 v[20:23], v[186:189], v[238:241], v[20:23]
	v_mfma_f32_16x16x32_bf16 v[16:19], v[194:197], v[238:241], v[16:19]
	v_mfma_f32_16x16x32_bf16 v[0:3], v[194:197], v[246:249], v[0:3]
	v_mfma_f32_16x16x32_bf16 v[4:7], v[186:189], v[246:249], v[4:7]
	s_setprio 0
	s_barrier
	s_add_i32 s77, 0, 0x18000
	s_add_i32 s78, 0, 0x1c000
	v_add_u32_e32 v144, s77, v179
	v_add_u32_e32 v178, s78, v179
	ds_read_b128 v[132:135], v144
	ds_read_b128 v[136:139], v144 offset:1024
	ds_read_b128 v[140:143], v144 offset:2048
	ds_read_b128 v[144:147], v144 offset:3072
	ds_read_b128 v[148:151], v178
	ds_read_b128 v[186:189], v178 offset:1024
	ds_read_b128 v[190:193], v178 offset:2048
	ds_read_b128 v[194:197], v178 offset:3072
	s_add_u32 s48, s48, 0x40000
	s_addc_u32 s49, s49, 0
	s_mov_b32 m0, s8
	v_lshl_add_u64 v[204:205], s[48:49], 0, v[152:153]
	ds_read_b128 v[198:201], v181 offset:32768
	ds_read_b128 v[208:211], v181 offset:33792
	ds_read_b128 v[214:217], v181 offset:34816
	ds_read_b128 v[230:233], v181 offset:35840
	ds_read_b128 v[234:237], v181 offset:36864
	ds_read_b128 v[238:241], v181 offset:37888
	ds_read_b128 v[242:245], v181 offset:38912
	ds_read_b128 v[246:249], v181 offset:39936
	global_load_lds_dwordx4 v[204:205], off
	v_lshl_add_u64 v[204:205], s[48:49], 0, v[154:155]
	s_mov_b32 m0, s9
	s_nop 0
	global_load_lds_dwordx4 v[204:205], off
	s_waitcnt vmcnt(8)
	s_waitcnt lgkmcnt(0)
	s_barrier
	s_setprio 1
	s_waitcnt lgkmcnt(0)
	v_mfma_f32_16x16x32_bf16 v[124:127], v[132:135], v[198:201], v[124:127]
	v_mfma_f32_16x16x32_bf16 v[120:123], v[140:143], v[198:201], v[120:123]
	v_mfma_f32_16x16x32_bf16 v[104:107], v[140:143], v[214:217], v[104:107]
	v_mfma_f32_16x16x32_bf16 v[108:111], v[132:135], v[214:217], v[108:111]
	v_mfma_f32_16x16x32_bf16 v[92:95], v[132:135], v[234:237], v[92:95]
	v_mfma_f32_16x16x32_bf16 v[88:91], v[140:143], v[234:237], v[88:91]
	v_mfma_f32_16x16x32_bf16 v[72:75], v[140:143], v[242:245], v[72:75]
	v_mfma_f32_16x16x32_bf16 v[76:79], v[132:135], v[242:245], v[76:79]
	v_mfma_f32_16x16x32_bf16 v[124:127], v[136:139], v[208:211], v[124:127]
	v_mfma_f32_16x16x32_bf16 v[120:123], v[144:147], v[208:211], v[120:123]
	v_mfma_f32_16x16x32_bf16 v[104:107], v[144:147], v[230:233], v[104:107]
	v_mfma_f32_16x16x32_bf16 v[108:111], v[136:139], v[230:233], v[108:111]
	v_mfma_f32_16x16x32_bf16 v[92:95], v[136:139], v[238:241], v[92:95]
	v_mfma_f32_16x16x32_bf16 v[88:91], v[144:147], v[238:241], v[88:91]
	v_mfma_f32_16x16x32_bf16 v[72:75], v[144:147], v[246:249], v[72:75]
	v_mfma_f32_16x16x32_bf16 v[76:79], v[136:139], v[246:249], v[76:79]
	s_setprio 0
	s_setprio 1
	v_mfma_f32_16x16x32_bf16 v[116:119], v[148:151], v[198:201], v[116:119]
	v_mfma_f32_16x16x32_bf16 v[112:115], v[190:193], v[198:201], v[112:115]
	v_mfma_f32_16x16x32_bf16 v[96:99], v[190:193], v[214:217], v[96:99]
	v_mfma_f32_16x16x32_bf16 v[100:103], v[148:151], v[214:217], v[100:103]
	v_mfma_f32_16x16x32_bf16 v[84:87], v[148:151], v[234:237], v[84:87]
	v_mfma_f32_16x16x32_bf16 v[80:83], v[190:193], v[234:237], v[80:83]
	v_mfma_f32_16x16x32_bf16 v[64:67], v[190:193], v[242:245], v[64:67]
	v_mfma_f32_16x16x32_bf16 v[68:71], v[148:151], v[242:245], v[68:71]
	v_mfma_f32_16x16x32_bf16 v[116:119], v[186:189], v[208:211], v[116:119]
	v_mfma_f32_16x16x32_bf16 v[112:115], v[194:197], v[208:211], v[112:115]
	v_mfma_f32_16x16x32_bf16 v[96:99], v[194:197], v[230:233], v[96:99]
	v_mfma_f32_16x16x32_bf16 v[100:103], v[186:189], v[230:233], v[100:103]
	v_mfma_f32_16x16x32_bf16 v[84:87], v[186:189], v[238:241], v[84:87]
	v_mfma_f32_16x16x32_bf16 v[80:83], v[194:197], v[238:241], v[80:83]
	v_mfma_f32_16x16x32_bf16 v[64:67], v[194:197], v[246:249], v[64:67]
	v_mfma_f32_16x16x32_bf16 v[68:71], v[186:189], v[246:249], v[68:71]
	s_setprio 0
	s_barrier
; #define PG8_STAGE(bufoff, gbase, voff) do { _Pragma("unroll") for (int _i = 0; _i < 2; ++_i) \
;         __builtin_amdgcn_global_load_lds((const unsigned*)((const char*)(gbase) + (voff)[_i]), (LAS unsigned*)(lds + (bufoff) + ldsw + _i * 8192), 16, 0, 0); } while (0)
; #define PG8_LDA(dst, b, h) do { _Pragma("unroll") for (int m = 0; m < 4; ++m) _Pragma("unroll") for (int k = 0; k < 2; ++k) dst[m][k] = *(const LAS bf16x8*)(lds + PG8_SA(b, h) + aoff + m * 2048 + k * 1024); } while (0)
; #define PG8_MMA(ai, bj, At, Bt) do { __builtin_amdgcn_s_setprio(1); _Pragma("unroll") for (int m = 0; m < 4; ++m) _Pragma("unroll") for (int n = 0; n < 2; ++n) _Pragma("unroll") for (int k = 0; k < 2; ++k) \
;         acc[ai][bj][m][n] = __builtin_amdgcn_mfma_f32_16x16x32_bf16(Bt[n][k], At[m][k], acc[ai][bj][m][n], 0, 0, 0); __builtin_amdgcn_s_setprio(0); } while (0)
; #define PG8_WAIT_V(n) asm volatile("s_waitcnt vmcnt(" #n ")" ::: "memory")
; #define PG8_WAIT_L(n) asm volatile("s_waitcnt lgkmcnt(" #n ")" ::: "memory")
; #define PG8_BAR __builtin_amdgcn_s_barrier()
; #define PG8_SCHED __builtin_amdgcn_sched_barrier(0)
;     ...
;         for (int t = 0; t < nt; t += 2) {
;     ...
;             PG8_LDA(At, 1, 1); PG8_STAGE(PG8_SB(1, 0), b3, voffB); PG8_STAGE(PG8_SB(1, 1), b3 + hB, voffB); PG8_STAGE(PG8_SA(1, 0), a3, voffA);
;             PG8_WAIT_V(8); PG8_WAIT_L(0); PG8_BAR; PG8_MMA(1, 0, At, B0); PG8_MMA(1, 1, At, B1); PG8_BAR; PG8_SCHED;
	s_add_i32 s48, s77, s5
	v_lshl_add_u64 v[182:183], v[182:183], 0, s[38:39]
	s_mov_b32 m0, s48
	ds_read_b128 v[198:201], v181 offset:49152
	ds_read_b128 v[208:211], v181 offset:50176
	ds_read_b128 v[214:217], v181 offset:51200
	ds_read_b128 v[230:233], v181 offset:52224
	ds_read_b128 v[234:237], v181 offset:53248
	ds_read_b128 v[238:241], v181 offset:54272
	ds_read_b128 v[242:245], v181 offset:55296
	ds_read_b128 v[246:249], v181 offset:56320
	global_load_lds_dwordx4 v[182:183], off
	s_add_i32 m0, s48, 0x2000
	s_add_u32 s44, s44, 0x40080
	v_lshl_add_u64 v[182:183], v[202:203], 0, s[38:39]
	s_addc_u32 s45, s45, 0
	s_add_i32 s48, s78, s5
	global_load_lds_dwordx4 v[182:183], off
	v_lshl_add_u64 v[182:183], s[44:45], 0, v[156:157]
	s_mov_b32 m0, s48
	s_nop 0
	global_load_lds_dwordx4 v[182:183], off
	v_lshl_add_u64 v[182:183], s[44:45], 0, v[168:169]
	s_add_i32 m0, s48, 0x2000
	s_nop 0
	global_load_lds_dwordx4 v[182:183], off
	v_lshl_add_u64 v[182:183], s[42:43], 0, v[152:153]
	s_mov_b32 m0, s50
	s_nop 0
	global_load_lds_dwordx4 v[182:183], off
	v_lshl_add_u64 v[182:183], s[42:43], 0, v[154:155]
	s_mov_b32 m0, s51
	s_nop 0
	global_load_lds_dwordx4 v[182:183], off
	s_waitcnt vmcnt(8)
	s_waitcnt lgkmcnt(0)
	s_barrier
	s_setprio 1
	s_waitcnt lgkmcnt(0)
	v_mfma_f32_16x16x32_bf16 v[60:63], v[132:135], v[198:201], v[60:63]
	v_mfma_f32_16x16x32_bf16 v[56:59], v[140:143], v[198:201], v[56:59]
	v_mfma_f32_16x16x32_bf16 v[40:43], v[140:143], v[214:217], v[40:43]
	v_mfma_f32_16x16x32_bf16 v[44:47], v[132:135], v[214:217], v[44:47]
	v_mfma_f32_16x16x32_bf16 v[28:31], v[132:135], v[234:237], v[28:31]
	v_mfma_f32_16x16x32_bf16 v[24:27], v[140:143], v[234:237], v[24:27]
	v_mfma_f32_16x16x32_bf16 v[8:11], v[140:143], v[242:245], v[8:11]
	v_mfma_f32_16x16x32_bf16 v[12:15], v[132:135], v[242:245], v[12:15]
	v_mfma_f32_16x16x32_bf16 v[60:63], v[136:139], v[208:211], v[60:63]
	v_mfma_f32_16x16x32_bf16 v[56:59], v[144:147], v[208:211], v[56:59]
	v_mfma_f32_16x16x32_bf16 v[40:43], v[144:147], v[230:233], v[40:43]
	v_mfma_f32_16x16x32_bf16 v[44:47], v[136:139], v[230:233], v[44:47]
	v_mfma_f32_16x16x32_bf16 v[28:31], v[136:139], v[238:241], v[28:31]
	v_mfma_f32_16x16x32_bf16 v[24:27], v[144:147], v[238:241], v[24:27]
	v_mfma_f32_16x16x32_bf16 v[8:11], v[144:147], v[246:249], v[8:11]
	v_mfma_f32_16x16x32_bf16 v[12:15], v[136:139], v[246:249], v[12:15]
	s_setprio 0
	s_setprio 1
	v_mfma_f32_16x16x32_bf16 v[52:55], v[148:151], v[198:201], v[52:55]
	v_mfma_f32_16x16x32_bf16 v[48:51], v[190:193], v[198:201], v[48:51]
	v_mfma_f32_16x16x32_bf16 v[32:35], v[190:193], v[214:217], v[32:35]
	v_mfma_f32_16x16x32_bf16 v[36:39], v[148:151], v[214:217], v[36:39]
	v_mfma_f32_16x16x32_bf16 v[20:23], v[148:151], v[234:237], v[20:23]
	v_mfma_f32_16x16x32_bf16 v[16:19], v[190:193], v[234:237], v[16:19]
	v_mfma_f32_16x16x32_bf16 v[0:3], v[190:193], v[242:245], v[0:3]
	v_mfma_f32_16x16x32_bf16 v[4:7], v[148:151], v[242:245], v[4:7]
	v_mfma_f32_16x16x32_bf16 v[52:55], v[186:189], v[208:211], v[52:55]
	v_mfma_f32_16x16x32_bf16 v[48:51], v[194:197], v[208:211], v[48:51]
	v_mfma_f32_16x16x32_bf16 v[32:35], v[194:197], v[230:233], v[32:35]
	v_mfma_f32_16x16x32_bf16 v[36:39], v[186:189], v[230:233], v[36:39]
	v_mfma_f32_16x16x32_bf16 v[20:23], v[186:189], v[238:241], v[20:23]
	v_mfma_f32_16x16x32_bf16 v[16:19], v[194:197], v[238:241], v[16:19]
	v_mfma_f32_16x16x32_bf16 v[0:3], v[194:197], v[246:249], v[0:3]
	v_mfma_f32_16x16x32_bf16 v[4:7], v[186:189], v[246:249], v[4:7]
	s_setprio 0
	s_barrier
	s_add_i32 s76, s76, 2
	s_add_u32 s34, s34, 0x100
	s_addc_u32 s35, s35, 0
	s_cmp_gt_u32 s76, 13
	s_cbranch_scc0 .LBB0_406
	s_and_b64 vcc, exec, s[14:15]
	s_cbranch_vccz .LBB0_409
	s_barrier
